# mixer-phase output stores (attention / pool / conv results) marked nt so they do not evict re-used K/V/xa/u lines from L2; on top of v11
# speedup vs baseline: 1.0042x; 1.0042x over previous
; #define LAS __attribute__((address_space(3)))
; #define SB_WAIT_V(n) asm volatile("s_waitcnt vmcnt(" #n ")" ::: "memory")
; #define SB_WAIT_L0() asm volatile("s_waitcnt lgkmcnt(0)" ::: "memory")
; __device__ __forceinline__ void sb_attn_item(bf16_t* PB, const bf16_t* VT, int b, int h, int qb, int lane, LAS unsigned char* wl  ) {
;     ...
;     SB_WAIT_V(0); SB_WAIT_L0();
; #pragma unroll
;     for (int blk = 0; blk < 4; ++blk)
; #pragma unroll
;         for (int g = 0; g < 4; ++g) { u32x2 w; w.x = cvtpk(o[blk][4 * g], o[blk][4 * g + 1]); w.y = cvtpk(o[blk][4 * g + 2], o[blk][4 * g + 3]);
;             *(LAS u32x2*)(kbuf + koff + (((4 * blk + g) ^ kx) << 4) + 8 * hi) = w; }
;     SB_WAIT_L0();
;     {
;         int ln = lane; asm volatile("" : "+v"(ln));
;         const size_t rowb = (size_t)(b * SEQ + qb * 32);
; #pragma unroll
;         for (int c = 0; c < 8; ++c) { const int r = 4 * c + (ln >> 4), chunk = (ln & 15) ^ (r & 15);
;             const u32x4 ov = *(const LAS u32x4*)(kbuf + c * 1024 + ln * 16);
;             bf16_t* rp = PB + (rowb + r) * PBW + h * 128 + chunk * 8;
;             const u32x4 zz = *(const u32x4*)(rp + C_ZB);
.LBB0_348:
	s_waitcnt vmcnt(0)
	s_nop 7
	v_cvt_pk_bf16_f32 v0, v0, v1
	v_cvt_pk_bf16_f32 v1, v2, v3
	v_add_u32_e32 v2, v151, v152
	s_waitcnt lgkmcnt(0)
	ds_write_b64 v2, v[0:1]
	v_cvt_pk_bf16_f32 v0, v4, v5
	v_cvt_pk_bf16_f32 v1, v6, v7
	ds_write_b64 v153, v[0:1]
	v_cvt_pk_bf16_f32 v0, v8, v9
	v_cvt_pk_bf16_f32 v1, v10, v11
	ds_write_b64 v154, v[0:1]
	v_cvt_pk_bf16_f32 v0, v12, v13
	v_cvt_pk_bf16_f32 v1, v14, v15
	ds_write_b64 v155, v[0:1]
	v_cvt_pk_bf16_f32 v0, v16, v17
	v_cvt_pk_bf16_f32 v1, v18, v19
	ds_write_b64 v156, v[0:1]
	v_cvt_pk_bf16_f32 v0, v20, v21
	v_cvt_pk_bf16_f32 v1, v22, v23
	ds_write_b64 v157, v[0:1]
	v_cvt_pk_bf16_f32 v0, v24, v25
	v_cvt_pk_bf16_f32 v1, v26, v27
	ds_write_b64 v158, v[0:1]
	v_cvt_pk_bf16_f32 v0, v28, v29
	v_cvt_pk_bf16_f32 v1, v30, v31
	ds_write_b64 v159, v[0:1]
	v_cvt_pk_bf16_f32 v0, v32, v33
	v_cvt_pk_bf16_f32 v1, v34, v35
	ds_write_b64 v160, v[0:1]
	v_cvt_pk_bf16_f32 v0, v36, v37
	v_cvt_pk_bf16_f32 v1, v38, v39
	ds_write_b64 v161, v[0:1]
	v_cvt_pk_bf16_f32 v0, v40, v41
	v_cvt_pk_bf16_f32 v1, v42, v43
	ds_write_b64 v162, v[0:1]
	v_cvt_pk_bf16_f32 v0, v44, v45
	v_cvt_pk_bf16_f32 v1, v46, v47
	ds_write_b64 v163, v[0:1]
	v_cvt_pk_bf16_f32 v0, v48, v49
	v_cvt_pk_bf16_f32 v1, v50, v51
	ds_write_b64 v164, v[0:1]
	v_cvt_pk_bf16_f32 v0, v52, v53
	v_cvt_pk_bf16_f32 v1, v54, v55
	s_lshl_b32 s33, s71, 5
	ds_write_b64 v166, v[0:1]
	v_cvt_pk_bf16_f32 v0, v56, v57
	v_cvt_pk_bf16_f32 v1, v58, v59
	ds_write_b64 v167, v[0:1]
	v_cvt_pk_bf16_f32 v0, v60, v61
	v_cvt_pk_bf16_f32 v1, v62, v63
	s_or_b32 s40, s33, s40
	ds_write_b64 v168, v[0:1]
	v_mov_b32_e32 v10, v150
	s_ashr_i32 s41, s40, 31
	s_waitcnt lgkmcnt(0)
	s_add_u32 s42, s92, s69
	v_ashrrev_i32_e32 v6, 4, v10
	s_addc_u32 s43, s93, 0
	v_ashrrev_i32_e32 v7, 31, v6
	v_xor_b32_e32 v8, v6, v10
	v_lshl_add_u64 v[0:1], v[6:7], 0, s[40:41]
	v_mov_b64_e32 v[4:5], s[42:43]
	v_mad_u64_u32 v[2:3], s[42:43], v0, s65, v[4:5]
	v_lshlrev_b32_e32 v0, 4, v8
	v_mad_i32_i24 v3, v1, s65, v3
	v_and_b32_e32 v194, 0xf0, v0
	v_lshl_add_u64 v[8:9], v[2:3], 0, v[194:195]
	v_mov_b32_e32 v98, 0x24000
	v_mov_b32_e32 v99, 0
	v_mov_b32_e32 v106, s72
	v_mov_b32_e32 v107, 0
	v_mov_b32_e32 v105, 0
	v_lshl_add_u64 v[100:101], v[2:3], 0, v[106:107]
	v_add_u32_e32 v96, 0, v6
	v_xor_b32_e32 v96, v96, v10
	v_lshlrev_b32_e32 v96, 4, v96
	v_and_b32_e32 v104, 0xf0, v96
	v_lshl_add_u64 v[108:109], v[100:101], 0, v[104:105]
	global_load_dwordx4 v[64:67], v[108:109], off
	v_lshl_add_u64 v[100:101], v[100:101], 0, v[98:99]
	v_add_u32_e32 v96, 4, v6
	v_xor_b32_e32 v96, v96, v10
	v_lshlrev_b32_e32 v96, 4, v96
	v_and_b32_e32 v104, 0xf0, v96
	v_lshl_add_u64 v[108:109], v[100:101], 0, v[104:105]
	global_load_dwordx4 v[68:71], v[108:109], off
	v_lshl_add_u64 v[100:101], v[100:101], 0, v[98:99]
	v_add_u32_e32 v96, 8, v6
	v_xor_b32_e32 v96, v96, v10
	v_lshlrev_b32_e32 v96, 4, v96
	v_and_b32_e32 v104, 0xf0, v96
	v_lshl_add_u64 v[108:109], v[100:101], 0, v[104:105]
	global_load_dwordx4 v[72:75], v[108:109], off
	v_lshl_add_u64 v[100:101], v[100:101], 0, v[98:99]
	v_add_u32_e32 v96, 12, v6
	v_xor_b32_e32 v96, v96, v10
	v_lshlrev_b32_e32 v96, 4, v96
	v_and_b32_e32 v104, 0xf0, v96
	v_lshl_add_u64 v[108:109], v[100:101], 0, v[104:105]
	global_load_dwordx4 v[76:79], v[108:109], off
	v_lshl_add_u64 v[100:101], v[100:101], 0, v[98:99]
	v_add_u32_e32 v96, 16, v6
	v_xor_b32_e32 v96, v96, v10
	v_lshlrev_b32_e32 v96, 4, v96
	v_and_b32_e32 v104, 0xf0, v96
	v_lshl_add_u64 v[108:109], v[100:101], 0, v[104:105]
	global_load_dwordx4 v[80:83], v[108:109], off
	v_lshl_add_u64 v[100:101], v[100:101], 0, v[98:99]
	v_add_u32_e32 v96, 20, v6
	v_xor_b32_e32 v96, v96, v10
	v_lshlrev_b32_e32 v96, 4, v96
	v_and_b32_e32 v104, 0xf0, v96
	v_lshl_add_u64 v[108:109], v[100:101], 0, v[104:105]
	global_load_dwordx4 v[84:87], v[108:109], off
	v_lshl_add_u64 v[100:101], v[100:101], 0, v[98:99]
	v_add_u32_e32 v96, 24, v6
	v_xor_b32_e32 v96, v96, v10
	v_lshlrev_b32_e32 v96, 4, v96
	v_and_b32_e32 v104, 0xf0, v96
	v_lshl_add_u64 v[108:109], v[100:101], 0, v[104:105]
	global_load_dwordx4 v[88:91], v[108:109], off
	v_lshl_add_u64 v[100:101], v[100:101], 0, v[98:99]
	v_add_u32_e32 v96, 28, v6
	v_xor_b32_e32 v96, v96, v10
	v_lshlrev_b32_e32 v96, 4, v96
	v_and_b32_e32 v104, 0xf0, v96
	v_lshl_add_u64 v[108:109], v[100:101], 0, v[104:105]
	global_load_dwordx4 v[92:95], v[108:109], off
	v_lshl_add_u64 v[100:101], v[100:101], 0, v[98:99]
	v_add_co_u32_e32 v0, vcc, s72, v8
	v_lshl_add_u32 v7, v10, 4, s86
	s_nop 0
	v_addc_co_u32_e32 v1, vcc, 0, v9, vcc
	ds_read_b128 v[16:19], v7
	ds_read_b128 v[0:3], v7 offset:1024
	v_add_co_u32_e32 v8, vcc, s1, v8
	s_add_i32 s50, s50, s74
	s_waitcnt lgkmcnt(0)
	v_lshlrev_b32_e32 v20, 16, v16
	v_and_b32_e32 v21, 0xffff0000, v16
	v_lshlrev_b32_e32 v16, 16, v17
	v_and_b32_e32 v17, 0xffff0000, v17
	v_addc_co_u32_e32 v9, vcc, 0, v9, vcc
	s_add_i32 s68, s68, s74
	s_add_i32 s56, s56, s82
	s_cmpk_gt_i32 s50, 0x1fff
	s_waitcnt vmcnt(7)
; #define LAS __attribute__((address_space(3)))
; __device__ __forceinline__ float fsigmoid(float v) { return __builtin_amdgcn_rcpf(1.f + __builtin_amdgcn_exp2f(-v * LOG2E)); }
; __device__ __forceinline__ u32x4 pack8(const float (&f)[8]) { u32x4 w; w.x = cvtpk(f[0], f[1]); w.y = cvtpk(f[2], f[3]); w.z = cvtpk(f[4], f[5]); w.w = cvtpk(f[6], f[7]); return w; }
; __device__ __forceinline__ void sb_attn_item(bf16_t* PB, const bf16_t* VT, int b, int h, int qb, int lane, LAS unsigned char* wl  ) {
;     ...
;         for (int c = 0; c < 8; ++c) { const int r = 4 * c + (ln >> 4), chunk = (ln & 15) ^ (r & 15);
;             const u32x4 ov = *(const LAS u32x4*)(kbuf + c * 1024 + ln * 16);
;             bf16_t* rp = PB + (rowb + r) * PBW + h * 128 + chunk * 8;
;             const u32x4 zz = *(const u32x4*)(rp + C_ZB);
;             float of[8], zf[8]; unpack8(ov, of); unpack8(zz, zf);
; #pragma unroll
;             for (int e = 0; e < 8; ++e) of[e] *= zf[e] * fsigmoid(zf[e]);
;             const u32x4 w = pack8(of);
;             *(u32x4*)(rp + C_Q) = w; }
	s_nop 1
	v_mov_b32_e32 v12, v64
	v_mov_b32_e32 v13, v65
	v_mov_b32_e32 v14, v66
	v_mov_b32_e32 v15, v67
	v_lshlrev_b32_e32 v22, 16, v12
	v_and_b32_e32 v23, 0xffff0000, v12
	v_lshlrev_b32_e32 v12, 16, v13
	v_mul_f32_e32 v11, 0xbfb8aa3b, v22
	v_mul_f32_e32 v24, 0xbfb8aa3b, v23
	v_and_b32_e32 v13, 0xffff0000, v13
	v_mul_f32_e32 v25, 0xbfb8aa3b, v12
	v_exp_f32_e32 v11, v11
	v_exp_f32_e32 v24, v24
	v_mul_f32_e32 v26, 0xbfb8aa3b, v13
	v_exp_f32_e32 v25, v25
	v_exp_f32_e32 v26, v26
	v_add_f32_e32 v11, 1.0, v11
	v_add_f32_e32 v27, 1.0, v24
	v_add_f32_e32 v28, 1.0, v25
	v_rcp_f32_e32 v24, v11
	v_rcp_f32_e32 v25, v27
	v_add_f32_e32 v29, 1.0, v26
	v_rcp_f32_e32 v26, v28
	v_rcp_f32_e32 v27, v29
	v_pk_mul_f32 v[22:23], v[24:25], v[22:23]
	v_pk_mul_f32 v[12:13], v[26:27], v[12:13]
	v_pk_mul_f32 v[20:21], v[22:23], v[20:21]
	v_lshlrev_b32_e32 v22, 16, v14
	v_and_b32_e32 v23, 0xffff0000, v14
	v_mul_f32_e32 v11, 0xbfb8aa3b, v22
	v_pk_mul_f32 v[16:17], v[12:13], v[16:17]
	v_exp_f32_e32 v11, v11
	v_mul_f32_e32 v13, 0xbfb8aa3b, v23
	v_exp_f32_e32 v14, v13
	v_lshlrev_b32_e32 v12, 16, v18
	v_add_f32_e32 v11, 1.0, v11
	v_rcp_f32_e32 v24, v11
	v_add_f32_e32 v11, 1.0, v14
	v_lshlrev_b32_e32 v14, 16, v15
	v_rcp_f32_e32 v25, v11
	v_and_b32_e32 v15, 0xffff0000, v15
	v_mul_f32_e32 v11, 0xbfb8aa3b, v14
	v_and_b32_e32 v13, 0xffff0000, v18
	v_exp_f32_e32 v11, v11
	v_mul_f32_e32 v18, 0xbfb8aa3b, v15
	v_exp_f32_e32 v18, v18
	v_pk_mul_f32 v[22:23], v[24:25], v[22:23]
	v_add_f32_e32 v11, 1.0, v11
	v_rcp_f32_e32 v24, v11
	v_add_f32_e32 v11, 1.0, v18
	v_rcp_f32_e32 v25, v11
	v_pk_mul_f32 v[22:23], v[22:23], v[12:13]
	v_lshlrev_b32_e32 v12, 16, v19
	v_and_b32_e32 v13, 0xffff0000, v19
	v_pk_mul_f32 v[14:15], v[24:25], v[14:15]
	s_nop 0
	v_pk_mul_f32 v[18:19], v[14:15], v[12:13]
	v_cvt_pk_bf16_f32 v12, v20, v21
	v_cvt_pk_bf16_f32 v13, v16, v17
	v_cvt_pk_bf16_f32 v14, v22, v23
	v_cvt_pk_bf16_f32 v15, v18, v19
	global_store_dwordx4 v[8:9], v[12:15], off nt
	v_add_u32_e32 v8, 4, v6
	v_ashrrev_i32_e32 v9, 31, v8
	v_xor_b32_e32 v11, v8, v10
	v_lshl_add_u64 v[8:9], v[8:9], 0, s[40:41]
	v_mad_u64_u32 v[12:13], s[42:43], v8, s65, v[4:5]
	v_lshlrev_b32_e32 v8, 4, v11
	v_mad_i32_i24 v13, v9, s65, v13
	v_and_b32_e32 v8, 0xf0, v8
	v_mov_b32_e32 v9, v195
	v_lshl_add_u64 v[8:9], v[12:13], 0, v[8:9]
	v_add_co_u32_e32 v12, vcc, s72, v8
	v_lshlrev_b32_e32 v18, 16, v2
	s_nop 0
	v_addc_co_u32_e32 v13, vcc, 0, v9, vcc
	v_and_b32_e32 v19, 0xffff0000, v2
	v_lshlrev_b32_e32 v16, 16, v0
	v_and_b32_e32 v17, 0xffff0000, v0
	v_lshlrev_b32_e32 v0, 16, v1
	v_and_b32_e32 v1, 0xffff0000, v1
	v_add_co_u32_e32 v8, vcc, s1, v8
	s_waitcnt vmcnt(7)
	s_nop 1
	v_mov_b32_e32 v12, v68
	v_mov_b32_e32 v13, v69
	v_mov_b32_e32 v14, v70
	v_mov_b32_e32 v15, v71
	v_lshlrev_b32_e32 v20, 16, v12
	v_and_b32_e32 v21, 0xffff0000, v12
	v_lshlrev_b32_e32 v12, 16, v13
	v_and_b32_e32 v13, 0xffff0000, v13
	v_lshlrev_b32_e32 v22, 16, v14
	v_and_b32_e32 v23, 0xffff0000, v14
	v_mul_f32_e32 v14, 0xbfb8aa3b, v12
	v_mul_f32_e32 v24, 0xbfb8aa3b, v13
	v_mul_f32_e32 v26, 0xbfb8aa3b, v23
	v_exp_f32_e32 v14, v14
	v_exp_f32_e32 v24, v24
	v_exp_f32_e32 v26, v26
	v_mul_f32_e32 v2, 0xbfb8aa3b, v20
	v_add_f32_e32 v14, 1.0, v14
	v_add_f32_e32 v27, 1.0, v24
	v_add_f32_e32 v29, 1.0, v26
	v_rcp_f32_e32 v26, v14
	v_rcp_f32_e32 v27, v27
	v_mul_f32_e32 v11, 0xbfb8aa3b, v21
	v_exp_f32_e32 v2, v2
	v_mul_f32_e32 v25, 0xbfb8aa3b, v22
	v_exp_f32_e32 v11, v11
	v_exp_f32_e32 v25, v25
	v_pk_mul_f32 v[12:13], v[26:27], v[12:13]
	v_add_f32_e32 v2, 1.0, v2
	v_pk_mul_f32 v[12:13], v[12:13], v[0:1]
	v_lshlrev_b32_e32 v0, 16, v15
	v_add_f32_e32 v11, 1.0, v11
	v_rcp_f32_e32 v24, v2
	v_and_b32_e32 v1, 0xffff0000, v15
	v_mul_f32_e32 v2, 0xbfb8aa3b, v0
	v_add_f32_e32 v28, 1.0, v25
	v_rcp_f32_e32 v25, v11
	v_exp_f32_e32 v2, v2
	v_mul_f32_e32 v11, 0xbfb8aa3b, v1
	v_exp_f32_e32 v11, v11
	v_pk_mul_f32 v[20:21], v[24:25], v[20:21]
	v_add_f32_e32 v2, 1.0, v2
	v_pk_mul_f32 v[16:17], v[20:21], v[16:17]
	v_rcp_f32_e32 v20, v2
	v_add_f32_e32 v2, 1.0, v11
	v_rcp_f32_e32 v28, v28
	v_rcp_f32_e32 v29, v29
	v_rcp_f32_e32 v21, v2
	v_lshlrev_b32_e32 v2, 16, v3
	v_and_b32_e32 v3, 0xffff0000, v3
	v_pk_mul_f32 v[14:15], v[28:29], v[22:23]
	v_pk_mul_f32 v[0:1], v[20:21], v[0:1]
	v_pk_mul_f32 v[14:15], v[14:15], v[18:19]
	v_pk_mul_f32 v[18:19], v[0:1], v[2:3]
	v_cvt_pk_bf16_f32 v0, v16, v17
	v_cvt_pk_bf16_f32 v1, v12, v13
	v_cvt_pk_bf16_f32 v2, v14, v15
	v_cvt_pk_bf16_f32 v3, v18, v19
	v_addc_co_u32_e32 v9, vcc, 0, v9, vcc
	global_store_dwordx4 v[8:9], v[0:3], off nt
	s_nop 1
	v_add_u32_e32 v0, 8, v6
	v_ashrrev_i32_e32 v1, 31, v0
	v_xor_b32_e32 v8, v0, v10
	v_lshl_add_u64 v[0:1], v[0:1], 0, s[40:41]
	v_mad_u64_u32 v[2:3], s[42:43], v0, s65, v[4:5]
	v_lshlrev_b32_e32 v0, 4, v8
	v_mad_i32_i24 v3, v1, s65, v3
	v_and_b32_e32 v0, 0xf0, v0
	v_mov_b32_e32 v1, v195
	v_lshl_add_u64 v[8:9], v[2:3], 0, v[0:1]
	v_add_co_u32_e32 v0, vcc, s72, v8
	s_nop 1
	v_addc_co_u32_e32 v1, vcc, 0, v9, vcc
	ds_read_b128 v[16:19], v7 offset:2048
	ds_read_b128 v[0:3], v7 offset:3072
	v_add_co_u32_e32 v8, vcc, s1, v8
	s_waitcnt lgkmcnt(1)
	v_lshlrev_b32_e32 v22, 16, v18
	v_and_b32_e32 v23, 0xffff0000, v18
	v_lshlrev_b32_e32 v20, 16, v16
	v_and_b32_e32 v21, 0xffff0000, v16
	v_lshlrev_b32_e32 v16, 16, v17
	v_and_b32_e32 v17, 0xffff0000, v17
	v_addc_co_u32_e32 v9, vcc, 0, v9, vcc
	s_waitcnt vmcnt(7)
; #define LAS __attribute__((address_space(3)))
; __device__ __forceinline__ float fsigmoid(float v) { return __builtin_amdgcn_rcpf(1.f + __builtin_amdgcn_exp2f(-v * LOG2E)); }
; __device__ __forceinline__ u32x4 pack8(const float (&f)[8]) { u32x4 w; w.x = cvtpk(f[0], f[1]); w.y = cvtpk(f[2], f[3]); w.z = cvtpk(f[4], f[5]); w.w = cvtpk(f[6], f[7]); return w; }
; __device__ __forceinline__ void sb_attn_item(bf16_t* PB, const bf16_t* VT, int b, int h, int qb, int lane, LAS unsigned char* wl  ) {
;     ...
;         for (int c = 0; c < 8; ++c) { const int r = 4 * c + (ln >> 4), chunk = (ln & 15) ^ (r & 15);
;             const u32x4 ov = *(const LAS u32x4*)(kbuf + c * 1024 + ln * 16);
;             bf16_t* rp = PB + (rowb + r) * PBW + h * 128 + chunk * 8;
;             const u32x4 zz = *(const u32x4*)(rp + C_ZB);
;             float of[8], zf[8]; unpack8(ov, of); unpack8(zz, zf);
; #pragma unroll
;             for (int e = 0; e < 8; ++e) of[e] *= zf[e] * fsigmoid(zf[e]);
;             const u32x4 w = pack8(of);
;             *(u32x4*)(rp + C_Q) = w; }
	s_nop 1
	v_mov_b32_e32 v12, v72
	v_mov_b32_e32 v13, v73
	v_mov_b32_e32 v14, v74
	v_mov_b32_e32 v15, v75
	v_lshlrev_b32_e32 v24, 16, v12
	v_and_b32_e32 v25, 0xffff0000, v12
	v_lshlrev_b32_e32 v12, 16, v13
	v_and_b32_e32 v13, 0xffff0000, v13
	v_lshlrev_b32_e32 v26, 16, v14
	v_and_b32_e32 v27, 0xffff0000, v14
	v_lshlrev_b32_e32 v14, 16, v15
	v_and_b32_e32 v15, 0xffff0000, v15
	v_mul_f32_e32 v28, 0xbfb8aa3b, v12
	v_mul_f32_e32 v29, 0xbfb8aa3b, v13
	v_mul_f32_e32 v11, 0xbfb8aa3b, v24
	v_mul_f32_e32 v18, 0xbfb8aa3b, v25
	v_mul_f32_e32 v30, 0xbfb8aa3b, v26
	v_mul_f32_e32 v31, 0xbfb8aa3b, v27
	v_mul_f32_e32 v32, 0xbfb8aa3b, v14
	v_mul_f32_e32 v33, 0xbfb8aa3b, v15
	v_exp_f32_e32 v28, v28
	v_exp_f32_e32 v29, v29
	v_exp_f32_e32 v11, v11
	v_exp_f32_e32 v18, v18
	v_exp_f32_e32 v30, v30
	v_exp_f32_e32 v31, v31
	v_exp_f32_e32 v32, v32
	v_exp_f32_e32 v33, v33
	v_add_f32_e32 v34, 1.0, v28
	v_add_f32_e32 v35, 1.0, v29
	v_add_f32_e32 v11, 1.0, v11
	v_add_f32_e32 v18, 1.0, v18
	v_add_f32_e32 v36, 1.0, v30
	v_add_f32_e32 v37, 1.0, v31
	v_add_f32_e32 v38, 1.0, v32
	v_add_f32_e32 v39, 1.0, v33
	v_rcp_f32_e32 v30, v34
	v_rcp_f32_e32 v31, v35
	v_rcp_f32_e32 v28, v11
	v_rcp_f32_e32 v29, v18
	v_rcp_f32_e32 v32, v36
	v_rcp_f32_e32 v33, v37
	v_rcp_f32_e32 v34, v38
	v_rcp_f32_e32 v35, v39
	v_pk_mul_f32 v[12:13], v[30:31], v[12:13]
	v_pk_mul_f32 v[24:25], v[28:29], v[24:25]
	v_pk_mul_f32 v[26:27], v[32:33], v[26:27]
	v_pk_mul_f32 v[16:17], v[12:13], v[16:17]
	v_lshlrev_b32_e32 v12, 16, v19
	v_and_b32_e32 v13, 0xffff0000, v19
	v_pk_mul_f32 v[14:15], v[34:35], v[14:15]
	v_pk_mul_f32 v[20:21], v[24:25], v[20:21]
	v_pk_mul_f32 v[22:23], v[26:27], v[22:23]
	v_pk_mul_f32 v[18:19], v[14:15], v[12:13]
	v_cvt_pk_bf16_f32 v12, v20, v21
	v_cvt_pk_bf16_f32 v13, v16, v17
	v_cvt_pk_bf16_f32 v14, v22, v23
	v_cvt_pk_bf16_f32 v15, v18, v19
	global_store_dwordx4 v[8:9], v[12:15], off nt
	v_add_u32_e32 v8, 12, v6
	v_ashrrev_i32_e32 v9, 31, v8
	v_xor_b32_e32 v11, v8, v10
	v_lshl_add_u64 v[8:9], v[8:9], 0, s[40:41]
	v_mad_u64_u32 v[12:13], s[42:43], v8, s65, v[4:5]
	v_lshlrev_b32_e32 v8, 4, v11
	v_mad_i32_i24 v13, v9, s65, v13
	v_and_b32_e32 v8, 0xf0, v8
	v_mov_b32_e32 v9, v195
	v_lshl_add_u64 v[8:9], v[12:13], 0, v[8:9]
	v_add_co_u32_e32 v12, vcc, s72, v8
	v_add_u32_e32 v16, 16, v6
	s_nop 0
	v_addc_co_u32_e32 v13, vcc, 0, v9, vcc
	s_waitcnt lgkmcnt(0)
	v_lshlrev_b32_e32 v18, 16, v0
	v_and_b32_e32 v19, 0xffff0000, v0
	v_lshlrev_b32_e32 v0, 16, v1
	v_and_b32_e32 v1, 0xffff0000, v1
	v_lshlrev_b32_e32 v20, 16, v2
	v_and_b32_e32 v21, 0xffff0000, v2
	v_lshlrev_b32_e32 v2, 16, v3
	v_and_b32_e32 v3, 0xffff0000, v3
	v_ashrrev_i32_e32 v17, 31, v16
	v_add_co_u32_e32 v8, vcc, s1, v8
	v_lshl_add_u64 v[16:17], v[16:17], 0, s[40:41]
	s_nop 0
	v_addc_co_u32_e32 v9, vcc, 0, v9, vcc
	s_waitcnt vmcnt(7)
	s_nop 1
	v_mov_b32_e32 v12, v76
	v_mov_b32_e32 v13, v77
	v_mov_b32_e32 v14, v78
	v_mov_b32_e32 v15, v79
	v_lshlrev_b32_e32 v22, 16, v12
	v_and_b32_e32 v23, 0xffff0000, v12
	v_lshlrev_b32_e32 v12, 16, v13
	v_and_b32_e32 v13, 0xffff0000, v13
	v_lshlrev_b32_e32 v24, 16, v14
	v_and_b32_e32 v25, 0xffff0000, v14
	v_lshlrev_b32_e32 v14, 16, v15
	v_and_b32_e32 v15, 0xffff0000, v15
	v_mul_f32_e32 v11, 0xbfb8aa3b, v22
	v_mul_f32_e32 v26, 0xbfb8aa3b, v23
	v_mul_f32_e32 v27, 0xbfb8aa3b, v12
	v_mul_f32_e32 v28, 0xbfb8aa3b, v13
	v_mul_f32_e32 v29, 0xbfb8aa3b, v24
	v_mul_f32_e32 v30, 0xbfb8aa3b, v25
	v_mul_f32_e32 v31, 0xbfb8aa3b, v14
	v_mul_f32_e32 v32, 0xbfb8aa3b, v15
	v_exp_f32_e32 v11, v11
	v_exp_f32_e32 v26, v26
	v_exp_f32_e32 v27, v27
	v_exp_f32_e32 v28, v28
	v_exp_f32_e32 v29, v29
	v_exp_f32_e32 v30, v30
	v_exp_f32_e32 v31, v31
	v_exp_f32_e32 v32, v32
	v_add_f32_e32 v11, 1.0, v11
	v_add_f32_e32 v33, 1.0, v26
	v_add_f32_e32 v34, 1.0, v27
	v_add_f32_e32 v35, 1.0, v28
	v_add_f32_e32 v36, 1.0, v29
	v_add_f32_e32 v37, 1.0, v30
	v_add_f32_e32 v38, 1.0, v31
	v_add_f32_e32 v39, 1.0, v32
	v_rcp_f32_e32 v26, v11
	v_rcp_f32_e32 v27, v33
	v_rcp_f32_e32 v28, v34
	v_rcp_f32_e32 v29, v35
	v_rcp_f32_e32 v30, v36
	v_rcp_f32_e32 v31, v37
	v_rcp_f32_e32 v32, v38
	v_rcp_f32_e32 v33, v39
	v_pk_mul_f32 v[22:23], v[26:27], v[22:23]
	v_pk_mul_f32 v[12:13], v[28:29], v[12:13]
	v_pk_mul_f32 v[24:25], v[30:31], v[24:25]
	v_pk_mul_f32 v[14:15], v[32:33], v[14:15]
	v_pk_mul_f32 v[18:19], v[22:23], v[18:19]
	v_pk_mul_f32 v[12:13], v[12:13], v[0:1]
	v_pk_mul_f32 v[20:21], v[24:25], v[20:21]
	v_pk_mul_f32 v[14:15], v[14:15], v[2:3]
	v_cvt_pk_bf16_f32 v0, v18, v19
	v_cvt_pk_bf16_f32 v1, v12, v13
	v_cvt_pk_bf16_f32 v2, v20, v21
	v_cvt_pk_bf16_f32 v3, v14, v15
	global_store_dwordx4 v[8:9], v[0:3], off nt
	v_add_u32_e32 v20, 20, v6
	v_xor_b32_e32 v11, v20, v10
	v_mad_u64_u32 v[0:1], s[42:43], v16, s65, v[4:5]
	v_mad_i32_i24 v1, v17, s65, v1
	v_lshl_add_u64 v[8:9], v[0:1], 0, v[194:195]
	v_add_co_u32_e32 v0, vcc, s72, v8
	v_lshlrev_b32_e32 v11, 4, v11
	s_nop 0
	v_addc_co_u32_e32 v1, vcc, 0, v9, vcc
	v_and_b32_e32 v194, 0xf0, v11
	ds_read_b128 v[12:15], v7 offset:4096
	ds_read_b128 v[16:19], v7 offset:5120
	v_ashrrev_i32_e32 v21, 31, v20
	v_lshl_add_u64 v[20:21], v[20:21], 0, s[40:41]
	v_mad_u64_u32 v[22:23], s[42:43], v20, s65, v[4:5]
	v_mad_i32_i24 v23, v21, s65, v23
	s_waitcnt lgkmcnt(1)
	v_lshlrev_b32_e32 v20, 16, v12
	v_and_b32_e32 v21, 0xffff0000, v12
	v_lshlrev_b32_e32 v12, 16, v13
	v_and_b32_e32 v13, 0xffff0000, v13
	v_lshlrev_b32_e32 v24, 16, v14
	v_and_b32_e32 v25, 0xffff0000, v14
	v_lshlrev_b32_e32 v14, 16, v15
	v_and_b32_e32 v15, 0xffff0000, v15
	v_add_co_u32_e32 v8, vcc, s1, v8
	v_lshl_add_u64 v[22:23], v[22:23], 0, v[194:195]
	s_nop 0
	v_addc_co_u32_e32 v9, vcc, 0, v9, vcc
	v_add_co_u32_e32 v26, vcc, s72, v22
	s_waitcnt vmcnt(7)
; #define LAS __attribute__((address_space(3)))
; __device__ __forceinline__ float fsigmoid(float v) { return __builtin_amdgcn_rcpf(1.f + __builtin_amdgcn_exp2f(-v * LOG2E)); }
; __device__ __forceinline__ u32x4 pack8(const float (&f)[8]) { u32x4 w; w.x = cvtpk(f[0], f[1]); w.y = cvtpk(f[2], f[3]); w.z = cvtpk(f[4], f[5]); w.w = cvtpk(f[6], f[7]); return w; }
; __device__ __forceinline__ void sb_attn_item(bf16_t* PB, const bf16_t* VT, int b, int h, int qb, int lane, LAS unsigned char* wl  ) {
;     ...
;         for (int c = 0; c < 8; ++c) { const int r = 4 * c + (ln >> 4), chunk = (ln & 15) ^ (r & 15);
;             const u32x4 ov = *(const LAS u32x4*)(kbuf + c * 1024 + ln * 16);
;             bf16_t* rp = PB + (rowb + r) * PBW + h * 128 + chunk * 8;
;             const u32x4 zz = *(const u32x4*)(rp + C_ZB);
;             float of[8], zf[8]; unpack8(ov, of); unpack8(zz, zf);
; #pragma unroll
;             for (int e = 0; e < 8; ++e) of[e] *= zf[e] * fsigmoid(zf[e]);
;             const u32x4 w = pack8(of);
;             *(u32x4*)(rp + C_Q) = w; }
	s_nop 1
	v_mov_b32_e32 v0, v80
	v_mov_b32_e32 v1, v81
	v_mov_b32_e32 v2, v82
	v_mov_b32_e32 v3, v83
	v_lshlrev_b32_e32 v28, 16, v0
	v_and_b32_e32 v29, 0xffff0000, v0
	v_lshlrev_b32_e32 v0, 16, v1
	v_and_b32_e32 v1, 0xffff0000, v1
	v_lshlrev_b32_e32 v30, 16, v2
	v_and_b32_e32 v31, 0xffff0000, v2
	v_lshlrev_b32_e32 v2, 16, v3
	v_and_b32_e32 v3, 0xffff0000, v3
	v_mul_f32_e32 v11, 0xbfb8aa3b, v28
	v_mul_f32_e32 v32, 0xbfb8aa3b, v29
	v_mul_f32_e32 v33, 0xbfb8aa3b, v0
	v_mul_f32_e32 v34, 0xbfb8aa3b, v1
	v_mul_f32_e32 v35, 0xbfb8aa3b, v30
	v_mul_f32_e32 v36, 0xbfb8aa3b, v31
	v_mul_f32_e32 v37, 0xbfb8aa3b, v2
	v_mul_f32_e32 v38, 0xbfb8aa3b, v3
	v_exp_f32_e32 v11, v11
	v_exp_f32_e32 v32, v32
	v_exp_f32_e32 v33, v33
	v_exp_f32_e32 v34, v34
	v_exp_f32_e32 v35, v35
	v_exp_f32_e32 v36, v36
	v_exp_f32_e32 v37, v37
	v_exp_f32_e32 v38, v38
	v_add_f32_e32 v11, 1.0, v11
	v_add_f32_e32 v39, 1.0, v32
	v_add_f32_e32 v40, 1.0, v33
	v_add_f32_e32 v41, 1.0, v34
	v_add_f32_e32 v42, 1.0, v35
	v_add_f32_e32 v43, 1.0, v36
	v_add_f32_e32 v44, 1.0, v37
	v_add_f32_e32 v45, 1.0, v38
	v_rcp_f32_e32 v32, v11
	v_rcp_f32_e32 v33, v39
	v_rcp_f32_e32 v34, v40
	v_rcp_f32_e32 v35, v41
	v_rcp_f32_e32 v36, v42
	v_rcp_f32_e32 v37, v43
	v_rcp_f32_e32 v38, v44
	v_rcp_f32_e32 v39, v45
	v_pk_mul_f32 v[28:29], v[32:33], v[28:29]
	v_pk_mul_f32 v[0:1], v[34:35], v[0:1]
	v_pk_mul_f32 v[30:31], v[36:37], v[30:31]
	v_pk_mul_f32 v[2:3], v[38:39], v[2:3]
	v_pk_mul_f32 v[20:21], v[28:29], v[20:21]
	v_pk_mul_f32 v[12:13], v[0:1], v[12:13]
	v_pk_mul_f32 v[24:25], v[30:31], v[24:25]
	v_pk_mul_f32 v[14:15], v[2:3], v[14:15]
	v_cvt_pk_bf16_f32 v0, v20, v21
	v_cvt_pk_bf16_f32 v1, v12, v13
	v_cvt_pk_bf16_f32 v2, v24, v25
	v_cvt_pk_bf16_f32 v3, v14, v15
	v_addc_co_u32_e32 v27, vcc, 0, v23, vcc
	global_store_dwordx4 v[8:9], v[0:3], off nt
	v_add_u32_e32 v8, 24, v6
	v_xor_b32_e32 v11, v8, v10
	v_lshlrev_b32_e32 v11, 4, v11
	v_and_b32_e32 v194, 0xf0, v11
	v_ashrrev_i32_e32 v9, 31, v8
	v_lshl_add_u64 v[8:9], v[8:9], 0, s[40:41]
	v_mad_u64_u32 v[12:13], s[42:43], v8, s65, v[4:5]
	v_mad_i32_i24 v13, v9, s65, v13
	s_waitcnt lgkmcnt(0)
	v_lshlrev_b32_e32 v8, 16, v16
	v_and_b32_e32 v9, 0xffff0000, v16
	v_lshlrev_b32_e32 v14, 16, v17
	v_and_b32_e32 v15, 0xffff0000, v17
	v_lshlrev_b32_e32 v16, 16, v18
	v_and_b32_e32 v17, 0xffff0000, v18
	v_lshlrev_b32_e32 v18, 16, v19
	v_and_b32_e32 v19, 0xffff0000, v19
	v_add_co_u32_e32 v20, vcc, s1, v22
	s_waitcnt vmcnt(7)
	s_nop 1
	v_mov_b32_e32 v0, v84
	v_mov_b32_e32 v1, v85
	v_mov_b32_e32 v2, v86
	v_mov_b32_e32 v3, v87
	v_lshlrev_b32_e32 v24, 16, v0
	v_and_b32_e32 v25, 0xffff0000, v0
	v_lshlrev_b32_e32 v0, 16, v1
	v_and_b32_e32 v1, 0xffff0000, v1
	v_lshlrev_b32_e32 v26, 16, v2
	v_and_b32_e32 v27, 0xffff0000, v2
	v_lshlrev_b32_e32 v2, 16, v3
	v_and_b32_e32 v3, 0xffff0000, v3
	v_mul_f32_e32 v11, 0xbfb8aa3b, v24
	v_mul_f32_e32 v28, 0xbfb8aa3b, v25
	v_mul_f32_e32 v29, 0xbfb8aa3b, v0
	v_mul_f32_e32 v30, 0xbfb8aa3b, v1
	v_mul_f32_e32 v31, 0xbfb8aa3b, v26
	v_mul_f32_e32 v32, 0xbfb8aa3b, v27
	v_mul_f32_e32 v33, 0xbfb8aa3b, v2
	v_mul_f32_e32 v34, 0xbfb8aa3b, v3
	v_exp_f32_e32 v11, v11
	v_exp_f32_e32 v28, v28
	v_exp_f32_e32 v29, v29
	v_exp_f32_e32 v30, v30
	v_exp_f32_e32 v31, v31
	v_exp_f32_e32 v32, v32
	v_exp_f32_e32 v33, v33
	v_exp_f32_e32 v34, v34
	v_add_f32_e32 v11, 1.0, v11
	v_add_f32_e32 v35, 1.0, v28
	v_add_f32_e32 v36, 1.0, v29
	v_add_f32_e32 v37, 1.0, v30
	v_add_f32_e32 v38, 1.0, v31
	v_add_f32_e32 v39, 1.0, v32
	v_add_f32_e32 v40, 1.0, v33
	v_add_f32_e32 v41, 1.0, v34
	v_rcp_f32_e32 v28, v11
	v_rcp_f32_e32 v29, v35
	v_rcp_f32_e32 v30, v36
	v_rcp_f32_e32 v31, v37
	v_rcp_f32_e32 v32, v38
	v_rcp_f32_e32 v33, v39
	v_rcp_f32_e32 v34, v40
	v_rcp_f32_e32 v35, v41
	v_pk_mul_f32 v[24:25], v[28:29], v[24:25]
	v_pk_mul_f32 v[0:1], v[30:31], v[0:1]
	v_pk_mul_f32 v[26:27], v[32:33], v[26:27]
	v_pk_mul_f32 v[2:3], v[34:35], v[2:3]
	v_addc_co_u32_e32 v21, vcc, 0, v23, vcc
	v_lshl_add_u64 v[22:23], v[12:13], 0, v[194:195]
	v_pk_mul_f32 v[8:9], v[24:25], v[8:9]
	v_pk_mul_f32 v[14:15], v[0:1], v[14:15]
	v_pk_mul_f32 v[16:17], v[26:27], v[16:17]
	v_pk_mul_f32 v[18:19], v[2:3], v[18:19]
	v_add_co_u32_e32 v12, vcc, s72, v22
	v_cvt_pk_bf16_f32 v0, v8, v9
	v_cvt_pk_bf16_f32 v1, v14, v15
	v_cvt_pk_bf16_f32 v2, v16, v17
	v_cvt_pk_bf16_f32 v3, v18, v19
	v_addc_co_u32_e32 v13, vcc, 0, v23, vcc
	global_store_dwordx4 v[20:21], v[0:3], off nt
	v_add_u32_e32 v16, 28, v6
	v_xor_b32_e32 v18, v16, v10
	v_lshlrev_b32_e32 v18, 4, v18
	v_and_b32_e32 v194, 0xf0, v18
	v_add_co_u32_e32 v18, vcc, s1, v22
	ds_read_b128 v[12:15], v7 offset:6144
	ds_read_b128 v[6:9], v7 offset:7168
	v_addc_co_u32_e32 v19, vcc, 0, v23, vcc
	v_ashrrev_i32_e32 v17, 31, v16
	v_lshl_add_u64 v[10:11], v[16:17], 0, s[40:41]
	v_mad_u64_u32 v[4:5], s[40:41], v10, s65, v[4:5]
	v_mad_i32_i24 v5, v11, s65, v5
	s_waitcnt lgkmcnt(1)
; #define LAS __attribute__((address_space(3)))
; __device__ __forceinline__ float fsigmoid(float v) { return __builtin_amdgcn_rcpf(1.f + __builtin_amdgcn_exp2f(-v * LOG2E)); }
; __device__ __forceinline__ u32x4 pack8(const float (&f)[8]) { u32x4 w; w.x = cvtpk(f[0], f[1]); w.y = cvtpk(f[2], f[3]); w.z = cvtpk(f[4], f[5]); w.w = cvtpk(f[6], f[7]); return w; }
; __device__ __forceinline__ void sb_attn_item(bf16_t* PB, const bf16_t* VT, int b, int h, int qb, int lane, LAS unsigned char* wl  ) {
;     ...
;         for (int c = 0; c < 8; ++c) { const int r = 4 * c + (ln >> 4), chunk = (ln & 15) ^ (r & 15);
;             const u32x4 ov = *(const LAS u32x4*)(kbuf + c * 1024 + ln * 16);
;             bf16_t* rp = PB + (rowb + r) * PBW + h * 128 + chunk * 8;
;             const u32x4 zz = *(const u32x4*)(rp + C_ZB);
;             float of[8], zf[8]; unpack8(ov, of); unpack8(zz, zf);
; #pragma unroll
;             for (int e = 0; e < 8; ++e) of[e] *= zf[e] * fsigmoid(zf[e]);
;             const u32x4 w = pack8(of);
;             *(u32x4*)(rp + C_Q) = w; }
; __device__ __forceinline__ void phase_mixers(PP p, int l, int lane, int wave, LAS unsigned char* lds) {
;     ...
;     for (int item = gwa; item < NBATCH * 16 * 128; item += NGW) { const int bh = item >> 7, qb = item & 127; sb_attn_item(PB, VT, bh >> 4, bh & 15, qb, lane, lds + wave * 16384); }
	v_lshlrev_b32_e32 v10, 16, v12
	v_and_b32_e32 v11, 0xffff0000, v12
	v_lshlrev_b32_e32 v12, 16, v13
	v_and_b32_e32 v13, 0xffff0000, v13
	v_lshlrev_b32_e32 v16, 16, v14
	v_and_b32_e32 v17, 0xffff0000, v14
	v_lshlrev_b32_e32 v14, 16, v15
	v_and_b32_e32 v15, 0xffff0000, v15
	v_lshl_add_u64 v[4:5], v[4:5], 0, v[194:195]
	v_add_co_u32_e32 v20, vcc, s72, v4
	s_waitcnt vmcnt(7)
	s_nop 1
	v_mov_b32_e32 v0, v88
	v_mov_b32_e32 v1, v89
	v_mov_b32_e32 v2, v90
	v_mov_b32_e32 v3, v91
	v_lshlrev_b32_e32 v22, 16, v0
	v_and_b32_e32 v23, 0xffff0000, v0
	v_lshlrev_b32_e32 v0, 16, v1
	v_and_b32_e32 v1, 0xffff0000, v1
	v_lshlrev_b32_e32 v24, 16, v2
	v_and_b32_e32 v25, 0xffff0000, v2
	v_lshlrev_b32_e32 v2, 16, v3
	v_and_b32_e32 v3, 0xffff0000, v3
	v_mul_f32_e32 v26, 0xbfb8aa3b, v22
	v_mul_f32_e32 v27, 0xbfb8aa3b, v23
	v_mul_f32_e32 v28, 0xbfb8aa3b, v0
	v_mul_f32_e32 v29, 0xbfb8aa3b, v1
	v_mul_f32_e32 v30, 0xbfb8aa3b, v24
	v_mul_f32_e32 v31, 0xbfb8aa3b, v25
	v_mul_f32_e32 v32, 0xbfb8aa3b, v2
	v_mul_f32_e32 v33, 0xbfb8aa3b, v3
	v_exp_f32_e32 v26, v26
	v_exp_f32_e32 v27, v27
	v_exp_f32_e32 v28, v28
	v_exp_f32_e32 v29, v29
	v_exp_f32_e32 v30, v30
	v_exp_f32_e32 v31, v31
	v_exp_f32_e32 v32, v32
	v_exp_f32_e32 v33, v33
	v_add_f32_e32 v26, 1.0, v26
	v_add_f32_e32 v27, 1.0, v27
	v_add_f32_e32 v28, 1.0, v28
	v_add_f32_e32 v29, 1.0, v29
	v_add_f32_e32 v30, 1.0, v30
	v_add_f32_e32 v31, 1.0, v31
	v_add_f32_e32 v32, 1.0, v32
	v_add_f32_e32 v33, 1.0, v33
	v_rcp_f32_e32 v26, v26
	v_rcp_f32_e32 v27, v27
	v_rcp_f32_e32 v28, v28
	v_rcp_f32_e32 v29, v29
	v_rcp_f32_e32 v30, v30
	v_rcp_f32_e32 v31, v31
	v_rcp_f32_e32 v32, v32
	v_rcp_f32_e32 v33, v33
	v_pk_mul_f32 v[22:23], v[26:27], v[22:23]
	v_pk_mul_f32 v[0:1], v[28:29], v[0:1]
	v_pk_mul_f32 v[24:25], v[30:31], v[24:25]
	v_pk_mul_f32 v[2:3], v[32:33], v[2:3]
	v_pk_mul_f32 v[10:11], v[22:23], v[10:11]
	v_pk_mul_f32 v[12:13], v[0:1], v[12:13]
	v_pk_mul_f32 v[16:17], v[24:25], v[16:17]
	v_pk_mul_f32 v[14:15], v[2:3], v[14:15]
	v_cvt_pk_bf16_f32 v0, v10, v11
	v_cvt_pk_bf16_f32 v1, v12, v13
	v_cvt_pk_bf16_f32 v2, v16, v17
	v_cvt_pk_bf16_f32 v3, v14, v15
	v_addc_co_u32_e32 v21, vcc, 0, v5, vcc
	global_store_dwordx4 v[18:19], v[0:3], off nt
	s_waitcnt lgkmcnt(0)
	v_lshlrev_b32_e32 v10, 16, v6
	v_and_b32_e32 v11, 0xffff0000, v6
	v_lshlrev_b32_e32 v6, 16, v7
	v_and_b32_e32 v7, 0xffff0000, v7
	v_lshlrev_b32_e32 v12, 16, v8
	v_and_b32_e32 v13, 0xffff0000, v8
	v_lshlrev_b32_e32 v8, 16, v9
	v_and_b32_e32 v9, 0xffff0000, v9
	v_add_co_u32_e32 v4, vcc, 0x1000, v4
	s_waitcnt vmcnt(7)
	s_nop 1
	v_mov_b32_e32 v0, v92
	v_mov_b32_e32 v1, v93
	v_mov_b32_e32 v2, v94
	v_mov_b32_e32 v3, v95
	v_lshlrev_b32_e32 v14, 16, v0
	v_and_b32_e32 v15, 0xffff0000, v0
	v_lshlrev_b32_e32 v0, 16, v1
	v_and_b32_e32 v1, 0xffff0000, v1
	v_lshlrev_b32_e32 v16, 16, v2
	v_and_b32_e32 v17, 0xffff0000, v2
	v_lshlrev_b32_e32 v2, 16, v3
	v_and_b32_e32 v3, 0xffff0000, v3
	v_mul_f32_e32 v18, 0xbfb8aa3b, v14
	v_mul_f32_e32 v19, 0xbfb8aa3b, v15
	v_mul_f32_e32 v20, 0xbfb8aa3b, v0
	v_mul_f32_e32 v21, 0xbfb8aa3b, v1
	v_mul_f32_e32 v22, 0xbfb8aa3b, v16
	v_mul_f32_e32 v23, 0xbfb8aa3b, v17
	v_mul_f32_e32 v24, 0xbfb8aa3b, v2
	v_mul_f32_e32 v25, 0xbfb8aa3b, v3
	v_exp_f32_e32 v18, v18
	v_exp_f32_e32 v19, v19
	v_exp_f32_e32 v20, v20
	v_exp_f32_e32 v21, v21
	v_exp_f32_e32 v22, v22
	v_exp_f32_e32 v23, v23
	v_exp_f32_e32 v24, v24
	v_exp_f32_e32 v25, v25
	v_add_f32_e32 v18, 1.0, v18
	v_add_f32_e32 v19, 1.0, v19
	v_add_f32_e32 v20, 1.0, v20
	v_add_f32_e32 v21, 1.0, v21
	v_add_f32_e32 v22, 1.0, v22
	v_add_f32_e32 v23, 1.0, v23
	v_add_f32_e32 v24, 1.0, v24
	v_add_f32_e32 v25, 1.0, v25
	v_rcp_f32_e32 v18, v18
	v_rcp_f32_e32 v19, v19
	v_rcp_f32_e32 v20, v20
	v_rcp_f32_e32 v21, v21
	v_rcp_f32_e32 v22, v22
	v_rcp_f32_e32 v23, v23
	v_rcp_f32_e32 v24, v24
	v_rcp_f32_e32 v25, v25
	v_pk_mul_f32 v[14:15], v[18:19], v[14:15]
	v_pk_mul_f32 v[0:1], v[20:21], v[0:1]
	v_pk_mul_f32 v[16:17], v[22:23], v[16:17]
	v_pk_mul_f32 v[2:3], v[24:25], v[2:3]
	v_pk_mul_f32 v[10:11], v[14:15], v[10:11]
	v_pk_mul_f32 v[6:7], v[0:1], v[6:7]
	v_pk_mul_f32 v[12:13], v[16:17], v[12:13]
	v_pk_mul_f32 v[8:9], v[2:3], v[8:9]
	v_addc_co_u32_e32 v5, vcc, 0, v5, vcc
	v_cvt_pk_bf16_f32 v0, v10, v11
	v_cvt_pk_bf16_f32 v1, v6, v7
	v_cvt_pk_bf16_f32 v2, v12, v13
	v_cvt_pk_bf16_f32 v3, v8, v9
	global_store_dwordx4 v[4:5], v[0:3], off nt
	s_cbranch_scc1 .LBB0_369

; __device__ __forceinline__ float fsigmoid(float v) { return __builtin_amdgcn_rcpf(1.f + __builtin_amdgcn_exp2f(-v * LOG2E)); }
; __device__ __forceinline__ u32x4 pack8(const float (&f)[8]) { u32x4 w; w.x = cvtpk(f[0], f[1]); w.y = cvtpk(f[2], f[3]); w.z = cvtpk(f[4], f[5]); w.w = cvtpk(f[6], f[7]); return w; }
; template <int W, int NI> __device__ __forceinline__ void pool_items(bf16_t* PB, const float* pscale, const int (&rps)[NI], int g, int lane) {
;     const int ch = g * 256 + (lane & 31) * 8;
;     u32x4 v[NI][W], zw[NI]; int t[NI]; bf16_t* zp[NI];
; #pragma unroll
;     for (int q = 0; q < NI; ++q) { const int row = 2 * rps[q] + (lane >> 5); t[q] = row & (SEQ - 1);
;         const bf16_t* xp = PB + (size_t)row * PBW + C_XA + ch;
; #pragma unroll
;         for (int jj = 0; jj < W; ++jj) { const int back = (jj <= t[q]) ? jj : 0; v[q][jj] = *(const u32x4*)(xp - (size_t)back * PBW); }
;         zp[q] = PB + (size_t)row * PBW + C_ZA + ch; zw[q] = *(const u32x4*)zp[q]; }
;     const f32x4 p0 = *(const f32x4*)(pscale + ch), p1 = *(const f32x4*)(pscale + ch + 4);
;     u32x4 outw[NI];
; #pragma unroll
;     for (int q = 0; q < NI; ++q) {
;         float za[8], sum[8], x0[8]; unpack8(zw[q], za); unpack8(v[q][0], x0);
; #pragma unroll
;         for (int e = 0; e < 8; ++e) sum[e] = x0[e];
; #pragma unroll
;         for (int jj = 1; jj < W; ++jj) { float f[8]; unpack8(v[q][jj], f); const float mk = (jj <= t[q]) ? 1.f : 0.f;
; #pragma unroll
;             for (int e = 0; e < 8; ++e) sum[e] += mk * f[e]; }
;         const int cnt = (t[q] + 1 < W) ? (t[q] + 1) : W;
;         const float inv = 1.f / (float)cnt;
;         float y[8];
; #pragma unroll
;         for (int e = 0; e < 8; ++e) { const float ps = (e < 4) ? p0[e & 3] : p1[e & 3]; y[e] = (sum[e] * inv - x0[e]) * ps * (za[e] * fsigmoid(za[e])); }
;         outw[q] = pack8(y); }
.LBB0_371:
	v_add_u32_e32 v0, s13, v57
	v_add_u32_e32 v12, s14, v57
	s_add_i32 s15, s2, s74
	v_and_b32_e32 v4, 0xfff, v0
	v_mad_i64_i32 v[48:49], s[2:3], v0, s65, v[46:47]
	v_and_b32_e32 v13, 0xfff, v12
	v_mad_i64_i32 v[50:51], s[2:3], v12, s65, v[46:47]
	v_cmp_eq_u32_e32 vcc, 0, v4
	v_cmp_eq_u32_e64 s[2:3], 0, v13
	global_load_dwordx4 v[0:3], v[48:49], off
	v_cndmask_b32_e64 v5, -1, 0, vcc
	v_cndmask_b32_e64 v4, v225, 0, vcc
	v_cndmask_b32_e64 v13, -1, 0, s[2:3]
	v_cndmask_b32_e64 v12, v225, 0, s[2:3]
	v_lshl_add_u64 v[4:5], v[48:49], 0, v[4:5]
	v_lshl_add_u64 v[12:13], v[50:51], 0, v[12:13]
	global_load_dwordx4 v[4:7], v[4:5], off
	s_nop 0
	global_load_dwordx4 v[8:11], v[48:49], off offset:2048
	global_load_dwordx4 v[16:19], v[50:51], off
	global_load_dwordx4 v[24:27], v[12:13], off
	global_load_dwordx4 v[32:35], v[50:51], off offset:2048
	v_add_u32_e32 v12, s12, v57
	v_and_b32_e32 v13, 0xfff, v12
	v_mad_i64_i32 v[52:53], s[4:5], v12, s65, v[46:47]
	v_cmp_eq_u32_e64 s[4:5], 0, v13
	global_load_dwordx4 v[62:65], v[52:53], off
	s_waitcnt vmcnt(0)
	v_lshlrev_b32_e32 v78, 16, v65
	v_cndmask_b32_e64 v13, -1, 0, s[4:5]
	v_cndmask_b32_e64 v12, v225, 0, s[4:5]
	v_lshl_add_u64 v[12:13], v[52:53], 0, v[12:13]
	global_load_dwordx4 v[66:69], v[12:13], off
	global_load_dwordx4 v[70:73], v[52:53], off offset:2048
	v_add_u32_e32 v12, s11, v57
	v_and_b32_e32 v20, 0xfff, v12
	v_mad_i64_i32 v[54:55], s[6:7], v12, s65, v[46:47]
	v_cmp_eq_u32_e64 s[6:7], 0, v20
	global_load_dwordx4 v[12:15], v[54:55], off
	v_cndmask_b32_e64 v76, 1.0, 0, s[4:5]
	v_cndmask_b32_e64 v21, -1, 0, s[6:7]
	v_cndmask_b32_e64 v20, v225, 0, s[6:7]
	v_lshl_add_u64 v[20:21], v[54:55], 0, v[20:21]
	global_load_dwordx4 v[20:23], v[20:21], off
	s_nop 0
	global_load_dwordx4 v[28:31], v[54:55], off offset:2048
	global_load_dwordx4 v[40:43], v[44:45], off
	global_load_dwordx4 v[36:39], v[44:45], off offset:16
	v_and_b32_e32 v79, 0xffff0000, v65
	v_cndmask_b32_e64 v74, 0.5, 1.0, s[4:5]
	s_waitcnt vmcnt(5)
	v_lshlrev_b32_e32 v58, 16, v73
	v_mul_f32_e32 v56, 0xbfb8aa3b, v58
	v_exp_f32_e32 v56, v56
	v_and_b32_e32 v59, 0xffff0000, v73
	v_add_f32_e32 v56, 1.0, v56
	v_rcp_f32_e32 v60, v56
	v_mul_f32_e32 v56, 0xbfb8aa3b, v59
	v_exp_f32_e32 v56, v56
	s_waitcnt vmcnt(4)
	v_lshlrev_b32_e32 v82, 16, v14
	v_and_b32_e32 v83, 0xffff0000, v14
	v_add_f32_e32 v56, 1.0, v56
	v_rcp_f32_e32 v61, v56
	v_cndmask_b32_e64 v56, 0.5, 1.0, s[6:7]
	v_pk_mul_f32 v[58:59], v[60:61], v[58:59]
	v_lshlrev_b32_e32 v60, 16, v69
	v_and_b32_e32 v61, 0xffff0000, v69
	v_pk_fma_f32 v[60:61], v[76:77], v[60:61], v[78:79] op_sel_hi:[0,1,1]
	v_pk_fma_f32 v[60:61], v[74:75], v[60:61], v[78:79] op_sel_hi:[0,1,1] neg_lo:[0,0,1] neg_hi:[0,0,1]
	s_waitcnt vmcnt(0)
	v_pk_mul_f32 v[60:61], v[60:61], v[38:39]
	v_and_b32_e32 v69, 0xffff0000, v64
	v_pk_mul_f32 v[78:79], v[60:61], v[58:59]
	v_lshlrev_b32_e32 v60, 16, v30
	v_and_b32_e32 v61, 0xffff0000, v30
	v_mul_f32_e32 v30, 0xbfb8aa3b, v60
	v_exp_f32_e32 v30, v30
	v_cndmask_b32_e64 v58, 1.0, 0, s[6:7]
	v_add_f32_e32 v30, 1.0, v30
	v_rcp_f32_e32 v80, v30
	v_mul_f32_e32 v30, 0xbfb8aa3b, v61
	v_exp_f32_e32 v30, v30
	s_nop 0
	v_add_f32_e32 v30, 1.0, v30
	v_rcp_f32_e32 v81, v30
	s_nop 0
	v_pk_mul_f32 v[60:61], v[80:81], v[60:61]
	v_lshlrev_b32_e32 v80, 16, v22
	v_and_b32_e32 v81, 0xffff0000, v22
	v_pk_fma_f32 v[80:81], v[58:59], v[80:81], v[82:83] op_sel_hi:[0,1,1]
	v_pk_fma_f32 v[80:81], v[56:57], v[80:81], v[82:83] op_sel_hi:[0,1,1] neg_lo:[0,0,1] neg_hi:[0,0,1]
	v_pk_mul_f32 v[80:81], v[36:37], v[80:81]
	v_lshlrev_b32_e32 v82, 16, v63
	v_pk_mul_f32 v[60:61], v[80:81], v[60:61]
	v_lshlrev_b32_e32 v80, 16, v72
	v_mul_f32_e32 v14, 0xbfb8aa3b, v80
	v_exp_f32_e32 v14, v14
	v_and_b32_e32 v81, 0xffff0000, v72
	v_and_b32_e32 v83, 0xffff0000, v63
	v_add_f32_e32 v14, 1.0, v14
	v_rcp_f32_e32 v72, v14
	v_mul_f32_e32 v14, 0xbfb8aa3b, v81
	v_exp_f32_e32 v14, v14
	s_nop 0
	v_add_f32_e32 v14, 1.0, v14
	v_rcp_f32_e32 v73, v14
	s_nop 0
	v_pk_mul_f32 v[72:73], v[72:73], v[80:81]
	v_lshlrev_b32_e32 v80, 16, v68
	v_and_b32_e32 v81, 0xffff0000, v68
	v_lshlrev_b32_e32 v68, 16, v64
	v_pk_fma_f32 v[64:65], v[76:77], v[80:81], v[68:69] op_sel_hi:[0,1,1]
	v_pk_fma_f32 v[64:65], v[74:75], v[64:65], v[68:69] op_sel_hi:[0,1,1] neg_lo:[0,0,1] neg_hi:[0,0,1]
	v_lshlrev_b32_e32 v68, 16, v29
	v_mul_f32_e32 v14, 0xbfb8aa3b, v68
	v_exp_f32_e32 v14, v14
	v_pk_mul_f32 v[64:65], v[64:65], v[36:37]
	v_and_b32_e32 v69, 0xffff0000, v29
	v_pk_mul_f32 v[64:65], v[64:65], v[72:73]
	v_add_f32_e32 v14, 1.0, v14
	v_rcp_f32_e32 v72, v14
	v_mul_f32_e32 v14, 0xbfb8aa3b, v69
	v_exp_f32_e32 v14, v14
	v_lshlrev_b32_e32 v80, 16, v13
	v_and_b32_e32 v81, 0xffff0000, v13
	v_cvt_pk_bf16_f32 v64, v64, v65
	v_add_f32_e32 v14, 1.0, v14
	v_rcp_f32_e32 v73, v14
	v_cvt_pk_bf16_f32 v65, v78, v79
	v_pk_mul_f32 v[68:69], v[72:73], v[68:69]
	v_lshlrev_b32_e32 v72, 16, v21
	v_and_b32_e32 v73, 0xffff0000, v21
	v_pk_fma_f32 v[72:73], v[58:59], v[72:73], v[80:81] op_sel_hi:[0,1,1]
	v_pk_fma_f32 v[72:73], v[56:57], v[72:73], v[80:81] op_sel_hi:[0,1,1] neg_lo:[0,0,1] neg_hi:[0,0,1]
	v_pk_mul_f32 v[72:73], v[42:43], v[72:73]
	v_and_b32_e32 v21, 0xffff0000, v12
	v_pk_mul_f32 v[68:69], v[72:73], v[68:69]
	v_lshlrev_b32_e32 v72, 16, v71
	v_mul_f32_e32 v13, 0xbfb8aa3b, v72
	v_exp_f32_e32 v13, v13
	v_and_b32_e32 v73, 0xffff0000, v71
	v_and_b32_e32 v71, 0xffff0000, v19
	v_add_f32_e32 v13, 1.0, v13
	v_rcp_f32_e32 v80, v13
	v_mul_f32_e32 v13, 0xbfb8aa3b, v73
	v_exp_f32_e32 v13, v13
	s_nop 0
	v_add_f32_e32 v13, 1.0, v13
	v_rcp_f32_e32 v81, v13
	s_nop 0
	v_pk_mul_f32 v[72:73], v[80:81], v[72:73]
	v_lshlrev_b32_e32 v80, 16, v67
	v_and_b32_e32 v81, 0xffff0000, v67
; __device__ __forceinline__ float fsigmoid(float v) { return __builtin_amdgcn_rcpf(1.f + __builtin_amdgcn_exp2f(-v * LOG2E)); }
; __device__ __forceinline__ u32x4 pack8(const float (&f)[8]) { u32x4 w; w.x = cvtpk(f[0], f[1]); w.y = cvtpk(f[2], f[3]); w.z = cvtpk(f[4], f[5]); w.w = cvtpk(f[6], f[7]); return w; }
; template <int W, int NI> __device__ __forceinline__ void pool_items(bf16_t* PB, const float* pscale, const int (&rps)[NI], int g, int lane) {
;     ...
;     for (int q = 0; q < NI; ++q) {
;         float za[8], sum[8], x0[8]; unpack8(zw[q], za); unpack8(v[q][0], x0);
; #pragma unroll
;         for (int e = 0; e < 8; ++e) sum[e] = x0[e];
; #pragma unroll
;         for (int jj = 1; jj < W; ++jj) { float f[8]; unpack8(v[q][jj], f); const float mk = (jj <= t[q]) ? 1.f : 0.f;
; #pragma unroll
;             for (int e = 0; e < 8; ++e) sum[e] += mk * f[e]; }
;         const int cnt = (t[q] + 1 < W) ? (t[q] + 1) : W;
;         const float inv = 1.f / (float)cnt;
;         float y[8];
; #pragma unroll
;         for (int e = 0; e < 8; ++e) { const float ps = (e < 4) ? p0[e & 3] : p1[e & 3]; y[e] = (sum[e] * inv - x0[e]) * ps * (za[e] * fsigmoid(za[e])); }
;         outw[q] = pack8(y); }
	v_pk_fma_f32 v[80:81], v[76:77], v[80:81], v[82:83] op_sel_hi:[0,1,1]
	v_pk_fma_f32 v[80:81], v[74:75], v[80:81], v[82:83] op_sel_hi:[0,1,1] neg_lo:[0,0,1] neg_hi:[0,0,1]
	v_pk_mul_f32 v[80:81], v[42:43], v[80:81]
	v_and_b32_e32 v67, 0xffff0000, v62
	v_pk_mul_f32 v[72:73], v[80:81], v[72:73]
	v_lshlrev_b32_e32 v80, 16, v28
	v_mul_f32_e32 v13, 0xbfb8aa3b, v80
	v_exp_f32_e32 v13, v13
	v_and_b32_e32 v81, 0xffff0000, v28
	v_cvt_pk_bf16_f32 v63, v72, v73
	v_add_f32_e32 v13, 1.0, v13
	v_rcp_f32_e32 v28, v13
	v_mul_f32_e32 v13, 0xbfb8aa3b, v81
	v_exp_f32_e32 v13, v13
	s_nop 0
	v_add_f32_e32 v13, 1.0, v13
	v_rcp_f32_e32 v29, v13
	s_nop 0
	v_pk_mul_f32 v[28:29], v[28:29], v[80:81]
	v_lshlrev_b32_e32 v80, 16, v20
	v_and_b32_e32 v81, 0xffff0000, v20
	v_lshlrev_b32_e32 v20, 16, v12
	v_pk_fma_f32 v[12:13], v[58:59], v[80:81], v[20:21] op_sel_hi:[0,1,1]
	v_pk_fma_f32 v[12:13], v[56:57], v[12:13], v[20:21] op_sel_hi:[0,1,1] neg_lo:[0,0,1] neg_hi:[0,0,1]
	v_lshlrev_b32_e32 v20, 16, v70
	v_mul_f32_e32 v14, 0xbfb8aa3b, v20
	v_exp_f32_e32 v14, v14
	v_pk_mul_f32 v[12:13], v[40:41], v[12:13]
	v_and_b32_e32 v21, 0xffff0000, v70
	v_pk_mul_f32 v[12:13], v[12:13], v[28:29]
	v_add_f32_e32 v14, 1.0, v14
	v_rcp_f32_e32 v28, v14
	v_mul_f32_e32 v14, 0xbfb8aa3b, v21
	v_exp_f32_e32 v14, v14
	v_lshlrev_b32_e32 v70, 16, v19
	v_add_f32_e32 v14, 1.0, v14
	v_rcp_f32_e32 v29, v14
	v_cndmask_b32_e64 v14, 0.5, 1.0, s[2:3]
	v_pk_mul_f32 v[20:21], v[28:29], v[20:21]
	v_lshlrev_b32_e32 v28, 16, v66
	v_and_b32_e32 v29, 0xffff0000, v66
	v_lshlrev_b32_e32 v66, 16, v62
	v_pk_fma_f32 v[28:29], v[76:77], v[28:29], v[66:67] op_sel_hi:[0,1,1]
	v_pk_fma_f32 v[28:29], v[74:75], v[28:29], v[66:67] op_sel_hi:[0,1,1] neg_lo:[0,0,1] neg_hi:[0,0,1]
	v_pk_mul_f32 v[28:29], v[40:41], v[28:29]
	s_nop 0
	v_pk_mul_f32 v[20:21], v[28:29], v[20:21]
	v_lshlrev_b32_e32 v28, 16, v35
	v_cvt_pk_bf16_f32 v62, v20, v21
	v_mul_f32_e32 v21, 0xbfb8aa3b, v28
	v_exp_f32_e32 v21, v21
	v_and_b32_e32 v29, 0xffff0000, v35
	v_cndmask_b32_e64 v20, 1.0, 0, s[2:3]
	s_add_i32 s2, s15, s31
	v_add_f32_e32 v21, 1.0, v21
	v_rcp_f32_e32 v66, v21
	v_mul_f32_e32 v21, 0xbfb8aa3b, v29
	v_exp_f32_e32 v21, v21
	s_add_i32 s3, s31, s2
	s_cmpk_gt_i32 s3, 0x1fff
	v_add_f32_e32 v21, 1.0, v21
	v_rcp_f32_e32 v67, v21
	s_nop 0
	v_pk_mul_f32 v[28:29], v[66:67], v[28:29]
	v_lshlrev_b32_e32 v66, 16, v27
	v_and_b32_e32 v67, 0xffff0000, v27
	v_pk_fma_f32 v[66:67], v[20:21], v[66:67], v[70:71] op_sel_hi:[0,1,1]
	v_pk_fma_f32 v[66:67], v[14:15], v[66:67], v[70:71] op_sel_hi:[0,1,1] neg_lo:[0,0,1] neg_hi:[0,0,1]
	v_pk_mul_f32 v[66:67], v[66:67], v[38:39]
	v_and_b32_e32 v27, 0xffff0000, v18
	v_pk_mul_f32 v[28:29], v[28:29], v[66:67]
	v_lshlrev_b32_e32 v66, 16, v34
	v_mul_f32_e32 v19, 0xbfb8aa3b, v66
	v_exp_f32_e32 v19, v19
	v_and_b32_e32 v67, 0xffff0000, v34
	v_add_f32_e32 v19, 1.0, v19
	v_rcp_f32_e32 v34, v19
	v_mul_f32_e32 v19, 0xbfb8aa3b, v67
	v_exp_f32_e32 v19, v19
	s_nop 0
	v_add_f32_e32 v19, 1.0, v19
	v_rcp_f32_e32 v35, v19
	s_nop 0
	v_pk_mul_f32 v[34:35], v[34:35], v[66:67]
	v_lshlrev_b32_e32 v66, 16, v26
	v_and_b32_e32 v67, 0xffff0000, v26
	v_lshlrev_b32_e32 v26, 16, v18
	v_pk_fma_f32 v[18:19], v[20:21], v[66:67], v[26:27] op_sel_hi:[0,1,1]
	v_pk_fma_f32 v[18:19], v[14:15], v[18:19], v[26:27] op_sel_hi:[0,1,1] neg_lo:[0,0,1] neg_hi:[0,0,1]
	v_lshlrev_b32_e32 v26, 16, v33
	v_mul_f32_e32 v21, 0xbfb8aa3b, v26
	v_exp_f32_e32 v21, v21
	v_pk_mul_f32 v[18:19], v[18:19], v[36:37]
	v_and_b32_e32 v27, 0xffff0000, v33
	v_pk_mul_f32 v[18:19], v[34:35], v[18:19]
	v_add_f32_e32 v21, 1.0, v21
	v_rcp_f32_e32 v34, v21
	v_mul_f32_e32 v21, 0xbfb8aa3b, v27
	v_exp_f32_e32 v21, v21
	v_lshlrev_b32_e32 v66, 16, v17
	v_and_b32_e32 v67, 0xffff0000, v17
	v_cvt_pk_bf16_f32 v18, v18, v19
	v_add_f32_e32 v21, 1.0, v21
	v_rcp_f32_e32 v35, v21
	v_cvt_pk_bf16_f32 v19, v28, v29
	v_lshlrev_b32_e32 v28, 16, v3
	v_and_b32_e32 v29, 0xffff0000, v3
	v_pk_mul_f32 v[26:27], v[34:35], v[26:27]
	v_lshlrev_b32_e32 v34, 16, v25
	v_and_b32_e32 v35, 0xffff0000, v25
	v_pk_fma_f32 v[34:35], v[20:21], v[34:35], v[66:67] op_sel_hi:[0,1,1]
	v_pk_fma_f32 v[34:35], v[14:15], v[34:35], v[66:67] op_sel_hi:[0,1,1] neg_lo:[0,0,1] neg_hi:[0,0,1]
	v_pk_mul_f32 v[34:35], v[34:35], v[42:43]
	v_and_b32_e32 v25, 0xffff0000, v16
	v_pk_mul_f32 v[26:27], v[26:27], v[34:35]
	v_lshlrev_b32_e32 v34, 16, v32
	v_mul_f32_e32 v17, 0xbfb8aa3b, v34
	v_exp_f32_e32 v17, v17
	v_and_b32_e32 v35, 0xffff0000, v32
	v_add_f32_e32 v17, 1.0, v17
	v_rcp_f32_e32 v32, v17
	v_mul_f32_e32 v17, 0xbfb8aa3b, v35
	v_exp_f32_e32 v17, v17
	s_nop 0
	v_add_f32_e32 v17, 1.0, v17
	v_rcp_f32_e32 v33, v17
; __device__ __forceinline__ float fsigmoid(float v) { return __builtin_amdgcn_rcpf(1.f + __builtin_amdgcn_exp2f(-v * LOG2E)); }
; __device__ __forceinline__ u32x4 pack8(const float (&f)[8]) { u32x4 w; w.x = cvtpk(f[0], f[1]); w.y = cvtpk(f[2], f[3]); w.z = cvtpk(f[4], f[5]); w.w = cvtpk(f[6], f[7]); return w; }
; template <int W, int NI> __device__ __forceinline__ void pool_items(bf16_t* PB, const float* pscale, const int (&rps)[NI], int g, int lane) {
;     ...
;     for (int q = 0; q < NI; ++q) {
;         float za[8], sum[8], x0[8]; unpack8(zw[q], za); unpack8(v[q][0], x0);
; #pragma unroll
;         for (int e = 0; e < 8; ++e) sum[e] = x0[e];
; #pragma unroll
;         for (int jj = 1; jj < W; ++jj) { float f[8]; unpack8(v[q][jj], f); const float mk = (jj <= t[q]) ? 1.f : 0.f;
; #pragma unroll
;             for (int e = 0; e < 8; ++e) sum[e] += mk * f[e]; }
;         const int cnt = (t[q] + 1 < W) ? (t[q] + 1) : W;
;         const float inv = 1.f / (float)cnt;
;         float y[8];
; #pragma unroll
;         for (int e = 0; e < 8; ++e) { const float ps = (e < 4) ? p0[e & 3] : p1[e & 3]; y[e] = (sum[e] * inv - x0[e]) * ps * (za[e] * fsigmoid(za[e])); }
;         outw[q] = pack8(y); }
; #pragma unroll
;     for (int q = 0; q < NI; ++q) *(u32x4*)zp[q] = outw[q];
	s_nop 0
	v_pk_mul_f32 v[32:33], v[32:33], v[34:35]
	v_lshlrev_b32_e32 v34, 16, v24
	v_and_b32_e32 v35, 0xffff0000, v24
	v_lshlrev_b32_e32 v24, 16, v16
	v_pk_fma_f32 v[16:17], v[20:21], v[34:35], v[24:25] op_sel_hi:[0,1,1]
	v_pk_fma_f32 v[16:17], v[14:15], v[16:17], v[24:25] op_sel_hi:[0,1,1] neg_lo:[0,0,1] neg_hi:[0,0,1]
	v_lshlrev_b32_e32 v24, 16, v11
	v_and_b32_e32 v25, 0xffff0000, v11
	v_mul_f32_e32 v11, 0xbfb8aa3b, v24
	v_exp_f32_e32 v11, v11
	v_pk_mul_f32 v[16:17], v[16:17], v[40:41]
	v_cndmask_b32_e64 v20, 1.0, 0, vcc
	v_pk_mul_f32 v[16:17], v[32:33], v[16:17]
	v_add_f32_e32 v11, 1.0, v11
	v_cvt_pk_bf16_f32 v16, v16, v17
	v_cvt_pk_bf16_f32 v17, v26, v27
	v_rcp_f32_e32 v26, v11
	v_mul_f32_e32 v11, 0xbfb8aa3b, v25
	v_exp_f32_e32 v11, v11
	v_cndmask_b32_e64 v14, 0.5, 1.0, vcc
	v_add_f32_e32 v11, 1.0, v11
	v_rcp_f32_e32 v27, v11
	s_nop 0
	v_pk_mul_f32 v[24:25], v[26:27], v[24:25]
	v_lshlrev_b32_e32 v26, 16, v7
	v_and_b32_e32 v27, 0xffff0000, v7
	v_pk_fma_f32 v[26:27], v[20:21], v[26:27], v[28:29] op_sel_hi:[0,1,1]
	v_pk_fma_f32 v[26:27], v[14:15], v[26:27], v[28:29] op_sel_hi:[0,1,1] neg_lo:[0,0,1] neg_hi:[0,0,1]
	v_pk_mul_f32 v[26:27], v[26:27], v[38:39]
	v_and_b32_e32 v7, 0xffff0000, v2
	v_pk_mul_f32 v[24:25], v[24:25], v[26:27]
	v_lshlrev_b32_e32 v26, 16, v10
	v_mul_f32_e32 v3, 0xbfb8aa3b, v26
	v_exp_f32_e32 v3, v3
	v_and_b32_e32 v27, 0xffff0000, v10
	v_add_f32_e32 v3, 1.0, v3
	v_rcp_f32_e32 v10, v3
	v_mul_f32_e32 v3, 0xbfb8aa3b, v27
	v_exp_f32_e32 v3, v3
	s_nop 0
	v_add_f32_e32 v3, 1.0, v3
	v_rcp_f32_e32 v11, v3
	s_nop 0
	v_pk_mul_f32 v[10:11], v[10:11], v[26:27]
	v_lshlrev_b32_e32 v26, 16, v6
	v_and_b32_e32 v27, 0xffff0000, v6
	v_lshlrev_b32_e32 v6, 16, v2
	v_pk_fma_f32 v[2:3], v[20:21], v[26:27], v[6:7] op_sel_hi:[0,1,1]
	v_pk_fma_f32 v[2:3], v[14:15], v[2:3], v[6:7] op_sel_hi:[0,1,1] neg_lo:[0,0,1] neg_hi:[0,0,1]
	v_lshlrev_b32_e32 v6, 16, v9
	v_and_b32_e32 v7, 0xffff0000, v9
	v_mul_f32_e32 v9, 0xbfb8aa3b, v6
	v_exp_f32_e32 v9, v9
	v_pk_mul_f32 v[2:3], v[2:3], v[36:37]
	v_lshlrev_b32_e32 v26, 16, v1
	v_pk_mul_f32 v[2:3], v[10:11], v[2:3]
	v_add_f32_e32 v9, 1.0, v9
	v_rcp_f32_e32 v10, v9
	v_mul_f32_e32 v9, 0xbfb8aa3b, v7
	v_exp_f32_e32 v9, v9
	v_and_b32_e32 v27, 0xffff0000, v1
	v_cvt_pk_bf16_f32 v2, v2, v3
	v_cvt_pk_bf16_f32 v3, v24, v25
	v_add_f32_e32 v9, 1.0, v9
	v_rcp_f32_e32 v11, v9
	s_nop 0
	v_pk_mul_f32 v[6:7], v[10:11], v[6:7]
	v_lshlrev_b32_e32 v10, 16, v5
	v_and_b32_e32 v11, 0xffff0000, v5
	v_pk_fma_f32 v[10:11], v[20:21], v[10:11], v[26:27] op_sel_hi:[0,1,1]
	v_pk_fma_f32 v[10:11], v[14:15], v[10:11], v[26:27] op_sel_hi:[0,1,1] neg_lo:[0,0,1] neg_hi:[0,0,1]
	v_pk_mul_f32 v[10:11], v[10:11], v[42:43]
	v_and_b32_e32 v5, 0xffff0000, v0
	v_pk_mul_f32 v[6:7], v[6:7], v[10:11]
	v_lshlrev_b32_e32 v10, 16, v8
	v_mul_f32_e32 v1, 0xbfb8aa3b, v10
	v_exp_f32_e32 v1, v1
	v_and_b32_e32 v11, 0xffff0000, v8
	v_add_f32_e32 v1, 1.0, v1
	v_rcp_f32_e32 v8, v1
	v_mul_f32_e32 v1, 0xbfb8aa3b, v11
	v_exp_f32_e32 v1, v1
	s_nop 0
	v_add_f32_e32 v1, 1.0, v1
	v_rcp_f32_e32 v9, v1
	s_nop 0
	v_pk_mul_f32 v[8:9], v[8:9], v[10:11]
	v_lshlrev_b32_e32 v10, 16, v4
	v_and_b32_e32 v11, 0xffff0000, v4
	v_lshlrev_b32_e32 v4, 16, v0
	v_pk_fma_f32 v[0:1], v[20:21], v[10:11], v[4:5] op_sel_hi:[0,1,1]
	v_pk_fma_f32 v[0:1], v[14:15], v[0:1], v[4:5] op_sel_hi:[0,1,1] neg_lo:[0,0,1] neg_hi:[0,0,1]
	v_pk_mul_f32 v[0:1], v[0:1], v[40:41]
	v_lshlrev_b32_e32 v4, 16, v31
	v_pk_mul_f32 v[0:1], v[8:9], v[0:1]
	v_and_b32_e32 v5, 0xffff0000, v31
	v_cvt_pk_bf16_f32 v0, v0, v1
	v_cvt_pk_bf16_f32 v1, v6, v7
	v_mul_f32_e32 v6, 0xbfb8aa3b, v4
	v_mul_f32_e32 v7, 0xbfb8aa3b, v5
	v_exp_f32_e32 v6, v6
	v_exp_f32_e32 v7, v7
	v_lshlrev_b32_e32 v8, 16, v15
	v_and_b32_e32 v9, 0xffff0000, v15
	v_add_f32_e32 v6, 1.0, v6
	v_add_f32_e32 v7, 1.0, v7
	v_rcp_f32_e32 v6, v6
	v_rcp_f32_e32 v7, v7
	v_lshlrev_b32_e32 v10, 16, v23
	v_and_b32_e32 v11, 0xffff0000, v23
	v_pk_fma_f32 v[10:11], v[58:59], v[10:11], v[8:9] op_sel_hi:[0,1,1]
	v_pk_fma_f32 v[8:9], v[56:57], v[10:11], v[8:9] op_sel_hi:[0,1,1] neg_lo:[0,0,1] neg_hi:[0,0,1]
	v_pk_mul_f32 v[8:9], v[38:39], v[8:9]
	v_pk_mul_f32 v[4:5], v[6:7], v[4:5]
	v_add_u32_e32 v57, s91, v57
	v_pk_mul_f32 v[8:9], v[8:9], v[4:5]
	v_cvt_pk_bf16_f32 v4, v12, v13
	v_cvt_pk_bf16_f32 v5, v68, v69
	v_cvt_pk_bf16_f32 v6, v60, v61
	v_cvt_pk_bf16_f32 v7, v8, v9
	global_store_dwordx4 v[48:49], v[0:3], off offset:2048 nt
	global_store_dwordx4 v[50:51], v[16:19], off offset:2048 nt
	global_store_dwordx4 v[52:53], v[62:65], off offset:2048 nt
	global_store_dwordx4 v[54:55], v[4:7], off offset:2048 nt
	s_cbranch_scc0 .LBB0_371

; __device__ __forceinline__ float fsigmoid(float v) { return __builtin_amdgcn_rcpf(1.f + __builtin_amdgcn_exp2f(-v * LOG2E)); }
; __device__ __forceinline__ u32x4 pack8(const float (&f)[8]) { u32x4 w; w.x = cvtpk(f[0], f[1]); w.y = cvtpk(f[2], f[3]); w.z = cvtpk(f[4], f[5]); w.w = cvtpk(f[6], f[7]); return w; }
; template <int W, int NI> __device__ __forceinline__ void pool_items(bf16_t* PB, const float* pscale, const int (&rps)[NI], int g, int lane) {
;     const int ch = g * 256 + (lane & 31) * 8;
;     u32x4 v[NI][W], zw[NI]; int t[NI]; bf16_t* zp[NI];
; #pragma unroll
;     for (int q = 0; q < NI; ++q) { const int row = 2 * rps[q] + (lane >> 5); t[q] = row & (SEQ - 1);
;         const bf16_t* xp = PB + (size_t)row * PBW + C_XA + ch;
; #pragma unroll
;         for (int jj = 0; jj < W; ++jj) { const int back = (jj <= t[q]) ? jj : 0; v[q][jj] = *(const u32x4*)(xp - (size_t)back * PBW); }
;         zp[q] = PB + (size_t)row * PBW + C_ZA + ch; zw[q] = *(const u32x4*)zp[q]; }
;     const f32x4 p0 = *(const f32x4*)(pscale + ch), p1 = *(const f32x4*)(pscale + ch + 4);
;     u32x4 outw[NI];
; #pragma unroll
;     for (int q = 0; q < NI; ++q) {
;         float za[8], sum[8], x0[8]; unpack8(zw[q], za); unpack8(v[q][0], x0);
; #pragma unroll
;         for (int e = 0; e < 8; ++e) sum[e] = x0[e];
; #pragma unroll
;         for (int jj = 1; jj < W; ++jj) { float f[8]; unpack8(v[q][jj], f); const float mk = (jj <= t[q]) ? 1.f : 0.f;
; #pragma unroll
;             for (int e = 0; e < 8; ++e) sum[e] += mk * f[e]; }
;         const int cnt = (t[q] + 1 < W) ? (t[q] + 1) : W;
;         const float inv = 1.f / (float)cnt;
;         float y[8];
; #pragma unroll
;         for (int e = 0; e < 8; ++e) { const float ps = (e < 4) ? p0[e & 3] : p1[e & 3]; y[e] = (sum[e] * inv - x0[e]) * ps * (za[e] * fsigmoid(za[e])); }
;         outw[q] = pack8(y); }
; #pragma unroll
;     for (int q = 0; q < NI; ++q) *(u32x4*)zp[q] = outw[q];
; __device__ __forceinline__ void phase_mixers(PP p, int l, int lane, int wave, LAS unsigned char* lds) {
;     ...
;       for (; rp < MTOK / 2; rp += NGW) { const int r1[1] = {rp}; pool_items<2, 1>(PB, pscale, r1, 0, lane); } }
.LBB0_374:
	v_mad_i64_i32 v[26:27], s[4:5], v4, s65, v[2:3]
	global_load_dwordx4 v[6:9], v[26:27], off offset:2048
	global_load_dwordx4 v[10:13], v[26:27], off
	v_and_b32_e32 v5, 0xfff, v4
	v_cmp_eq_u32_e32 vcc, 0, v5
	s_add_i32 s2, s2, s74
	v_add_u32_e32 v4, s82, v4
	v_cndmask_b32_e64 v15, -1, 0, vcc
	v_cndmask_b32_e64 v14, v225, 0, vcc
	v_lshl_add_u64 v[14:15], v[26:27], 0, v[14:15]
	global_load_dwordx4 v[14:17], v[14:15], off
	s_nop 0
	global_load_dwordx4 v[18:21], v[0:1], off offset:16
	global_load_dwordx4 v[22:25], v[0:1], off
	v_cndmask_b32_e64 v30, 1.0, 0, vcc
	v_cndmask_b32_e64 v28, 0.5, 1.0, vcc
	s_cmpk_gt_i32 s2, 0x1fff
	s_waitcnt vmcnt(4)
	v_lshlrev_b32_e32 v32, 16, v8
	v_mul_f32_e32 v5, 0xbfb8aa3b, v32
	v_exp_f32_e32 v5, v5
	v_and_b32_e32 v33, 0xffff0000, v8
	s_waitcnt vmcnt(3)
	v_lshlrev_b32_e32 v36, 16, v12
	v_and_b32_e32 v37, 0xffff0000, v12
	v_add_f32_e32 v5, 1.0, v5
	v_rcp_f32_e32 v34, v5
	v_mul_f32_e32 v5, 0xbfb8aa3b, v33
	v_exp_f32_e32 v5, v5
	v_lshlrev_b32_e32 v8, 16, v9
	v_and_b32_e32 v9, 0xffff0000, v9
	v_lshlrev_b32_e32 v12, 16, v13
	v_add_f32_e32 v5, 1.0, v5
	v_rcp_f32_e32 v35, v5
	v_and_b32_e32 v13, 0xffff0000, v13
	v_pk_mul_f32 v[32:33], v[34:35], v[32:33]
	s_waitcnt vmcnt(2)
	v_lshlrev_b32_e32 v34, 16, v16
	v_and_b32_e32 v35, 0xffff0000, v16
	v_pk_fma_f32 v[34:35], v[30:31], v[34:35], v[36:37] op_sel_hi:[0,1,1]
	v_pk_fma_f32 v[34:35], v[28:29], v[34:35], v[36:37] op_sel_hi:[0,1,1] neg_lo:[0,0,1] neg_hi:[0,0,1]
	s_waitcnt vmcnt(1)
	v_pk_mul_f32 v[18:19], v[18:19], v[34:35]
	v_lshlrev_b32_e32 v36, 16, v11
	v_pk_mul_f32 v[18:19], v[32:33], v[18:19]
	v_lshlrev_b32_e32 v32, 16, v7
	v_mul_f32_e32 v5, 0xbfb8aa3b, v32
	v_exp_f32_e32 v5, v5
	v_and_b32_e32 v33, 0xffff0000, v7
	v_and_b32_e32 v37, 0xffff0000, v11
	v_add_f32_e32 v5, 1.0, v5
	v_rcp_f32_e32 v34, v5
	v_mul_f32_e32 v5, 0xbfb8aa3b, v33
	v_exp_f32_e32 v5, v5
	s_nop 0
	v_add_f32_e32 v5, 1.0, v5
	v_rcp_f32_e32 v35, v5
	s_nop 0
	v_pk_mul_f32 v[32:33], v[34:35], v[32:33]
	v_lshlrev_b32_e32 v34, 16, v15
	v_and_b32_e32 v35, 0xffff0000, v15
	v_pk_fma_f32 v[34:35], v[30:31], v[34:35], v[36:37] op_sel_hi:[0,1,1]
	v_pk_fma_f32 v[34:35], v[28:29], v[34:35], v[36:37] op_sel_hi:[0,1,1] neg_lo:[0,0,1] neg_hi:[0,0,1]
	s_waitcnt vmcnt(0)
	v_pk_mul_f32 v[24:25], v[24:25], v[34:35]
	v_and_b32_e32 v15, 0xffff0000, v10
	v_pk_mul_f32 v[24:25], v[32:33], v[24:25]
	v_lshlrev_b32_e32 v32, 16, v6
	v_mul_f32_e32 v5, 0xbfb8aa3b, v32
	v_exp_f32_e32 v5, v5
	v_and_b32_e32 v33, 0xffff0000, v6
	v_add_f32_e32 v5, 1.0, v5
	v_rcp_f32_e32 v6, v5
	v_mul_f32_e32 v5, 0xbfb8aa3b, v33
	v_exp_f32_e32 v5, v5
	s_nop 0
	v_add_f32_e32 v5, 1.0, v5
	v_rcp_f32_e32 v7, v5
	v_mul_f32_e32 v5, 0xbfb8aa3b, v8
	v_exp_f32_e32 v5, v5
	v_pk_mul_f32 v[6:7], v[6:7], v[32:33]
	v_lshlrev_b32_e32 v32, 16, v14
	v_and_b32_e32 v33, 0xffff0000, v14
	v_lshlrev_b32_e32 v14, 16, v10
	v_pk_fma_f32 v[10:11], v[30:31], v[32:33], v[14:15] op_sel_hi:[0,1,1]
	v_pk_fma_f32 v[10:11], v[28:29], v[10:11], v[14:15] op_sel_hi:[0,1,1] neg_lo:[0,0,1] neg_hi:[0,0,1]
	v_pk_mul_f32 v[10:11], v[22:23], v[10:11]
	v_add_f32_e32 v5, 1.0, v5
	v_pk_mul_f32 v[6:7], v[6:7], v[10:11]
	v_rcp_f32_e32 v10, v5
	v_mul_f32_e32 v5, 0xbfb8aa3b, v9
	v_exp_f32_e32 v5, v5
	v_lshlrev_b32_e32 v14, 16, v17
	v_and_b32_e32 v15, 0xffff0000, v17
	v_pk_fma_f32 v[14:15], v[30:31], v[14:15], v[12:13] op_sel_hi:[0,1,1]
	v_add_f32_e32 v5, 1.0, v5
	v_rcp_f32_e32 v11, v5
	v_pk_fma_f32 v[12:13], v[28:29], v[14:15], v[12:13] op_sel_hi:[0,1,1] neg_lo:[0,0,1] neg_hi:[0,0,1]
	v_pk_mul_f32 v[12:13], v[20:21], v[12:13]
	v_cvt_pk_bf16_f32 v6, v6, v7
	v_pk_mul_f32 v[8:9], v[10:11], v[8:9]
	v_cvt_pk_bf16_f32 v7, v24, v25
	v_pk_mul_f32 v[10:11], v[8:9], v[12:13]
	v_cvt_pk_bf16_f32 v8, v18, v19
	v_cvt_pk_bf16_f32 v9, v10, v11
	global_store_dwordx4 v[26:27], v[6:9], off offset:2048 nt
	s_cbranch_scc0 .LBB0_374

; template <int W, int NI> __device__ __forceinline__ void pool_items(bf16_t* PB, const float* pscale, const int (&rps)[NI], int g, int lane) {
;     const int ch = g * 256 + (lane & 31) * 8;
;     u32x4 v[NI][W], zw[NI]; int t[NI]; bf16_t* zp[NI];
; #pragma unroll
;     for (int q = 0; q < NI; ++q) { const int row = 2 * rps[q] + (lane >> 5); t[q] = row & (SEQ - 1);
;         const bf16_t* xp = PB + (size_t)row * PBW + C_XA + ch;
; #pragma unroll
;         for (int jj = 0; jj < W; ++jj) { const int back = (jj <= t[q]) ? jj : 0; v[q][jj] = *(const u32x4*)(xp - (size_t)back * PBW); }
;         zp[q] = PB + (size_t)row * PBW + C_ZA + ch; zw[q] = *(const u32x4*)zp[q]; }
;     const f32x4 p0 = *(const f32x4*)(pscale + ch), p1 = *(const f32x4*)(pscale + ch + 4);
; __device__ __forceinline__ void phase_mixers(PP p, int l, int lane, int wave, LAS unsigned char* lds) {
;     ...
;       for (; rp + 3 * NGW < MTOK / 2; rp += 4 * NGW) { const int r4[4] = {rp, rp + NGW, rp + 2 * NGW, rp + 3 * NGW}; pool_items<4, 4>(PB, pscale, r4, 1, lane); }
.LBB0_377:
	v_add_u32_e32 v0, s29, v101
	v_add_u32_e32 v20, s30, v101
	v_add_u32_e32 v40, s28, v101
	v_and_b32_e32 v103, 0xfff, v0
	v_mad_i64_i32 v[92:93], s[2:3], v0, s65, v[90:91]
	v_and_b32_e32 v105, 0xfff, v20
	v_mad_i64_i32 v[94:95], s[8:9], v20, s65, v[90:91]
	v_and_b32_e32 v100, 0xfff, v40
	v_mad_i64_i32 v[96:97], s[14:15], v40, s65, v[90:91]
	v_cmp_eq_u32_e64 s[2:3], 0, v103
	v_cmp_gt_u32_e64 s[4:5], 2, v103
	v_cmp_gt_u32_e64 s[6:7], 3, v103
	v_cmp_eq_u32_e64 s[8:9], 0, v105
	v_cmp_gt_u32_e64 s[10:11], 2, v105
	v_cmp_gt_u32_e64 s[12:13], 3, v105
	v_cmp_eq_u32_e64 s[14:15], 0, v100
	v_cndmask_b32_e64 v5, -1, 0, s[2:3]
	v_cndmask_b32_e64 v4, v225, 0, s[2:3]
	v_cndmask_b32_e64 v9, -1, 0, s[4:5]
	v_cndmask_b32_e64 v8, v227, 0, s[4:5]
	v_cndmask_b32_e64 v13, -1, 0, s[6:7]
	v_cndmask_b32_e64 v12, v229, 0, s[6:7]
	v_cndmask_b32_e64 v25, -1, 0, s[8:9]
	v_cndmask_b32_e64 v24, v225, 0, s[8:9]
	v_cndmask_b32_e64 v29, -1, 0, s[10:11]
	v_cndmask_b32_e64 v28, v227, 0, s[10:11]
	v_cndmask_b32_e64 v33, -1, 0, s[12:13]
	v_cndmask_b32_e64 v32, v229, 0, s[12:13]
	v_cndmask_b32_e64 v41, -1, 0, s[14:15]
	v_cndmask_b32_e64 v40, v225, 0, s[14:15]
	v_lshl_add_u64 v[4:5], v[92:93], 0, v[4:5]
	v_lshl_add_u64 v[8:9], v[92:93], 0, v[8:9]
	v_lshl_add_u64 v[12:13], v[92:93], 0, v[12:13]
	v_lshl_add_u64 v[24:25], v[94:95], 0, v[24:25]
	v_lshl_add_u64 v[28:29], v[94:95], 0, v[28:29]
	v_lshl_add_u64 v[32:33], v[94:95], 0, v[32:33]
	v_lshl_add_u64 v[40:41], v[96:97], 0, v[40:41]
	v_cmp_gt_u32_e64 s[16:17], 2, v100
	global_load_dwordx4 v[0:3], v[92:93], off offset:512
	v_cmp_gt_u32_e64 s[18:19], 3, v100
	global_load_dwordx4 v[4:7], v[4:5], off offset:512
	v_add_u32_e32 v100, 1, v100
	global_load_dwordx4 v[8:11], v[8:9], off offset:512
	s_nop 0
	global_load_dwordx4 v[12:15], v[12:13], off offset:512
	s_nop 0
	global_load_dwordx4 v[16:19], v[92:93], off offset:2560
	global_load_dwordx4 v[20:23], v[94:95], off offset:512
	v_cvt_f32_u32_e32 v100, v100
	global_load_dwordx4 v[24:27], v[24:25], off offset:512
	v_cndmask_b32_e64 v112, 1.0, 0, s[14:15]
	global_load_dwordx4 v[28:31], v[28:29], off offset:512
	s_nop 0
	global_load_dwordx4 v[32:35], v[32:33], off offset:512
	s_nop 0
	global_load_dwordx4 v[36:39], v[94:95], off offset:2560
	global_load_dwordx4 v[68:71], v[96:97], off offset:512
	global_load_dwordx4 v[72:75], v[40:41], off offset:512
	v_cndmask_b32_e64 v41, -1, 0, s[16:17]
	v_cndmask_b32_e64 v40, v227, 0, s[16:17]
	v_lshl_add_u64 v[40:41], v[96:97], 0, v[40:41]
	global_load_dwordx4 v[76:79], v[40:41], off offset:512
	v_cndmask_b32_e64 v41, -1, 0, s[18:19]
	v_cndmask_b32_e64 v40, v229, 0, s[18:19]
	v_lshl_add_u64 v[40:41], v[96:97], 0, v[40:41]
	global_load_dwordx4 v[80:83], v[40:41], off offset:512
	global_load_dwordx4 v[84:87], v[96:97], off offset:2560
	v_add_u32_e32 v40, s27, v101
	v_and_b32_e32 v102, 0xfff, v40
	v_mad_i64_i32 v[98:99], s[20:21], v40, s65, v[90:91]
	v_cmp_eq_u32_e64 s[20:21], 0, v102
	v_cmp_gt_u32_e64 s[22:23], 2, v102
	v_cmp_gt_u32_e64 s[24:25], 3, v102
	v_cndmask_b32_e64 v45, -1, 0, s[20:21]
	v_cndmask_b32_e64 v44, v225, 0, s[20:21]
	v_cndmask_b32_e64 v49, -1, 0, s[22:23]
	v_cndmask_b32_e64 v48, v227, 0, s[22:23]
	v_cndmask_b32_e64 v53, -1, 0, s[24:25]
	v_cndmask_b32_e64 v52, v229, 0, s[24:25]
	v_lshl_add_u64 v[44:45], v[98:99], 0, v[44:45]
	v_lshl_add_u64 v[48:49], v[98:99], 0, v[48:49]
	v_lshl_add_u64 v[52:53], v[98:99], 0, v[52:53]
	global_load_dwordx4 v[40:43], v[98:99], off offset:512
	v_div_scale_f32 v104, s[34:35], v100, v100, 1.0
	global_load_dwordx4 v[44:47], v[44:45], off offset:512
	v_rcp_f32_e32 v106, v104
	global_load_dwordx4 v[48:51], v[48:49], off offset:512
	s_nop 0
	global_load_dwordx4 v[52:55], v[52:53], off offset:512
	s_nop 0
	global_load_dwordx4 v[56:59], v[98:99], off offset:2560
	global_load_dwordx4 v[64:67], v[88:89], off offset:1024
	global_load_dwordx4 v[60:63], v[88:89], off offset:1040
	v_cndmask_b32_e64 v114, 1.0, 0, s[16:17]
	v_fma_f32 v107, -v104, v106, 1.0
	v_fmac_f32_e32 v106, v107, v106
	v_div_scale_f32 v107, vcc, 1.0, v100, 1.0
	v_mul_f32_e32 v108, v107, v106
	v_fma_f32 v109, -v104, v108, v107
	v_fmac_f32_e32 v108, v109, v106
	v_fma_f32 v104, -v104, v108, v107
	v_div_fmas_f32 v104, v104, v106, v108
	v_div_fixup_f32 v100, v104, v100, 1.0
	v_cndmask_b32_e64 v116, 1.0, 0, s[18:19]
	v_cndmask_b32_e64 v110, v250, v100, s[18:19]
	v_cndmask_b32_e64 v104, 1.0, 0, s[22:23]
	s_add_i32 s26, s26, s87
	s_waitcnt vmcnt(11)
	v_lshlrev_b32_e32 v118, 16, v71
	v_and_b32_e32 v119, 0xffff0000, v71
	v_add_u32_e32 v71, 1, v102
	v_cvt_f32_u32_e32 v71, v71
	v_cndmask_b32_e64 v102, 1.0, 0, s[24:25]
	s_waitcnt vmcnt(9)
	v_lshlrev_b32_e32 v120, 16, v79
	v_and_b32_e32 v121, 0xffff0000, v79
	s_waitcnt vmcnt(7)
	v_lshlrev_b32_e32 v106, 16, v87
	v_and_b32_e32 v107, 0xffff0000, v87
	v_mul_f32_e32 v87, 0xbfb8aa3b, v106
	v_exp_f32_e32 v87, v87
	s_waitcnt vmcnt(6)
	v_lshlrev_b32_e32 v122, 16, v42
	v_add_f32_e32 v87, 1.0, v87
	v_rcp_f32_e32 v108, v87
	v_mul_f32_e32 v87, 0xbfb8aa3b, v107
	v_exp_f32_e32 v87, v87
	v_and_b32_e32 v123, 0xffff0000, v42
	s_waitcnt vmcnt(4)
	v_lshlrev_b32_e32 v124, 16, v50
	v_and_b32_e32 v125, 0xffff0000, v50
	v_add_f32_e32 v87, 1.0, v87
	v_rcp_f32_e32 v109, v87
	s_nop 0
	v_pk_mul_f32 v[106:107], v[108:109], v[106:107]
	v_lshlrev_b32_e32 v108, 16, v75
	v_and_b32_e32 v109, 0xffff0000, v75
	v_pk_fma_f32 v[108:109], v[112:113], v[108:109], v[118:119] op_sel_hi:[0,1,1]
	v_pk_fma_f32 v[108:109], v[114:115], v[120:121], v[108:109] op_sel_hi:[0,1,1]
	v_lshlrev_b32_e32 v120, 16, v83
	v_and_b32_e32 v121, 0xffff0000, v83
	v_pk_fma_f32 v[108:109], v[116:117], v[120:121], v[108:109] op_sel_hi:[0,1,1]
	v_pk_fma_f32 v[108:109], v[110:111], v[108:109], v[118:119] op_sel_hi:[0,1,1] neg_lo:[0,0,1] neg_hi:[0,0,1]
	s_waitcnt vmcnt(0)
; __device__ __forceinline__ float fsigmoid(float v) { return __builtin_amdgcn_rcpf(1.f + __builtin_amdgcn_exp2f(-v * LOG2E)); }
; __device__ __forceinline__ u32x4 pack8(const float (&f)[8]) { u32x4 w; w.x = cvtpk(f[0], f[1]); w.y = cvtpk(f[2], f[3]); w.z = cvtpk(f[4], f[5]); w.w = cvtpk(f[6], f[7]); return w; }
; template <int W, int NI> __device__ __forceinline__ void pool_items(bf16_t* PB, const float* pscale, const int (&rps)[NI], int g, int lane) {
;     ...
; #pragma unroll
;     for (int q = 0; q < NI; ++q) {
;         float za[8], sum[8], x0[8]; unpack8(zw[q], za); unpack8(v[q][0], x0);
; #pragma unroll
;         for (int e = 0; e < 8; ++e) sum[e] = x0[e];
; #pragma unroll
;         for (int jj = 1; jj < W; ++jj) { float f[8]; unpack8(v[q][jj], f); const float mk = (jj <= t[q]) ? 1.f : 0.f;
; #pragma unroll
;             for (int e = 0; e < 8; ++e) sum[e] += mk * f[e]; }
;         const int cnt = (t[q] + 1 < W) ? (t[q] + 1) : W;
;         const float inv = 1.f / (float)cnt;
;         float y[8];
; #pragma unroll
;         for (int e = 0; e < 8; ++e) { const float ps = (e < 4) ? p0[e & 3] : p1[e & 3]; y[e] = (sum[e] * inv - x0[e]) * ps * (za[e] * fsigmoid(za[e])); }
;         outw[q] = pack8(y); }
	v_pk_mul_f32 v[108:109], v[108:109], v[62:63]
	v_div_scale_f32 v75, s[14:15], v71, v71, 1.0
	v_pk_mul_f32 v[118:119], v[106:107], v[108:109]
	v_lshlrev_b32_e32 v108, 16, v58
	v_and_b32_e32 v109, 0xffff0000, v58
	v_mul_f32_e32 v58, 0xbfb8aa3b, v108
	v_exp_f32_e32 v58, v58
	v_rcp_f32_e32 v79, v75
	v_cndmask_b32_e64 v106, 1.0, 0, s[20:21]
	v_add_f32_e32 v58, 1.0, v58
	v_rcp_f32_e32 v120, v58
	v_mul_f32_e32 v58, 0xbfb8aa3b, v109
	v_exp_f32_e32 v58, v58
	v_fma_f32 v83, -v75, v79, 1.0
	v_fmac_f32_e32 v79, v83, v79
	v_div_scale_f32 v83, vcc, 1.0, v71, 1.0
	v_add_f32_e32 v58, 1.0, v58
	v_rcp_f32_e32 v121, v58
	v_mul_f32_e32 v87, v83, v79
	v_fma_f32 v100, -v75, v87, v83
	v_fmac_f32_e32 v87, v100, v79
	v_fma_f32 v75, -v75, v87, v83
	v_pk_mul_f32 v[108:109], v[120:121], v[108:109]
	v_lshlrev_b32_e32 v120, 16, v46
	v_and_b32_e32 v121, 0xffff0000, v46
	v_div_fmas_f32 v75, v75, v79, v87
	v_pk_fma_f32 v[120:121], v[106:107], v[120:121], v[122:123] op_sel_hi:[0,1,1]
	v_div_fixup_f32 v71, v75, v71, 1.0
	v_pk_fma_f32 v[120:121], v[104:105], v[124:125], v[120:121] op_sel_hi:[0,1,1]
	v_lshlrev_b32_e32 v124, 16, v54
	v_and_b32_e32 v125, 0xffff0000, v54
	v_cndmask_b32_e64 v100, v250, v71, s[24:25]
	v_pk_fma_f32 v[120:121], v[102:103], v[124:125], v[120:121] op_sel_hi:[0,1,1]
	v_pk_fma_f32 v[120:121], v[100:101], v[120:121], v[122:123] op_sel_hi:[0,1,1] neg_lo:[0,0,1] neg_hi:[0,0,1]
	v_pk_mul_f32 v[120:121], v[60:61], v[120:121]
	v_and_b32_e32 v75, 0xffff0000, v70
	v_pk_mul_f32 v[108:109], v[120:121], v[108:109]
	v_lshlrev_b32_e32 v120, 16, v86
	v_mul_f32_e32 v42, 0xbfb8aa3b, v120
	v_exp_f32_e32 v42, v42
	v_and_b32_e32 v121, 0xffff0000, v86
	v_and_b32_e32 v79, 0xffff0000, v82
	v_and_b32_e32 v83, 0xffff0000, v41
	v_add_f32_e32 v42, 1.0, v42
	v_rcp_f32_e32 v86, v42
	v_mul_f32_e32 v42, 0xbfb8aa3b, v121
	v_exp_f32_e32 v42, v42
	s_nop 0
	v_add_f32_e32 v42, 1.0, v42
	v_rcp_f32_e32 v87, v42
	s_nop 0
	v_pk_mul_f32 v[86:87], v[86:87], v[120:121]
	v_lshlrev_b32_e32 v120, 16, v74
	v_and_b32_e32 v121, 0xffff0000, v74
	v_lshlrev_b32_e32 v74, 16, v70
	v_pk_fma_f32 v[70:71], v[112:113], v[120:121], v[74:75] op_sel_hi:[0,1,1]
	v_lshlrev_b32_e32 v120, 16, v78
	v_and_b32_e32 v121, 0xffff0000, v78
	v_pk_fma_f32 v[70:71], v[114:115], v[120:121], v[70:71] op_sel_hi:[0,1,1]
	v_lshlrev_b32_e32 v78, 16, v82
	v_pk_fma_f32 v[70:71], v[116:117], v[78:79], v[70:71] op_sel_hi:[0,1,1]
	v_pk_fma_f32 v[70:71], v[110:111], v[70:71], v[74:75] op_sel_hi:[0,1,1] neg_lo:[0,0,1] neg_hi:[0,0,1]
	v_lshlrev_b32_e32 v74, 16, v57
	v_mul_f32_e32 v42, 0xbfb8aa3b, v74
	v_exp_f32_e32 v42, v42
	v_and_b32_e32 v75, 0xffff0000, v57
	v_pk_mul_f32 v[70:71], v[70:71], v[60:61]
	v_lshlrev_b32_e32 v82, 16, v41
	v_add_f32_e32 v42, 1.0, v42
	v_rcp_f32_e32 v78, v42
	v_mul_f32_e32 v42, 0xbfb8aa3b, v75
	v_exp_f32_e32 v42, v42
	v_pk_mul_f32 v[70:71], v[86:87], v[70:71]
	v_lshlrev_b32_e32 v86, 16, v49
	v_and_b32_e32 v87, 0xffff0000, v49
	v_add_f32_e32 v42, 1.0, v42
	v_rcp_f32_e32 v79, v42
	v_lshlrev_b32_e32 v120, 16, v77
	v_and_b32_e32 v121, 0xffff0000, v77
	v_and_b32_e32 v49, 0xffff0000, v52
	v_pk_mul_f32 v[74:75], v[78:79], v[74:75]
	v_lshlrev_b32_e32 v78, 16, v45
	v_and_b32_e32 v79, 0xffff0000, v45
	v_pk_fma_f32 v[78:79], v[106:107], v[78:79], v[82:83] op_sel_hi:[0,1,1]
	v_pk_fma_f32 v[78:79], v[104:105], v[86:87], v[78:79] op_sel_hi:[0,1,1]
	v_lshlrev_b32_e32 v86, 16, v53
	v_and_b32_e32 v87, 0xffff0000, v53
	v_pk_fma_f32 v[78:79], v[102:103], v[86:87], v[78:79] op_sel_hi:[0,1,1]
	v_pk_fma_f32 v[78:79], v[100:101], v[78:79], v[82:83] op_sel_hi:[0,1,1] neg_lo:[0,0,1] neg_hi:[0,0,1]
	v_pk_mul_f32 v[78:79], v[66:67], v[78:79]
	v_lshlrev_b32_e32 v86, 16, v69
	v_pk_mul_f32 v[74:75], v[78:79], v[74:75]
	v_lshlrev_b32_e32 v78, 16, v85
	v_mul_f32_e32 v41, 0xbfb8aa3b, v78
	v_exp_f32_e32 v41, v41
	v_and_b32_e32 v79, 0xffff0000, v85
	v_and_b32_e32 v87, 0xffff0000, v69
	v_and_b32_e32 v45, 0xffff0000, v40
	v_add_f32_e32 v41, 1.0, v41
	v_rcp_f32_e32 v82, v41
	v_mul_f32_e32 v41, 0xbfb8aa3b, v79
	v_exp_f32_e32 v41, v41
	v_and_b32_e32 v53, 0xffff0000, v68
	v_and_b32_e32 v77, 0xffff0000, v31
	v_cvt_pk_bf16_f32 v70, v70, v71
	v_add_f32_e32 v41, 1.0, v41
	v_rcp_f32_e32 v83, v41
	v_cvt_pk_bf16_f32 v71, v118, v119
	v_pk_mul_f32 v[78:79], v[82:83], v[78:79]
	v_lshlrev_b32_e32 v82, 16, v73
	v_and_b32_e32 v83, 0xffff0000, v73
	v_pk_fma_f32 v[82:83], v[112:113], v[82:83], v[86:87] op_sel_hi:[0,1,1]
	v_pk_fma_f32 v[82:83], v[114:115], v[120:121], v[82:83] op_sel_hi:[0,1,1]
	v_lshlrev_b32_e32 v120, 16, v81
	v_and_b32_e32 v121, 0xffff0000, v81
	v_pk_fma_f32 v[82:83], v[116:117], v[120:121], v[82:83] op_sel_hi:[0,1,1]
	v_pk_fma_f32 v[82:83], v[110:111], v[82:83], v[86:87] op_sel_hi:[0,1,1] neg_lo:[0,0,1] neg_hi:[0,0,1]
	v_pk_mul_f32 v[82:83], v[82:83], v[66:67]
	v_and_b32_e32 v73, 0xffff0000, v23
	v_pk_mul_f32 v[78:79], v[78:79], v[82:83]
	v_lshlrev_b32_e32 v82, 16, v56
	v_mul_f32_e32 v41, 0xbfb8aa3b, v82
	v_exp_f32_e32 v41, v41
	v_and_b32_e32 v83, 0xffff0000, v56
	v_cvt_pk_bf16_f32 v69, v78, v79
	v_add_f32_e32 v41, 1.0, v41
	v_rcp_f32_e32 v56, v41
	v_mul_f32_e32 v41, 0xbfb8aa3b, v83
	v_exp_f32_e32 v41, v41
	s_nop 0
	v_add_f32_e32 v41, 1.0, v41
	v_rcp_f32_e32 v57, v41
	s_nop 0
	v_pk_mul_f32 v[56:57], v[56:57], v[82:83]
	v_lshlrev_b32_e32 v82, 16, v44
	v_and_b32_e32 v83, 0xffff0000, v44
	v_lshlrev_b32_e32 v44, 16, v40
	v_pk_fma_f32 v[40:41], v[106:107], v[82:83], v[44:45] op_sel_hi:[0,1,1]
	v_lshlrev_b32_e32 v82, 16, v48
	v_and_b32_e32 v83, 0xffff0000, v48
	v_pk_fma_f32 v[40:41], v[104:105], v[82:83], v[40:41] op_sel_hi:[0,1,1]
	v_lshlrev_b32_e32 v48, 16, v52
	v_pk_fma_f32 v[40:41], v[102:103], v[48:49], v[40:41] op_sel_hi:[0,1,1]
; __device__ __forceinline__ float fsigmoid(float v) { return __builtin_amdgcn_rcpf(1.f + __builtin_amdgcn_exp2f(-v * LOG2E)); }
; __device__ __forceinline__ u32x4 pack8(const float (&f)[8]) { u32x4 w; w.x = cvtpk(f[0], f[1]); w.y = cvtpk(f[2], f[3]); w.z = cvtpk(f[4], f[5]); w.w = cvtpk(f[6], f[7]); return w; }
; template <int W, int NI> __device__ __forceinline__ void pool_items(bf16_t* PB, const float* pscale, const int (&rps)[NI], int g, int lane) {
;     ...
; #pragma unroll
;     for (int q = 0; q < NI; ++q) {
;         float za[8], sum[8], x0[8]; unpack8(zw[q], za); unpack8(v[q][0], x0);
; #pragma unroll
;         for (int e = 0; e < 8; ++e) sum[e] = x0[e];
; #pragma unroll
;         for (int jj = 1; jj < W; ++jj) { float f[8]; unpack8(v[q][jj], f); const float mk = (jj <= t[q]) ? 1.f : 0.f;
; #pragma unroll
;             for (int e = 0; e < 8; ++e) sum[e] += mk * f[e]; }
;         const int cnt = (t[q] + 1 < W) ? (t[q] + 1) : W;
;         const float inv = 1.f / (float)cnt;
;         float y[8];
; #pragma unroll
;         for (int e = 0; e < 8; ++e) { const float ps = (e < 4) ? p0[e & 3] : p1[e & 3]; y[e] = (sum[e] * inv - x0[e]) * ps * (za[e] * fsigmoid(za[e])); }
;         outw[q] = pack8(y); }
	v_pk_fma_f32 v[40:41], v[100:101], v[40:41], v[44:45] op_sel_hi:[0,1,1] neg_lo:[0,0,1] neg_hi:[0,0,1]
	v_lshlrev_b32_e32 v44, 16, v84
	v_mul_f32_e32 v42, 0xbfb8aa3b, v44
	v_exp_f32_e32 v42, v42
	v_and_b32_e32 v45, 0xffff0000, v84
	v_pk_mul_f32 v[40:41], v[64:65], v[40:41]
	v_lshlrev_b32_e32 v52, 16, v68
	v_add_f32_e32 v42, 1.0, v42
	v_rcp_f32_e32 v48, v42
	v_mul_f32_e32 v42, 0xbfb8aa3b, v45
	v_exp_f32_e32 v42, v42
	v_pk_mul_f32 v[40:41], v[40:41], v[56:57]
	v_lshlrev_b32_e32 v56, 16, v76
	v_and_b32_e32 v57, 0xffff0000, v76
	v_add_f32_e32 v42, 1.0, v42
	v_rcp_f32_e32 v49, v42
	v_add_u32_e32 v42, 1, v105
	v_cvt_f32_u32_e32 v42, v42
	v_lshlrev_b32_e32 v76, 16, v31
	v_pk_mul_f32 v[44:45], v[48:49], v[44:45]
	v_lshlrev_b32_e32 v48, 16, v72
	v_and_b32_e32 v49, 0xffff0000, v72
	v_pk_fma_f32 v[48:49], v[112:113], v[48:49], v[52:53] op_sel_hi:[0,1,1]
	v_pk_fma_f32 v[48:49], v[114:115], v[56:57], v[48:49] op_sel_hi:[0,1,1]
	v_lshlrev_b32_e32 v56, 16, v80
	v_and_b32_e32 v57, 0xffff0000, v80
	v_pk_fma_f32 v[48:49], v[116:117], v[56:57], v[48:49] op_sel_hi:[0,1,1]
	v_pk_fma_f32 v[48:49], v[110:111], v[48:49], v[52:53] op_sel_hi:[0,1,1] neg_lo:[0,0,1] neg_hi:[0,0,1]
	v_lshlrev_b32_e32 v52, 16, v39
	v_and_b32_e32 v53, 0xffff0000, v39
	v_mul_f32_e32 v39, 0xbfb8aa3b, v52
	v_exp_f32_e32 v39, v39
	v_pk_mul_f32 v[48:49], v[48:49], v[64:65]
	v_lshlrev_b32_e32 v72, 16, v23
	v_pk_mul_f32 v[44:45], v[44:45], v[48:49]
	v_add_f32_e32 v39, 1.0, v39
	v_cvt_pk_bf16_f32 v68, v44, v45
	v_div_scale_f32 v44, s[14:15], v42, v42, 1.0
	v_rcp_f32_e32 v45, v44
	v_rcp_f32_e32 v56, v39
	v_mul_f32_e32 v39, 0xbfb8aa3b, v53
	v_exp_f32_e32 v39, v39
	v_fma_f32 v46, -v44, v45, 1.0
	v_fmac_f32_e32 v45, v46, v45
	v_div_scale_f32 v46, vcc, 1.0, v42, 1.0
	v_mul_f32_e32 v48, v46, v45
	v_add_f32_e32 v39, 1.0, v39
	v_fma_f32 v49, -v44, v48, v46
	v_rcp_f32_e32 v57, v39
	v_fmac_f32_e32 v48, v49, v45
	v_fma_f32 v44, -v44, v48, v46
	v_div_fmas_f32 v44, v44, v45, v48
	v_div_fixup_f32 v42, v44, v42, 1.0
	v_cndmask_b32_e64 v44, 1.0, 0, s[8:9]
	v_pk_mul_f32 v[52:53], v[56:57], v[52:53]
	v_lshlrev_b32_e32 v56, 16, v27
	v_and_b32_e32 v57, 0xffff0000, v27
	v_cndmask_b32_e64 v46, 1.0, 0, s[10:11]
	v_pk_fma_f32 v[56:57], v[44:45], v[56:57], v[72:73] op_sel_hi:[0,1,1]
	v_cndmask_b32_e64 v48, 1.0, 0, s[12:13]
	v_pk_fma_f32 v[56:57], v[46:47], v[76:77], v[56:57] op_sel_hi:[0,1,1]
	v_lshlrev_b32_e32 v76, 16, v35
	v_and_b32_e32 v77, 0xffff0000, v35
	v_cndmask_b32_e64 v42, v250, v42, s[12:13]
	v_pk_fma_f32 v[56:57], v[48:49], v[76:77], v[56:57] op_sel_hi:[0,1,1]
	v_pk_fma_f32 v[56:57], v[42:43], v[56:57], v[72:73] op_sel_hi:[0,1,1] neg_lo:[0,0,1] neg_hi:[0,0,1]
	v_pk_mul_f32 v[56:57], v[56:57], v[62:63]
	v_and_b32_e32 v27, 0xffff0000, v22
	v_pk_mul_f32 v[52:53], v[52:53], v[56:57]
	v_lshlrev_b32_e32 v56, 16, v38
	v_mul_f32_e32 v23, 0xbfb8aa3b, v56
	v_exp_f32_e32 v23, v23
	v_and_b32_e32 v57, 0xffff0000, v38
	v_and_b32_e32 v31, 0xffff0000, v34
	v_and_b32_e32 v35, 0xffff0000, v21
	v_add_f32_e32 v23, 1.0, v23
	v_rcp_f32_e32 v38, v23
	v_mul_f32_e32 v23, 0xbfb8aa3b, v57
	v_exp_f32_e32 v23, v23
	s_nop 0
	v_add_f32_e32 v23, 1.0, v23
	v_rcp_f32_e32 v39, v23
	s_nop 0
	v_pk_mul_f32 v[38:39], v[38:39], v[56:57]
	v_lshlrev_b32_e32 v56, 16, v26
	v_and_b32_e32 v57, 0xffff0000, v26
	v_lshlrev_b32_e32 v26, 16, v22
	v_pk_fma_f32 v[22:23], v[44:45], v[56:57], v[26:27] op_sel_hi:[0,1,1]
	v_lshlrev_b32_e32 v56, 16, v30
	v_and_b32_e32 v57, 0xffff0000, v30
	v_pk_fma_f32 v[22:23], v[46:47], v[56:57], v[22:23] op_sel_hi:[0,1,1]
	v_lshlrev_b32_e32 v30, 16, v34
	v_pk_fma_f32 v[22:23], v[48:49], v[30:31], v[22:23] op_sel_hi:[0,1,1]
	v_pk_fma_f32 v[22:23], v[42:43], v[22:23], v[26:27] op_sel_hi:[0,1,1] neg_lo:[0,0,1] neg_hi:[0,0,1]
	v_lshlrev_b32_e32 v26, 16, v37
	v_and_b32_e32 v27, 0xffff0000, v37
	v_mul_f32_e32 v30, 0xbfb8aa3b, v26
	v_mul_f32_e32 v31, 0xbfb8aa3b, v27
	v_exp_f32_e32 v30, v30
	v_exp_f32_e32 v31, v31
	v_pk_mul_f32 v[22:23], v[22:23], v[60:61]
	v_lshlrev_b32_e32 v34, 16, v21
	v_add_f32_e32 v30, 1.0, v30
	v_add_f32_e32 v31, 1.0, v31
	v_rcp_f32_e32 v30, v30
	v_rcp_f32_e32 v31, v31
	v_pk_mul_f32 v[22:23], v[38:39], v[22:23]
	v_lshlrev_b32_e32 v38, 16, v29
	v_and_b32_e32 v39, 0xffff0000, v29
	v_pk_mul_f32 v[26:27], v[30:31], v[26:27]
	v_lshlrev_b32_e32 v30, 16, v25
	v_and_b32_e32 v31, 0xffff0000, v25
	v_pk_fma_f32 v[30:31], v[44:45], v[30:31], v[34:35] op_sel_hi:[0,1,1]
	v_pk_fma_f32 v[30:31], v[46:47], v[38:39], v[30:31] op_sel_hi:[0,1,1]
	v_lshlrev_b32_e32 v38, 16, v33
	v_and_b32_e32 v39, 0xffff0000, v33
	v_pk_fma_f32 v[30:31], v[48:49], v[38:39], v[30:31] op_sel_hi:[0,1,1]
	v_pk_fma_f32 v[30:31], v[42:43], v[30:31], v[34:35] op_sel_hi:[0,1,1] neg_lo:[0,0,1] neg_hi:[0,0,1]
	v_pk_mul_f32 v[30:31], v[30:31], v[66:67]
	v_and_b32_e32 v25, 0xffff0000, v20
	v_pk_mul_f32 v[26:27], v[26:27], v[30:31]
	v_lshlrev_b32_e32 v30, 16, v36
	v_mul_f32_e32 v21, 0xbfb8aa3b, v30
	v_exp_f32_e32 v21, v21
	v_and_b32_e32 v31, 0xffff0000, v36
	v_and_b32_e32 v29, 0xffff0000, v32
	v_and_b32_e32 v33, 0xffff0000, v19
	v_add_f32_e32 v21, 1.0, v21
	v_rcp_f32_e32 v34, v21
	v_mul_f32_e32 v21, 0xbfb8aa3b, v31
	v_exp_f32_e32 v21, v21
	v_lshlrev_b32_e32 v36, 16, v3
	v_and_b32_e32 v37, 0xffff0000, v3
	v_lshlrev_b32_e32 v38, 16, v11
	v_add_f32_e32 v21, 1.0, v21
	v_rcp_f32_e32 v35, v21
	v_and_b32_e32 v39, 0xffff0000, v11
	v_and_b32_e32 v11, 0xffff0000, v14
	v_cvt_pk_bf16_f32 v22, v22, v23
	v_pk_mul_f32 v[30:31], v[34:35], v[30:31]
	v_lshlrev_b32_e32 v34, 16, v24
	v_and_b32_e32 v35, 0xffff0000, v24
	v_lshlrev_b32_e32 v24, 16, v20
	v_pk_fma_f32 v[20:21], v[44:45], v[34:35], v[24:25] op_sel_hi:[0,1,1]
	v_lshlrev_b32_e32 v34, 16, v28
	v_and_b32_e32 v35, 0xffff0000, v28
; __device__ __forceinline__ float fsigmoid(float v) { return __builtin_amdgcn_rcpf(1.f + __builtin_amdgcn_exp2f(-v * LOG2E)); }
; __device__ __forceinline__ u32x4 pack8(const float (&f)[8]) { u32x4 w; w.x = cvtpk(f[0], f[1]); w.y = cvtpk(f[2], f[3]); w.z = cvtpk(f[4], f[5]); w.w = cvtpk(f[6], f[7]); return w; }
; template <int W, int NI> __device__ __forceinline__ void pool_items(bf16_t* PB, const float* pscale, const int (&rps)[NI], int g, int lane) {
;     ...
; #pragma unroll
;     for (int q = 0; q < NI; ++q) {
;         float za[8], sum[8], x0[8]; unpack8(zw[q], za); unpack8(v[q][0], x0);
; #pragma unroll
;         for (int e = 0; e < 8; ++e) sum[e] = x0[e];
; #pragma unroll
;         for (int jj = 1; jj < W; ++jj) { float f[8]; unpack8(v[q][jj], f); const float mk = (jj <= t[q]) ? 1.f : 0.f;
; #pragma unroll
;             for (int e = 0; e < 8; ++e) sum[e] += mk * f[e]; }
;         const int cnt = (t[q] + 1 < W) ? (t[q] + 1) : W;
;         const float inv = 1.f / (float)cnt;
;         float y[8];
; #pragma unroll
;         for (int e = 0; e < 8; ++e) { const float ps = (e < 4) ? p0[e & 3] : p1[e & 3]; y[e] = (sum[e] * inv - x0[e]) * ps * (za[e] * fsigmoid(za[e])); }
;         outw[q] = pack8(y); }
; #pragma unroll
;     for (int q = 0; q < NI; ++q) *(u32x4*)zp[q] = outw[q];
	v_pk_fma_f32 v[20:21], v[46:47], v[34:35], v[20:21] op_sel_hi:[0,1,1]
	v_lshlrev_b32_e32 v28, 16, v32
	v_pk_fma_f32 v[20:21], v[48:49], v[28:29], v[20:21] op_sel_hi:[0,1,1]
	v_lshlrev_b32_e32 v32, 16, v19
	v_pk_fma_f32 v[20:21], v[42:43], v[20:21], v[24:25] op_sel_hi:[0,1,1] neg_lo:[0,0,1] neg_hi:[0,0,1]
	v_add_u32_e32 v24, 1, v103
	v_mul_f32_e32 v19, 0xbfb8aa3b, v32
	v_cvt_f32_u32_e32 v24, v24
	v_exp_f32_e32 v19, v19
	v_pk_mul_f32 v[20:21], v[20:21], v[64:65]
	v_cvt_pk_bf16_f32 v23, v52, v53
	v_pk_mul_f32 v[20:21], v[30:31], v[20:21]
	v_div_scale_f32 v25, s[8:9], v24, v24, 1.0
	v_add_f32_e32 v19, 1.0, v19
	v_cvt_pk_bf16_f32 v20, v20, v21
	v_cvt_pk_bf16_f32 v21, v26, v27
	v_rcp_f32_e32 v26, v25
	v_rcp_f32_e32 v34, v19
	v_mul_f32_e32 v19, 0xbfb8aa3b, v33
	v_exp_f32_e32 v19, v19
	v_fma_f32 v27, -v25, v26, 1.0
	v_fmac_f32_e32 v26, v27, v26
	v_div_scale_f32 v27, vcc, 1.0, v24, 1.0
	v_add_f32_e32 v19, 1.0, v19
	v_mul_f32_e32 v28, v27, v26
	v_rcp_f32_e32 v35, v19
	v_fma_f32 v29, -v25, v28, v27
	v_fmac_f32_e32 v28, v29, v26
	v_fma_f32 v25, -v25, v28, v27
	v_div_fmas_f32 v25, v25, v26, v28
	v_cndmask_b32_e64 v26, 1.0, 0, s[2:3]
	v_pk_mul_f32 v[32:33], v[34:35], v[32:33]
	v_lshlrev_b32_e32 v34, 16, v7
	v_and_b32_e32 v35, 0xffff0000, v7
	v_cndmask_b32_e64 v28, 1.0, 0, s[4:5]
	v_pk_fma_f32 v[34:35], v[26:27], v[34:35], v[36:37] op_sel_hi:[0,1,1]
	v_div_fixup_f32 v24, v25, v24, 1.0
	v_cndmask_b32_e64 v30, 1.0, 0, s[6:7]
	v_pk_fma_f32 v[34:35], v[28:29], v[38:39], v[34:35] op_sel_hi:[0,1,1]
	v_lshlrev_b32_e32 v38, 16, v15
	v_and_b32_e32 v39, 0xffff0000, v15
	v_cndmask_b32_e64 v24, v250, v24, s[6:7]
	v_pk_fma_f32 v[34:35], v[30:31], v[38:39], v[34:35] op_sel_hi:[0,1,1]
	v_pk_fma_f32 v[34:35], v[24:25], v[34:35], v[36:37] op_sel_hi:[0,1,1] neg_lo:[0,0,1] neg_hi:[0,0,1]
	v_pk_mul_f32 v[34:35], v[34:35], v[62:63]
	v_and_b32_e32 v7, 0xffff0000, v2
	v_pk_mul_f32 v[32:33], v[32:33], v[34:35]
	v_lshlrev_b32_e32 v34, 16, v18
	v_mul_f32_e32 v3, 0xbfb8aa3b, v34
	v_exp_f32_e32 v3, v3
	v_and_b32_e32 v35, 0xffff0000, v18
	v_and_b32_e32 v15, 0xffff0000, v1
	s_add_i32 s2, s31, s26
	v_add_f32_e32 v3, 1.0, v3
	v_rcp_f32_e32 v18, v3
	v_mul_f32_e32 v3, 0xbfb8aa3b, v35
	v_exp_f32_e32 v3, v3
	s_cmpk_gt_i32 s2, 0x1fff
	v_add_f32_e32 v3, 1.0, v3
	v_rcp_f32_e32 v19, v3
	s_nop 0
	v_pk_mul_f32 v[18:19], v[18:19], v[34:35]
	v_lshlrev_b32_e32 v34, 16, v6
	v_and_b32_e32 v35, 0xffff0000, v6
	v_lshlrev_b32_e32 v6, 16, v2
	v_pk_fma_f32 v[2:3], v[26:27], v[34:35], v[6:7] op_sel_hi:[0,1,1]
	v_lshlrev_b32_e32 v34, 16, v10
	v_and_b32_e32 v35, 0xffff0000, v10
	v_pk_fma_f32 v[2:3], v[28:29], v[34:35], v[2:3] op_sel_hi:[0,1,1]
	v_lshlrev_b32_e32 v10, 16, v14
	v_pk_fma_f32 v[2:3], v[30:31], v[10:11], v[2:3] op_sel_hi:[0,1,1]
	v_pk_fma_f32 v[2:3], v[24:25], v[2:3], v[6:7] op_sel_hi:[0,1,1] neg_lo:[0,0,1] neg_hi:[0,0,1]
	v_lshlrev_b32_e32 v6, 16, v17
	v_and_b32_e32 v7, 0xffff0000, v17
	v_mul_f32_e32 v10, 0xbfb8aa3b, v6
	v_mul_f32_e32 v11, 0xbfb8aa3b, v7
	v_exp_f32_e32 v10, v10
	v_exp_f32_e32 v11, v11
	v_pk_mul_f32 v[2:3], v[2:3], v[60:61]
	v_lshlrev_b32_e32 v14, 16, v1
	v_add_f32_e32 v10, 1.0, v10
	v_add_f32_e32 v11, 1.0, v11
	v_rcp_f32_e32 v10, v10
	v_rcp_f32_e32 v11, v11
	v_pk_mul_f32 v[2:3], v[18:19], v[2:3]
	v_lshlrev_b32_e32 v18, 16, v9
	v_and_b32_e32 v19, 0xffff0000, v9
	v_pk_mul_f32 v[6:7], v[10:11], v[6:7]
	v_lshlrev_b32_e32 v10, 16, v5
	v_and_b32_e32 v11, 0xffff0000, v5
	v_pk_fma_f32 v[10:11], v[26:27], v[10:11], v[14:15] op_sel_hi:[0,1,1]
	v_pk_fma_f32 v[10:11], v[28:29], v[18:19], v[10:11] op_sel_hi:[0,1,1]
	v_lshlrev_b32_e32 v18, 16, v13
	v_and_b32_e32 v19, 0xffff0000, v13
	v_pk_fma_f32 v[10:11], v[30:31], v[18:19], v[10:11] op_sel_hi:[0,1,1]
	v_pk_fma_f32 v[10:11], v[24:25], v[10:11], v[14:15] op_sel_hi:[0,1,1] neg_lo:[0,0,1] neg_hi:[0,0,1]
	v_pk_mul_f32 v[10:11], v[10:11], v[66:67]
	v_and_b32_e32 v5, 0xffff0000, v0
	v_pk_mul_f32 v[6:7], v[6:7], v[10:11]
	v_lshlrev_b32_e32 v10, 16, v16
	v_mul_f32_e32 v1, 0xbfb8aa3b, v10
	v_exp_f32_e32 v1, v1
	v_and_b32_e32 v11, 0xffff0000, v16
	v_and_b32_e32 v9, 0xffff0000, v12
	v_and_b32_e32 v13, 0xffff0000, v51
	v_add_f32_e32 v1, 1.0, v1
	v_rcp_f32_e32 v14, v1
	v_mul_f32_e32 v1, 0xbfb8aa3b, v11
	v_exp_f32_e32 v1, v1
	v_cvt_pk_bf16_f32 v2, v2, v3
	v_cvt_pk_bf16_f32 v3, v32, v33
	v_add_f32_e32 v1, 1.0, v1
	v_rcp_f32_e32 v15, v1
	s_nop 0
	v_pk_mul_f32 v[10:11], v[14:15], v[10:11]
	v_lshlrev_b32_e32 v14, 16, v4
	v_and_b32_e32 v15, 0xffff0000, v4
	v_lshlrev_b32_e32 v4, 16, v0
	v_pk_fma_f32 v[0:1], v[26:27], v[14:15], v[4:5] op_sel_hi:[0,1,1]
	v_lshlrev_b32_e32 v14, 16, v8
	v_and_b32_e32 v15, 0xffff0000, v8
	v_pk_fma_f32 v[0:1], v[28:29], v[14:15], v[0:1] op_sel_hi:[0,1,1]
	v_lshlrev_b32_e32 v8, 16, v12
	v_pk_fma_f32 v[0:1], v[30:31], v[8:9], v[0:1] op_sel_hi:[0,1,1]
	v_pk_fma_f32 v[0:1], v[24:25], v[0:1], v[4:5] op_sel_hi:[0,1,1] neg_lo:[0,0,1] neg_hi:[0,0,1]
	v_pk_mul_f32 v[0:1], v[0:1], v[64:65]
	v_lshlrev_b32_e32 v4, 16, v59
	v_pk_mul_f32 v[0:1], v[10:11], v[0:1]
	v_and_b32_e32 v5, 0xffff0000, v59
	v_cvt_pk_bf16_f32 v0, v0, v1
	v_cvt_pk_bf16_f32 v1, v6, v7
	v_mul_f32_e32 v6, 0xbfb8aa3b, v4
	v_mul_f32_e32 v7, 0xbfb8aa3b, v5
	v_exp_f32_e32 v6, v6
	v_exp_f32_e32 v7, v7
	v_lshlrev_b32_e32 v8, 16, v47
	v_and_b32_e32 v9, 0xffff0000, v47
	v_add_f32_e32 v6, 1.0, v6
	v_lshlrev_b32_e32 v10, 16, v43
	v_and_b32_e32 v11, 0xffff0000, v43
	v_add_f32_e32 v7, 1.0, v7
	v_rcp_f32_e32 v6, v6
	v_pk_fma_f32 v[8:9], v[106:107], v[8:9], v[10:11] op_sel_hi:[0,1,1]
	v_lshlrev_b32_e32 v12, 16, v51
	v_rcp_f32_e32 v7, v7
	v_pk_fma_f32 v[8:9], v[104:105], v[12:13], v[8:9] op_sel_hi:[0,1,1]
	v_lshlrev_b32_e32 v12, 16, v55
	v_and_b32_e32 v13, 0xffff0000, v55
	v_pk_fma_f32 v[8:9], v[102:103], v[12:13], v[8:9] op_sel_hi:[0,1,1]
	v_pk_fma_f32 v[8:9], v[100:101], v[8:9], v[10:11] op_sel_hi:[0,1,1] neg_lo:[0,0,1] neg_hi:[0,0,1]
	v_pk_mul_f32 v[8:9], v[62:63], v[8:9]
	v_pk_mul_f32 v[4:5], v[6:7], v[4:5]
	v_add_u32_e32 v101, s91, v101
	v_pk_mul_f32 v[8:9], v[8:9], v[4:5]
	v_cvt_pk_bf16_f32 v4, v40, v41
	v_cvt_pk_bf16_f32 v5, v74, v75
	v_cvt_pk_bf16_f32 v6, v108, v109
	v_cvt_pk_bf16_f32 v7, v8, v9
	global_store_dwordx4 v[92:93], v[0:3], off offset:2560 nt
	global_store_dwordx4 v[94:95], v[20:23], off offset:2560 nt
	global_store_dwordx4 v[96:97], v[68:71], off offset:2560 nt
	global_store_dwordx4 v[98:99], v[4:7], off offset:2560 nt
	s_cbranch_scc0 .LBB0_377

; __device__ __forceinline__ float fsigmoid(float v) { return __builtin_amdgcn_rcpf(1.f + __builtin_amdgcn_exp2f(-v * LOG2E)); }
; __device__ __forceinline__ u32x4 pack8(const float (&f)[8]) { u32x4 w; w.x = cvtpk(f[0], f[1]); w.y = cvtpk(f[2], f[3]); w.z = cvtpk(f[4], f[5]); w.w = cvtpk(f[6], f[7]); return w; }
; template <int W, int NI> __device__ __forceinline__ void pool_items(bf16_t* PB, const float* pscale, const int (&rps)[NI], int g, int lane) {
;     const int ch = g * 256 + (lane & 31) * 8;
;     u32x4 v[NI][W], zw[NI]; int t[NI]; bf16_t* zp[NI];
; #pragma unroll
;     for (int q = 0; q < NI; ++q) { const int row = 2 * rps[q] + (lane >> 5); t[q] = row & (SEQ - 1);
;         const bf16_t* xp = PB + (size_t)row * PBW + C_XA + ch;
; #pragma unroll
;         for (int jj = 0; jj < W; ++jj) { const int back = (jj <= t[q]) ? jj : 0; v[q][jj] = *(const u32x4*)(xp - (size_t)back * PBW); }
;         zp[q] = PB + (size_t)row * PBW + C_ZA + ch; zw[q] = *(const u32x4*)zp[q]; }
;     const f32x4 p0 = *(const f32x4*)(pscale + ch), p1 = *(const f32x4*)(pscale + ch + 4);
;     u32x4 outw[NI];
; #pragma unroll
;     for (int q = 0; q < NI; ++q) {
;         float za[8], sum[8], x0[8]; unpack8(zw[q], za); unpack8(v[q][0], x0);
; #pragma unroll
;         for (int e = 0; e < 8; ++e) sum[e] = x0[e];
; #pragma unroll
;         for (int jj = 1; jj < W; ++jj) { float f[8]; unpack8(v[q][jj], f); const float mk = (jj <= t[q]) ? 1.f : 0.f;
; #pragma unroll
;             for (int e = 0; e < 8; ++e) sum[e] += mk * f[e]; }
;         const int cnt = (t[q] + 1 < W) ? (t[q] + 1) : W;
;         const float inv = 1.f / (float)cnt;
;         float y[8];
; #pragma unroll
;         for (int e = 0; e < 8; ++e) { const float ps = (e < 4) ? p0[e & 3] : p1[e & 3]; y[e] = (sum[e] * inv - x0[e]) * ps * (za[e] * fsigmoid(za[e])); }
;         outw[q] = pack8(y); }
; #pragma unroll
;     for (int q = 0; q < NI; ++q) *(u32x4*)zp[q] = outw[q];
; __device__ __forceinline__ void phase_mixers(PP p, int l, int lane, int wave, LAS unsigned char* lds) {
;     ...
;       for (; rp < MTOK / 2; rp += NGW) { const int r1[1] = {rp}; pool_items<4, 1>(PB, pscale, r1, 1, lane); } }
.LBB0_380:
	v_mad_i64_i32 v[34:35], s[2:3], v4, s65, v[2:3]
	global_load_dwordx4 v[6:9], v[34:35], off offset:2560
	global_load_dwordx4 v[10:13], v[34:35], off offset:512
	v_and_b32_e32 v5, 0xfff, v4
	v_cmp_eq_u32_e64 s[2:3], 0, v5
	v_cmp_gt_u32_e64 s[4:5], 2, v5
	v_cmp_gt_u32_e64 s[6:7], 3, v5
	v_cndmask_b32_e64 v15, -1, 0, s[2:3]
	v_cndmask_b32_e64 v14, v225, 0, s[2:3]
	v_lshl_add_u64 v[14:15], v[34:35], 0, v[14:15]
	v_cndmask_b32_e64 v19, -1, 0, s[4:5]
	v_cndmask_b32_e64 v18, v227, 0, s[4:5]
	global_load_dwordx4 v[14:17], v[14:15], off offset:512
	v_lshl_add_u64 v[18:19], v[34:35], 0, v[18:19]
	global_load_dwordx4 v[18:21], v[18:19], off offset:512
	v_cndmask_b32_e64 v23, -1, 0, s[6:7]
	v_cndmask_b32_e64 v22, v229, 0, s[6:7]
	v_lshl_add_u64 v[22:23], v[34:35], 0, v[22:23]
	global_load_dwordx4 v[22:25], v[22:23], off offset:512
	s_nop 0
	global_load_dwordx4 v[26:29], v[0:1], off offset:1040
	global_load_dwordx4 v[30:33], v[0:1], off offset:1024
	v_add_u32_e32 v5, 1, v5
	v_cvt_f32_u32_e32 v5, v5
	v_cndmask_b32_e64 v42, 1.0, 0, s[6:7]
	s_add_i32 s26, s26, s74
	v_add_u32_e32 v4, s82, v4
	v_div_scale_f32 v36, s[8:9], v5, v5, 1.0
	v_rcp_f32_e32 v37, v36
	s_cmpk_gt_i32 s26, 0x1fff
	v_fma_f32 v38, -v36, v37, 1.0
	v_fmac_f32_e32 v37, v38, v37
	v_div_scale_f32 v38, vcc, 1.0, v5, 1.0
	v_mul_f32_e32 v39, v38, v37
	v_fma_f32 v40, -v36, v39, v38
	v_fmac_f32_e32 v39, v40, v37
	v_fma_f32 v36, -v36, v39, v38
	v_div_fmas_f32 v36, v36, v37, v39
	v_div_fixup_f32 v5, v36, v5, 1.0
	v_cndmask_b32_e64 v36, v250, v5, s[6:7]
	v_cndmask_b32_e64 v38, 1.0, 0, s[2:3]
	v_cndmask_b32_e64 v40, 1.0, 0, s[4:5]
	s_waitcnt vmcnt(6)
	v_lshlrev_b32_e32 v44, 16, v8
	v_mul_f32_e32 v5, 0xbfb8aa3b, v44
	v_exp_f32_e32 v5, v5
	v_and_b32_e32 v45, 0xffff0000, v8
	s_waitcnt vmcnt(5)
	v_lshlrev_b32_e32 v48, 16, v12
	v_and_b32_e32 v49, 0xffff0000, v12
	v_add_f32_e32 v5, 1.0, v5
	v_rcp_f32_e32 v46, v5
	v_mul_f32_e32 v5, 0xbfb8aa3b, v45
	v_exp_f32_e32 v5, v5
	v_lshlrev_b32_e32 v8, 16, v9
	v_and_b32_e32 v9, 0xffff0000, v9
	v_lshlrev_b32_e32 v12, 16, v13
	v_add_f32_e32 v5, 1.0, v5
	v_rcp_f32_e32 v47, v5
	s_waitcnt vmcnt(3)
	v_lshlrev_b32_e32 v50, 16, v20
	v_and_b32_e32 v51, 0xffff0000, v20
	v_and_b32_e32 v13, 0xffff0000, v13
	v_pk_mul_f32 v[44:45], v[46:47], v[44:45]
	v_lshlrev_b32_e32 v46, 16, v16
	v_and_b32_e32 v47, 0xffff0000, v16
	v_pk_fma_f32 v[46:47], v[38:39], v[46:47], v[48:49] op_sel_hi:[0,1,1]
	v_pk_fma_f32 v[46:47], v[40:41], v[50:51], v[46:47] op_sel_hi:[0,1,1]
	s_waitcnt vmcnt(2)
	v_lshlrev_b32_e32 v50, 16, v24
	v_and_b32_e32 v51, 0xffff0000, v24
	v_pk_fma_f32 v[46:47], v[42:43], v[50:51], v[46:47] op_sel_hi:[0,1,1]
	v_pk_fma_f32 v[46:47], v[36:37], v[46:47], v[48:49] op_sel_hi:[0,1,1] neg_lo:[0,0,1] neg_hi:[0,0,1]
	s_waitcnt vmcnt(1)
	v_pk_mul_f32 v[26:27], v[26:27], v[46:47]
	v_lshlrev_b32_e32 v48, 16, v11
	v_pk_mul_f32 v[26:27], v[44:45], v[26:27]
	v_lshlrev_b32_e32 v44, 16, v7
	v_mul_f32_e32 v5, 0xbfb8aa3b, v44
	v_exp_f32_e32 v5, v5
	v_and_b32_e32 v45, 0xffff0000, v7
	v_and_b32_e32 v49, 0xffff0000, v11
	v_lshlrev_b32_e32 v50, 16, v19
	v_add_f32_e32 v5, 1.0, v5
	v_rcp_f32_e32 v46, v5
	v_mul_f32_e32 v5, 0xbfb8aa3b, v45
	v_exp_f32_e32 v5, v5
	v_and_b32_e32 v51, 0xffff0000, v19
	v_and_b32_e32 v19, 0xffff0000, v22
	v_lshlrev_b32_e32 v16, 16, v21
	v_add_f32_e32 v5, 1.0, v5
	v_rcp_f32_e32 v47, v5
	s_nop 0
	v_pk_mul_f32 v[44:45], v[46:47], v[44:45]
	v_lshlrev_b32_e32 v46, 16, v15
	v_and_b32_e32 v47, 0xffff0000, v15
	v_pk_fma_f32 v[46:47], v[38:39], v[46:47], v[48:49] op_sel_hi:[0,1,1]
	v_pk_fma_f32 v[46:47], v[40:41], v[50:51], v[46:47] op_sel_hi:[0,1,1]
	v_lshlrev_b32_e32 v50, 16, v23
	v_and_b32_e32 v51, 0xffff0000, v23
	v_pk_fma_f32 v[46:47], v[42:43], v[50:51], v[46:47] op_sel_hi:[0,1,1]
	v_pk_fma_f32 v[46:47], v[36:37], v[46:47], v[48:49] op_sel_hi:[0,1,1] neg_lo:[0,0,1] neg_hi:[0,0,1]
	s_waitcnt vmcnt(0)
	v_pk_mul_f32 v[32:33], v[32:33], v[46:47]
	v_and_b32_e32 v15, 0xffff0000, v10
	v_pk_mul_f32 v[32:33], v[44:45], v[32:33]
	v_lshlrev_b32_e32 v44, 16, v6
	v_mul_f32_e32 v5, 0xbfb8aa3b, v44
	v_exp_f32_e32 v5, v5
	v_and_b32_e32 v45, 0xffff0000, v6
	v_add_f32_e32 v5, 1.0, v5
	v_rcp_f32_e32 v6, v5
	v_mul_f32_e32 v5, 0xbfb8aa3b, v45
	v_exp_f32_e32 v5, v5
	s_nop 0
	v_add_f32_e32 v5, 1.0, v5
	v_rcp_f32_e32 v7, v5
	v_mul_f32_e32 v5, 0xbfb8aa3b, v8
	v_exp_f32_e32 v5, v5
	v_pk_mul_f32 v[6:7], v[6:7], v[44:45]
	v_lshlrev_b32_e32 v44, 16, v14
	v_and_b32_e32 v45, 0xffff0000, v14
	v_lshlrev_b32_e32 v14, 16, v10
	v_pk_fma_f32 v[10:11], v[38:39], v[44:45], v[14:15] op_sel_hi:[0,1,1]
	v_lshlrev_b32_e32 v44, 16, v18
	v_and_b32_e32 v45, 0xffff0000, v18
	v_pk_fma_f32 v[10:11], v[40:41], v[44:45], v[10:11] op_sel_hi:[0,1,1]
	v_lshlrev_b32_e32 v18, 16, v22
	v_pk_fma_f32 v[10:11], v[42:43], v[18:19], v[10:11] op_sel_hi:[0,1,1]
	v_pk_fma_f32 v[10:11], v[36:37], v[10:11], v[14:15] op_sel_hi:[0,1,1] neg_lo:[0,0,1] neg_hi:[0,0,1]
	v_pk_mul_f32 v[10:11], v[30:31], v[10:11]
	v_add_f32_e32 v5, 1.0, v5
	v_pk_mul_f32 v[6:7], v[6:7], v[10:11]
	v_rcp_f32_e32 v10, v5
	v_mul_f32_e32 v5, 0xbfb8aa3b, v9
	v_exp_f32_e32 v5, v5
	v_lshlrev_b32_e32 v14, 16, v17
	v_and_b32_e32 v15, 0xffff0000, v17
	v_pk_fma_f32 v[14:15], v[38:39], v[14:15], v[12:13] op_sel_hi:[0,1,1]
	v_add_f32_e32 v5, 1.0, v5
	v_and_b32_e32 v17, 0xffff0000, v21
	v_rcp_f32_e32 v11, v5
	v_pk_fma_f32 v[14:15], v[40:41], v[16:17], v[14:15] op_sel_hi:[0,1,1]
	v_lshlrev_b32_e32 v16, 16, v25
	v_and_b32_e32 v17, 0xffff0000, v25
	v_pk_fma_f32 v[14:15], v[42:43], v[16:17], v[14:15] op_sel_hi:[0,1,1]
	v_pk_fma_f32 v[12:13], v[36:37], v[14:15], v[12:13] op_sel_hi:[0,1,1] neg_lo:[0,0,1] neg_hi:[0,0,1]
	v_pk_mul_f32 v[12:13], v[28:29], v[12:13]
	v_pk_mul_f32 v[8:9], v[10:11], v[8:9]
	v_cvt_pk_bf16_f32 v6, v6, v7
	v_pk_mul_f32 v[10:11], v[8:9], v[12:13]
	v_cvt_pk_bf16_f32 v7, v32, v33
	v_cvt_pk_bf16_f32 v8, v26, v27
	v_cvt_pk_bf16_f32 v9, v10, v11
	global_store_dwordx4 v[34:35], v[6:9], off offset:2560 nt
	s_cbranch_scc0 .LBB0_380

; __device__ __forceinline__ float fsigmoid(float v) { return __builtin_amdgcn_rcpf(1.f + __builtin_amdgcn_exp2f(-v * LOG2E)); }
; template <int W, int NI> __device__ __forceinline__ void pool_items(bf16_t* PB, const float* pscale, const int (&rps)[NI], int g, int lane) {
;     const int ch = g * 256 + (lane & 31) * 8;
;     u32x4 v[NI][W], zw[NI]; int t[NI]; bf16_t* zp[NI];
; #pragma unroll
;     for (int q = 0; q < NI; ++q) { const int row = 2 * rps[q] + (lane >> 5); t[q] = row & (SEQ - 1);
;         const bf16_t* xp = PB + (size_t)row * PBW + C_XA + ch;
; #pragma unroll
;         for (int jj = 0; jj < W; ++jj) { const int back = (jj <= t[q]) ? jj : 0; v[q][jj] = *(const u32x4*)(xp - (size_t)back * PBW); }
;         zp[q] = PB + (size_t)row * PBW + C_ZA + ch; zw[q] = *(const u32x4*)zp[q]; }
;     const f32x4 p0 = *(const f32x4*)(pscale + ch), p1 = *(const f32x4*)(pscale + ch + 4);
;     u32x4 outw[NI];
; #pragma unroll
;     for (int q = 0; q < NI; ++q) {
;         float za[8], sum[8], x0[8]; unpack8(zw[q], za); unpack8(v[q][0], x0);
; #pragma unroll
;         for (int e = 0; e < 8; ++e) sum[e] = x0[e];
; #pragma unroll
;         for (int jj = 1; jj < W; ++jj) { float f[8]; unpack8(v[q][jj], f); const float mk = (jj <= t[q]) ? 1.f : 0.f;
; #pragma unroll
;             for (int e = 0; e < 8; ++e) sum[e] += mk * f[e]; }
;         const int cnt = (t[q] + 1 < W) ? (t[q] + 1) : W;
;         const float inv = 1.f / (float)cnt;
;         float y[8];
; #pragma unroll
;         for (int e = 0; e < 8; ++e) { const float ps = (e < 4) ? p0[e & 3] : p1[e & 3]; y[e] = (sum[e] * inv - x0[e]) * ps * (za[e] * fsigmoid(za[e])); }
.LBB0_383:
	v_and_b32_e32 v88, 0xfff, v89
	v_mad_i64_i32 v[84:85], s[2:3], v89, s65, v[82:83]
	v_cmp_eq_u32_e64 s[2:3], 0, v88
	v_cmp_gt_u32_e64 s[12:13], 6, v88
	v_cmp_gt_u32_e64 s[4:5], 2, v88
	v_cndmask_b32_e64 v5, -1, 0, s[2:3]
	v_cndmask_b32_e64 v4, v225, 0, s[2:3]
	v_cndmask_b32_e64 v13, -1, 0, s[12:13]
	v_cndmask_b32_e64 v12, v253, 0, s[12:13]
	v_lshl_add_u64 v[4:5], v[84:85], 0, v[4:5]
	v_lshl_add_u64 v[12:13], v[84:85], 0, v[12:13]
	global_load_dwordx4 v[8:11], v[4:5], off offset:1024
	v_cmp_gt_u32_e64 s[6:7], 3, v88
	global_load_dwordx4 v[12:15], v[12:13], off offset:1024
	v_cndmask_b32_e64 v5, -1, 0, s[4:5]
	v_cndmask_b32_e64 v4, v227, 0, s[4:5]
	v_lshl_add_u64 v[4:5], v[84:85], 0, v[4:5]
	global_load_dwordx4 v[0:3], v[84:85], off offset:1024
	global_load_dwordx4 v[20:23], v[4:5], off offset:1024
	v_cndmask_b32_e64 v5, -1, 0, s[6:7]
	v_cndmask_b32_e64 v4, v229, 0, s[6:7]
	v_lshl_add_u64 v[4:5], v[84:85], 0, v[4:5]
	v_cmp_gt_u32_e64 s[8:9], 4, v88
	global_load_dwordx4 v[24:27], v[4:5], off offset:1024
	v_cmp_gt_u32_e64 s[10:11], 5, v88
	v_cndmask_b32_e64 v5, -1, 0, s[8:9]
	v_cndmask_b32_e64 v4, v251, 0, s[8:9]
	v_lshl_add_u64 v[4:5], v[84:85], 0, v[4:5]
	v_cmp_gt_u32_e64 s[14:15], 7, v88
	global_load_dwordx4 v[28:31], v[4:5], off offset:1024
	v_cndmask_b32_e64 v5, -1, 0, s[10:11]
	v_cndmask_b32_e64 v4, v252, 0, s[10:11]
	v_cndmask_b32_e64 v17, -1, 0, s[14:15]
	v_cndmask_b32_e64 v16, v234, 0, s[14:15]
	v_lshl_add_u64 v[4:5], v[84:85], 0, v[4:5]
	v_lshl_add_u64 v[16:17], v[84:85], 0, v[16:17]
	global_load_dwordx4 v[4:7], v[4:5], off offset:1024
	s_nop 0
	global_load_dwordx4 v[16:19], v[16:17], off offset:1024
	s_nop 0
	global_load_dwordx4 v[32:35], v[84:85], off offset:3072
	v_lshl_add_u32 v36, s16, 1, v165
	v_and_b32_e32 v91, 0xfff, v36
	v_mad_i64_i32 v[86:87], s[16:17], v36, s65, v[82:83]
	v_cmp_eq_u32_e64 s[16:17], 0, v91
	v_cmp_gt_u32_e64 s[26:27], 6, v91
	v_cmp_gt_u32_e64 s[18:19], 2, v91
	v_cndmask_b32_e64 v41, -1, 0, s[16:17]
	v_cndmask_b32_e64 v40, v225, 0, s[16:17]
	v_cndmask_b32_e64 v49, -1, 0, s[26:27]
	v_cndmask_b32_e64 v48, v253, 0, s[26:27]
	v_lshl_add_u64 v[40:41], v[86:87], 0, v[40:41]
	v_lshl_add_u64 v[48:49], v[86:87], 0, v[48:49]
	global_load_dwordx4 v[44:47], v[40:41], off offset:1024
	v_cmp_gt_u32_e64 s[20:21], 3, v91
	global_load_dwordx4 v[48:51], v[48:49], off offset:1024
	v_cndmask_b32_e64 v41, -1, 0, s[18:19]
	v_cndmask_b32_e64 v40, v227, 0, s[18:19]
	v_lshl_add_u64 v[40:41], v[86:87], 0, v[40:41]
	global_load_dwordx4 v[36:39], v[86:87], off offset:1024
	global_load_dwordx4 v[56:59], v[40:41], off offset:1024
	v_cndmask_b32_e64 v41, -1, 0, s[20:21]
	v_cndmask_b32_e64 v40, v229, 0, s[20:21]
	v_lshl_add_u64 v[40:41], v[86:87], 0, v[40:41]
	v_cmp_gt_u32_e64 s[22:23], 4, v91
	global_load_dwordx4 v[60:63], v[40:41], off offset:1024
	v_cmp_gt_u32_e64 s[24:25], 5, v91
	v_cndmask_b32_e64 v41, -1, 0, s[22:23]
	v_cndmask_b32_e64 v40, v251, 0, s[22:23]
	v_lshl_add_u64 v[40:41], v[86:87], 0, v[40:41]
	v_cmp_gt_u32_e64 s[28:29], 7, v91
	global_load_dwordx4 v[64:67], v[40:41], off offset:1024
	v_cndmask_b32_e64 v41, -1, 0, s[24:25]
	v_cndmask_b32_e64 v40, v252, 0, s[24:25]
	v_cndmask_b32_e64 v53, -1, 0, s[28:29]
	v_cndmask_b32_e64 v52, v234, 0, s[28:29]
	v_lshl_add_u64 v[40:41], v[86:87], 0, v[40:41]
	v_lshl_add_u64 v[52:53], v[86:87], 0, v[52:53]
	global_load_dwordx4 v[40:43], v[40:41], off offset:1024
	s_nop 0
	global_load_dwordx4 v[52:55], v[52:53], off offset:1024
	s_nop 0
	global_load_dwordx4 v[68:71], v[86:87], off offset:3072
	global_load_dwordx4 v[76:79], v[80:81], off offset:2048
	global_load_dwordx4 v[72:75], v[80:81], off offset:2064
	v_add_u32_e32 v88, 1, v88
	v_cvt_f32_u32_e32 v88, v88
	v_cndmask_b32_e64 v96, 1.0, 0, s[4:5]
	v_cndmask_b32_e64 v98, 1.0, 0, s[6:7]
	v_cndmask_b32_e64 v102, 1.0, 0, s[8:9]
	v_div_scale_f32 v90, s[36:37], v88, v88, 1.0
	v_rcp_f32_e32 v92, v90
	v_cndmask_b32_e64 v100, 1.0, 0, s[10:11]
	v_cndmask_b32_e64 v118, 1.0, 0, s[22:23]
	v_cndmask_b32_e64 v122, 1.0, 0, s[24:25]
	v_fma_f32 v93, -v90, v92, 1.0
	v_fmac_f32_e32 v92, v93, v92
	s_waitcnt vmcnt(19)
	v_lshlrev_b32_e32 v110, 16, v11
	v_and_b32_e32 v111, 0xffff0000, v11
	v_div_scale_f32 v93, vcc, 1.0, v88, 1.0
	v_mul_f32_e32 v94, v93, v92
	v_fma_f32 v95, -v90, v94, v93
	v_fmac_f32_e32 v94, v95, v92
	v_fma_f32 v90, -v90, v94, v93
	v_div_fmas_f32 v90, v90, v92, v94
	v_cndmask_b32_e64 v94, 1.0, 0, s[2:3]
	s_waitcnt vmcnt(16)
	v_lshlrev_b32_e32 v104, 16, v23
	v_and_b32_e32 v105, 0xffff0000, v23
	s_waitcnt vmcnt(15)
	v_lshlrev_b32_e32 v106, 16, v27
	v_and_b32_e32 v107, 0xffff0000, v27
	v_cndmask_b32_e64 v92, 1.0, 0, s[12:13]
	v_div_fixup_f32 v88, v90, v88, 1.0
	v_cndmask_b32_e64 v90, 1.0, 0, s[14:15]
	v_cndmask_b32_e64 v88, v224, v88, s[14:15]
	s_waitcnt vmcnt(14)
	v_lshlrev_b32_e32 v108, 16, v31
	v_and_b32_e32 v109, 0xffff0000, v31
	v_cndmask_b32_e64 v124, 1.0, 0, s[26:27]
	v_cndmask_b32_e64 v126, 1.0, 0, s[28:29]
	s_add_i32 s35, s35, s82
	s_add_i32 s34, s34, s82
	s_waitcnt vmcnt(13)
	v_and_b32_e32 v27, 0xffff0000, v6
	s_waitcnt vmcnt(11)
	v_lshlrev_b32_e32 v112, 16, v35
	v_mul_f32_e32 v11, 0xbfb8aa3b, v112
	v_exp_f32_e32 v11, v11
	v_and_b32_e32 v113, 0xffff0000, v35
	v_add_f32_e32 v11, 1.0, v11
	v_rcp_f32_e32 v114, v11
	v_mul_f32_e32 v11, 0xbfb8aa3b, v113
	v_exp_f32_e32 v11, v11
	s_waitcnt vmcnt(10)
; __device__ __forceinline__ float fsigmoid(float v) { return __builtin_amdgcn_rcpf(1.f + __builtin_amdgcn_exp2f(-v * LOG2E)); }
; __device__ __forceinline__ u32x4 pack8(const float (&f)[8]) { u32x4 w; w.x = cvtpk(f[0], f[1]); w.y = cvtpk(f[2], f[3]); w.z = cvtpk(f[4], f[5]); w.w = cvtpk(f[6], f[7]); return w; }
; template <int W, int NI> __device__ __forceinline__ void pool_items(bf16_t* PB, const float* pscale, const int (&rps)[NI], int g, int lane) {
;     ...
;     for (int q = 0; q < NI; ++q) {
;         float za[8], sum[8], x0[8]; unpack8(zw[q], za); unpack8(v[q][0], x0);
; #pragma unroll
;         for (int e = 0; e < 8; ++e) sum[e] = x0[e];
; #pragma unroll
;         for (int jj = 1; jj < W; ++jj) { float f[8]; unpack8(v[q][jj], f); const float mk = (jj <= t[q]) ? 1.f : 0.f;
; #pragma unroll
;             for (int e = 0; e < 8; ++e) sum[e] += mk * f[e]; }
;         const int cnt = (t[q] + 1 < W) ? (t[q] + 1) : W;
;         const float inv = 1.f / (float)cnt;
;         float y[8];
; #pragma unroll
;         for (int e = 0; e < 8; ++e) { const float ps = (e < 4) ? p0[e & 3] : p1[e & 3]; y[e] = (sum[e] * inv - x0[e]) * ps * (za[e] * fsigmoid(za[e])); }
;         outw[q] = pack8(y); }
	v_lshlrev_b32_e32 v134, 16, v46
	v_add_f32_e32 v11, 1.0, v11
	v_rcp_f32_e32 v115, v11
	v_and_b32_e32 v135, 0xffff0000, v46
	v_pk_mul_f32 v[112:113], v[114:115], v[112:113]
	v_lshlrev_b32_e32 v114, 16, v3
	v_and_b32_e32 v115, 0xffff0000, v3
	v_add_u32_e32 v3, 1, v91
	v_cvt_f32_u32_e32 v3, v3
	v_pk_fma_f32 v[110:111], v[94:95], v[110:111], v[114:115] op_sel_hi:[0,1,1]
	v_pk_fma_f32 v[104:105], v[96:97], v[104:105], v[110:111] op_sel_hi:[0,1,1]
	v_pk_fma_f32 v[104:105], v[98:99], v[106:107], v[104:105] op_sel_hi:[0,1,1]
	v_lshlrev_b32_e32 v106, 16, v7
	v_and_b32_e32 v107, 0xffff0000, v7
	v_div_scale_f32 v7, s[2:3], v3, v3, 1.0
	v_rcp_f32_e32 v11, v7
	v_pk_fma_f32 v[104:105], v[102:103], v[108:109], v[104:105] op_sel_hi:[0,1,1]
	v_pk_fma_f32 v[104:105], v[100:101], v[106:107], v[104:105] op_sel_hi:[0,1,1]
	v_lshlrev_b32_e32 v106, 16, v15
	v_and_b32_e32 v107, 0xffff0000, v15
	v_fma_f32 v15, -v7, v11, 1.0
	v_fmac_f32_e32 v11, v15, v11
	v_div_scale_f32 v15, vcc, 1.0, v3, 1.0
	v_pk_fma_f32 v[104:105], v[92:93], v[106:107], v[104:105] op_sel_hi:[0,1,1]
	v_lshlrev_b32_e32 v106, 16, v19
	v_and_b32_e32 v107, 0xffff0000, v19
	v_mul_f32_e32 v19, v15, v11
	v_fma_f32 v23, -v7, v19, v15
	v_fmac_f32_e32 v19, v23, v11
	v_pk_fma_f32 v[104:105], v[90:91], v[106:107], v[104:105] op_sel_hi:[0,1,1]
	v_fma_f32 v7, -v7, v19, v15
	v_pk_fma_f32 v[104:105], v[88:89], v[104:105], v[114:115] op_sel_hi:[0,1,1] neg_lo:[0,0,1] neg_hi:[0,0,1]
	v_div_fmas_f32 v7, v7, v11, v19
	s_waitcnt vmcnt(0)
	v_pk_mul_f32 v[104:105], v[104:105], v[74:75]
	v_div_fixup_f32 v3, v7, v3, 1.0
	v_lshlrev_b32_e32 v136, 16, v70
	v_pk_mul_f32 v[106:107], v[112:113], v[104:105]
	v_cndmask_b32_e64 v104, v224, v3, s[28:29]
	v_mul_f32_e32 v3, 0xbfb8aa3b, v136
	v_exp_f32_e32 v3, v3
	v_and_b32_e32 v137, 0xffff0000, v70
	v_cndmask_b32_e64 v108, 1.0, 0, s[16:17]
	v_cndmask_b32_e64 v110, 1.0, 0, s[18:19]
	v_add_f32_e32 v3, 1.0, v3
	v_rcp_f32_e32 v138, v3
	v_mul_f32_e32 v3, 0xbfb8aa3b, v137
	v_exp_f32_e32 v3, v3
	v_lshlrev_b32_e32 v128, 16, v58
	v_and_b32_e32 v129, 0xffff0000, v58
	v_cndmask_b32_e64 v114, 1.0, 0, s[20:21]
	v_add_f32_e32 v3, 1.0, v3
	v_rcp_f32_e32 v139, v3
	v_lshlrev_b32_e32 v130, 16, v62
	v_and_b32_e32 v131, 0xffff0000, v62
	v_lshlrev_b32_e32 v132, 16, v66
	v_pk_mul_f32 v[136:137], v[138:139], v[136:137]
	v_lshlrev_b32_e32 v138, 16, v38
	v_and_b32_e32 v139, 0xffff0000, v38
	v_pk_fma_f32 v[134:135], v[108:109], v[134:135], v[138:139] op_sel_hi:[0,1,1]
	v_pk_fma_f32 v[128:129], v[110:111], v[128:129], v[134:135] op_sel_hi:[0,1,1]
	v_and_b32_e32 v133, 0xffff0000, v66
	v_pk_fma_f32 v[128:129], v[114:115], v[130:131], v[128:129] op_sel_hi:[0,1,1]
	v_pk_fma_f32 v[128:129], v[118:119], v[132:133], v[128:129] op_sel_hi:[0,1,1]
	v_lshlrev_b32_e32 v130, 16, v42
	v_and_b32_e32 v131, 0xffff0000, v42
	v_pk_fma_f32 v[128:129], v[122:123], v[130:131], v[128:129] op_sel_hi:[0,1,1]
	v_lshlrev_b32_e32 v130, 16, v50
	v_and_b32_e32 v131, 0xffff0000, v50
	v_pk_fma_f32 v[128:129], v[124:125], v[130:131], v[128:129] op_sel_hi:[0,1,1]
	v_lshlrev_b32_e32 v130, 16, v54
	v_and_b32_e32 v131, 0xffff0000, v54
	v_pk_fma_f32 v[128:129], v[126:127], v[130:131], v[128:129] op_sel_hi:[0,1,1]
	v_pk_fma_f32 v[128:129], v[104:105], v[128:129], v[138:139] op_sel_hi:[0,1,1] neg_lo:[0,0,1] neg_hi:[0,0,1]
	v_pk_mul_f32 v[128:129], v[72:73], v[128:129]
	v_and_b32_e32 v11, 0xffff0000, v34
	v_pk_mul_f32 v[128:129], v[128:129], v[136:137]
	v_lshlrev_b32_e32 v136, 16, v10
	v_and_b32_e32 v137, 0xffff0000, v10
	v_lshlrev_b32_e32 v10, 16, v34
	v_mul_f32_e32 v3, 0xbfb8aa3b, v10
	v_exp_f32_e32 v3, v3
	v_lshlrev_b32_e32 v130, 16, v22
	v_and_b32_e32 v131, 0xffff0000, v22
	v_lshlrev_b32_e32 v132, 16, v26
	v_add_f32_e32 v3, 1.0, v3
	v_rcp_f32_e32 v22, v3
	v_mul_f32_e32 v3, 0xbfb8aa3b, v11
	v_exp_f32_e32 v3, v3
	v_and_b32_e32 v133, 0xffff0000, v26
	v_lshlrev_b32_e32 v134, 16, v30
	v_and_b32_e32 v135, 0xffff0000, v30
	v_add_f32_e32 v3, 1.0, v3
	v_rcp_f32_e32 v23, v3
	v_lshlrev_b32_e32 v26, 16, v6
	v_lshlrev_b32_e32 v6, 16, v14
	v_and_b32_e32 v7, 0xffff0000, v14
	v_pk_mul_f32 v[10:11], v[22:23], v[10:11]
	v_lshlrev_b32_e32 v22, 16, v2
	v_and_b32_e32 v23, 0xffff0000, v2
	v_pk_fma_f32 v[2:3], v[94:95], v[136:137], v[22:23] op_sel_hi:[0,1,1]
	v_pk_fma_f32 v[2:3], v[96:97], v[130:131], v[2:3] op_sel_hi:[0,1,1]
	v_pk_fma_f32 v[2:3], v[98:99], v[132:133], v[2:3] op_sel_hi:[0,1,1]
	v_pk_fma_f32 v[2:3], v[102:103], v[134:135], v[2:3] op_sel_hi:[0,1,1]
	v_pk_fma_f32 v[2:3], v[100:101], v[26:27], v[2:3] op_sel_hi:[0,1,1]
	v_pk_fma_f32 v[2:3], v[92:93], v[6:7], v[2:3] op_sel_hi:[0,1,1]
	v_lshlrev_b32_e32 v6, 16, v18
	v_and_b32_e32 v7, 0xffff0000, v18
	v_pk_fma_f32 v[2:3], v[90:91], v[6:7], v[2:3] op_sel_hi:[0,1,1]
	v_pk_fma_f32 v[2:3], v[88:89], v[2:3], v[22:23] op_sel_hi:[0,1,1] neg_lo:[0,0,1] neg_hi:[0,0,1]
	v_lshlrev_b32_e32 v22, 16, v69
	v_and_b32_e32 v23, 0xffff0000, v69
	v_mul_f32_e32 v26, 0xbfb8aa3b, v22
	v_mul_f32_e32 v27, 0xbfb8aa3b, v23
	v_exp_f32_e32 v26, v26
	v_exp_f32_e32 v27, v27
	v_lshlrev_b32_e32 v18, 16, v45
	v_and_b32_e32 v19, 0xffff0000, v45
	v_add_f32_e32 v26, 1.0, v26
	v_add_f32_e32 v27, 1.0, v27
	v_rcp_f32_e32 v26, v26
	v_rcp_f32_e32 v27, v27
	v_pk_mul_f32 v[2:3], v[2:3], v[72:73]
	v_lshlrev_b32_e32 v6, 16, v57
	v_and_b32_e32 v7, 0xffff0000, v57
	v_pk_mul_f32 v[22:23], v[26:27], v[22:23]
	v_lshlrev_b32_e32 v26, 16, v37
	v_and_b32_e32 v27, 0xffff0000, v37
	v_pk_fma_f32 v[18:19], v[108:109], v[18:19], v[26:27] op_sel_hi:[0,1,1]
	v_pk_mul_f32 v[2:3], v[10:11], v[2:3]
	v_lshlrev_b32_e32 v10, 16, v61
	v_and_b32_e32 v11, 0xffff0000, v61
	v_pk_fma_f32 v[6:7], v[110:111], v[6:7], v[18:19] op_sel_hi:[0,1,1]
	v_lshlrev_b32_e32 v14, 16, v65
; __device__ __forceinline__ float fsigmoid(float v) { return __builtin_amdgcn_rcpf(1.f + __builtin_amdgcn_exp2f(-v * LOG2E)); }
; __device__ __forceinline__ u32x4 pack8(const float (&f)[8]) { u32x4 w; w.x = cvtpk(f[0], f[1]); w.y = cvtpk(f[2], f[3]); w.z = cvtpk(f[4], f[5]); w.w = cvtpk(f[6], f[7]); return w; }
; template <int W, int NI> __device__ __forceinline__ void pool_items(bf16_t* PB, const float* pscale, const int (&rps)[NI], int g, int lane) {
;     ...
;     for (int q = 0; q < NI; ++q) {
;         float za[8], sum[8], x0[8]; unpack8(zw[q], za); unpack8(v[q][0], x0);
; #pragma unroll
;         for (int e = 0; e < 8; ++e) sum[e] = x0[e];
; #pragma unroll
;         for (int jj = 1; jj < W; ++jj) { float f[8]; unpack8(v[q][jj], f); const float mk = (jj <= t[q]) ? 1.f : 0.f;
; #pragma unroll
;             for (int e = 0; e < 8; ++e) sum[e] += mk * f[e]; }
;         const int cnt = (t[q] + 1 < W) ? (t[q] + 1) : W;
;         const float inv = 1.f / (float)cnt;
;         float y[8];
; #pragma unroll
;         for (int e = 0; e < 8; ++e) { const float ps = (e < 4) ? p0[e & 3] : p1[e & 3]; y[e] = (sum[e] * inv - x0[e]) * ps * (za[e] * fsigmoid(za[e])); }
;         outw[q] = pack8(y); }
	v_and_b32_e32 v15, 0xffff0000, v65
	v_pk_fma_f32 v[6:7], v[114:115], v[10:11], v[6:7] op_sel_hi:[0,1,1]
	v_pk_fma_f32 v[6:7], v[118:119], v[14:15], v[6:7] op_sel_hi:[0,1,1]
	v_lshlrev_b32_e32 v10, 16, v41
	v_and_b32_e32 v11, 0xffff0000, v41
	v_pk_fma_f32 v[6:7], v[122:123], v[10:11], v[6:7] op_sel_hi:[0,1,1]
	v_lshlrev_b32_e32 v10, 16, v49
	v_and_b32_e32 v11, 0xffff0000, v49
	v_pk_fma_f32 v[6:7], v[124:125], v[10:11], v[6:7] op_sel_hi:[0,1,1]
	v_lshlrev_b32_e32 v10, 16, v53
	v_and_b32_e32 v11, 0xffff0000, v53
	v_pk_fma_f32 v[6:7], v[126:127], v[10:11], v[6:7] op_sel_hi:[0,1,1]
	v_pk_fma_f32 v[6:7], v[104:105], v[6:7], v[26:27] op_sel_hi:[0,1,1] neg_lo:[0,0,1] neg_hi:[0,0,1]
	v_pk_mul_f32 v[6:7], v[78:79], v[6:7]
	v_lshlrev_b32_e32 v26, 16, v33
	v_pk_mul_f32 v[6:7], v[6:7], v[22:23]
	v_lshlrev_b32_e32 v22, 16, v9
	v_and_b32_e32 v23, 0xffff0000, v9
	v_mul_f32_e32 v9, 0xbfb8aa3b, v26
	v_exp_f32_e32 v9, v9
	v_and_b32_e32 v27, 0xffff0000, v33
	v_lshlrev_b32_e32 v10, 16, v21
	v_and_b32_e32 v11, 0xffff0000, v21
	v_add_f32_e32 v9, 1.0, v9
	v_rcp_f32_e32 v30, v9
	v_mul_f32_e32 v9, 0xbfb8aa3b, v27
	v_exp_f32_e32 v9, v9
	v_lshlrev_b32_e32 v14, 16, v25
	v_and_b32_e32 v15, 0xffff0000, v25
	v_lshlrev_b32_e32 v18, 16, v29
	v_add_f32_e32 v9, 1.0, v9
	v_rcp_f32_e32 v31, v9
	v_and_b32_e32 v19, 0xffff0000, v29
	v_and_b32_e32 v9, 0xffff0000, v32
	v_lshlrev_b32_e32 v112, 16, v59
	v_pk_mul_f32 v[26:27], v[30:31], v[26:27]
	v_lshlrev_b32_e32 v30, 16, v1
	v_and_b32_e32 v31, 0xffff0000, v1
	v_pk_fma_f32 v[22:23], v[94:95], v[22:23], v[30:31] op_sel_hi:[0,1,1]
	v_pk_fma_f32 v[10:11], v[96:97], v[10:11], v[22:23] op_sel_hi:[0,1,1]
	v_pk_fma_f32 v[10:11], v[98:99], v[14:15], v[10:11] op_sel_hi:[0,1,1]
	v_pk_fma_f32 v[10:11], v[102:103], v[18:19], v[10:11] op_sel_hi:[0,1,1]
	v_lshlrev_b32_e32 v14, 16, v5
	v_and_b32_e32 v15, 0xffff0000, v5
	v_pk_fma_f32 v[10:11], v[100:101], v[14:15], v[10:11] op_sel_hi:[0,1,1]
	v_lshlrev_b32_e32 v14, 16, v13
	v_and_b32_e32 v15, 0xffff0000, v13
	v_pk_fma_f32 v[10:11], v[92:93], v[14:15], v[10:11] op_sel_hi:[0,1,1]
	v_lshlrev_b32_e32 v14, 16, v17
	v_and_b32_e32 v15, 0xffff0000, v17
	v_pk_fma_f32 v[10:11], v[90:91], v[14:15], v[10:11] op_sel_hi:[0,1,1]
	v_pk_fma_f32 v[10:11], v[88:89], v[10:11], v[30:31] op_sel_hi:[0,1,1] neg_lo:[0,0,1] neg_hi:[0,0,1]
	v_lshlrev_b32_e32 v30, 16, v68
	v_mul_f32_e32 v1, 0xbfb8aa3b, v30
	v_exp_f32_e32 v1, v1
	v_and_b32_e32 v31, 0xffff0000, v68
	v_pk_mul_f32 v[10:11], v[10:11], v[78:79]
	v_lshlrev_b32_e32 v14, 16, v56
	v_add_f32_e32 v1, 1.0, v1
	v_rcp_f32_e32 v34, v1
	v_mul_f32_e32 v1, 0xbfb8aa3b, v31
	v_exp_f32_e32 v1, v1
	v_pk_mul_f32 v[10:11], v[26:27], v[10:11]
	v_lshlrev_b32_e32 v26, 16, v44
	v_and_b32_e32 v27, 0xffff0000, v44
	v_add_f32_e32 v1, 1.0, v1
	v_rcp_f32_e32 v35, v1
	v_and_b32_e32 v15, 0xffff0000, v56
	v_lshlrev_b32_e32 v18, 16, v60
	v_and_b32_e32 v19, 0xffff0000, v60
	v_pk_mul_f32 v[30:31], v[34:35], v[30:31]
	v_lshlrev_b32_e32 v34, 16, v36
	v_and_b32_e32 v35, 0xffff0000, v36
	v_pk_fma_f32 v[26:27], v[108:109], v[26:27], v[34:35] op_sel_hi:[0,1,1]
	v_pk_fma_f32 v[14:15], v[110:111], v[14:15], v[26:27] op_sel_hi:[0,1,1]
	v_lshlrev_b32_e32 v22, 16, v64
	v_and_b32_e32 v23, 0xffff0000, v64
	v_pk_fma_f32 v[14:15], v[114:115], v[18:19], v[14:15] op_sel_hi:[0,1,1]
	v_pk_fma_f32 v[14:15], v[118:119], v[22:23], v[14:15] op_sel_hi:[0,1,1]
	v_lshlrev_b32_e32 v18, 16, v40
	v_and_b32_e32 v19, 0xffff0000, v40
	v_pk_fma_f32 v[14:15], v[122:123], v[18:19], v[14:15] op_sel_hi:[0,1,1]
	v_lshlrev_b32_e32 v18, 16, v48
	v_and_b32_e32 v19, 0xffff0000, v48
	v_pk_fma_f32 v[14:15], v[124:125], v[18:19], v[14:15] op_sel_hi:[0,1,1]
	v_lshlrev_b32_e32 v18, 16, v52
	v_and_b32_e32 v19, 0xffff0000, v52
; __device__ __forceinline__ float fsigmoid(float v) { return __builtin_amdgcn_rcpf(1.f + __builtin_amdgcn_exp2f(-v * LOG2E)); }
; __device__ __forceinline__ u32x4 pack8(const float (&f)[8]) { u32x4 w; w.x = cvtpk(f[0], f[1]); w.y = cvtpk(f[2], f[3]); w.z = cvtpk(f[4], f[5]); w.w = cvtpk(f[6], f[7]); return w; }
; template <int W, int NI> __device__ __forceinline__ void pool_items(bf16_t* PB, const float* pscale, const int (&rps)[NI], int g, int lane) {
;     ...
;         for (int jj = 1; jj < W; ++jj) { float f[8]; unpack8(v[q][jj], f); const float mk = (jj <= t[q]) ? 1.f : 0.f;
; #pragma unroll
;             for (int e = 0; e < 8; ++e) sum[e] += mk * f[e]; }
;         const int cnt = (t[q] + 1 < W) ? (t[q] + 1) : W;
;         const float inv = 1.f / (float)cnt;
;         float y[8];
; #pragma unroll
;         for (int e = 0; e < 8; ++e) { const float ps = (e < 4) ? p0[e & 3] : p1[e & 3]; y[e] = (sum[e] * inv - x0[e]) * ps * (za[e] * fsigmoid(za[e])); }
;         outw[q] = pack8(y); }
; #pragma unroll
;     for (int q = 0; q < NI; ++q) *(u32x4*)zp[q] = outw[q];
	v_pk_fma_f32 v[14:15], v[126:127], v[18:19], v[14:15] op_sel_hi:[0,1,1]
	v_pk_fma_f32 v[14:15], v[104:105], v[14:15], v[34:35] op_sel_hi:[0,1,1] neg_lo:[0,0,1] neg_hi:[0,0,1]
	v_pk_mul_f32 v[14:15], v[76:77], v[14:15]
	v_lshlrev_b32_e32 v18, 16, v20
	v_pk_mul_f32 v[14:15], v[14:15], v[30:31]
	v_lshlrev_b32_e32 v30, 16, v8
	v_and_b32_e32 v31, 0xffff0000, v8
	v_lshlrev_b32_e32 v8, 16, v32
	v_mul_f32_e32 v1, 0xbfb8aa3b, v8
	v_exp_f32_e32 v1, v1
	v_and_b32_e32 v19, 0xffff0000, v20
	v_lshlrev_b32_e32 v22, 16, v24
	v_and_b32_e32 v23, 0xffff0000, v24
	v_add_f32_e32 v1, 1.0, v1
	v_rcp_f32_e32 v20, v1
	v_mul_f32_e32 v1, 0xbfb8aa3b, v9
	v_exp_f32_e32 v1, v1
	v_lshlrev_b32_e32 v26, 16, v28
	v_and_b32_e32 v27, 0xffff0000, v28
	v_and_b32_e32 v5, 0xffff0000, v12
	v_add_f32_e32 v1, 1.0, v1
	v_rcp_f32_e32 v21, v1
	v_and_b32_e32 v13, 0xffff0000, v39
	v_and_b32_e32 v113, 0xffff0000, v59
	v_lshlrev_b32_e32 v116, 16, v63
	v_pk_mul_f32 v[8:9], v[20:21], v[8:9]
	v_lshlrev_b32_e32 v20, 16, v0
	v_and_b32_e32 v21, 0xffff0000, v0
	v_pk_fma_f32 v[0:1], v[94:95], v[30:31], v[20:21] op_sel_hi:[0,1,1]
	v_pk_fma_f32 v[0:1], v[96:97], v[18:19], v[0:1] op_sel_hi:[0,1,1]
	v_pk_fma_f32 v[0:1], v[98:99], v[22:23], v[0:1] op_sel_hi:[0,1,1]
	v_pk_fma_f32 v[0:1], v[102:103], v[26:27], v[0:1] op_sel_hi:[0,1,1]
	v_lshlrev_b32_e32 v18, 16, v4
	v_and_b32_e32 v19, 0xffff0000, v4
	v_pk_fma_f32 v[0:1], v[100:101], v[18:19], v[0:1] op_sel_hi:[0,1,1]
	v_lshlrev_b32_e32 v4, 16, v12
	v_pk_fma_f32 v[0:1], v[92:93], v[4:5], v[0:1] op_sel_hi:[0,1,1]
	v_lshlrev_b32_e32 v4, 16, v16
	v_and_b32_e32 v5, 0xffff0000, v16
	v_pk_fma_f32 v[0:1], v[90:91], v[4:5], v[0:1] op_sel_hi:[0,1,1]
	v_pk_fma_f32 v[0:1], v[88:89], v[0:1], v[20:21] op_sel_hi:[0,1,1] neg_lo:[0,0,1] neg_hi:[0,0,1]
	v_pk_mul_f32 v[0:1], v[0:1], v[76:77]
	v_lshlrev_b32_e32 v4, 16, v47
	v_pk_mul_f32 v[0:1], v[8:9], v[0:1]
	v_lshlrev_b32_e32 v8, 16, v71
	v_and_b32_e32 v9, 0xffff0000, v71
	v_cvt_pk_bf16_f32 v0, v0, v1
	v_cvt_pk_bf16_f32 v1, v10, v11
	v_mul_f32_e32 v10, 0xbfb8aa3b, v8
	v_mul_f32_e32 v11, 0xbfb8aa3b, v9
	v_and_b32_e32 v5, 0xffff0000, v47
	v_exp_f32_e32 v10, v10
	v_lshlrev_b32_e32 v12, 16, v39
	v_exp_f32_e32 v11, v11
	v_pk_fma_f32 v[4:5], v[108:109], v[4:5], v[12:13] op_sel_hi:[0,1,1]
	v_and_b32_e32 v117, 0xffff0000, v63
	v_pk_fma_f32 v[4:5], v[110:111], v[112:113], v[4:5] op_sel_hi:[0,1,1]
	v_lshlrev_b32_e32 v120, 16, v67
	v_and_b32_e32 v121, 0xffff0000, v67
	v_pk_fma_f32 v[4:5], v[114:115], v[116:117], v[4:5] op_sel_hi:[0,1,1]
	v_add_f32_e32 v10, 1.0, v10
	v_pk_fma_f32 v[4:5], v[118:119], v[120:121], v[4:5] op_sel_hi:[0,1,1]
	v_lshlrev_b32_e32 v16, 16, v43
	v_and_b32_e32 v17, 0xffff0000, v43
	v_add_f32_e32 v11, 1.0, v11
	v_rcp_f32_e32 v10, v10
	v_pk_fma_f32 v[4:5], v[122:123], v[16:17], v[4:5] op_sel_hi:[0,1,1]
	v_lshlrev_b32_e32 v16, 16, v51
	v_and_b32_e32 v17, 0xffff0000, v51
	v_rcp_f32_e32 v11, v11
	v_pk_fma_f32 v[4:5], v[124:125], v[16:17], v[4:5] op_sel_hi:[0,1,1]
	v_lshlrev_b32_e32 v16, 16, v55
	v_and_b32_e32 v17, 0xffff0000, v55
	v_pk_fma_f32 v[4:5], v[126:127], v[16:17], v[4:5] op_sel_hi:[0,1,1]
	v_pk_fma_f32 v[4:5], v[104:105], v[4:5], v[12:13] op_sel_hi:[0,1,1] neg_lo:[0,0,1] neg_hi:[0,0,1]
	v_pk_mul_f32 v[4:5], v[74:75], v[4:5]
	v_pk_mul_f32 v[8:9], v[10:11], v[8:9]
	s_add_i32 s16, s35, s74
	s_add_i32 s2, s88, s34
	v_cvt_pk_bf16_f32 v2, v2, v3
	v_cvt_pk_bf16_f32 v3, v106, v107
	v_pk_mul_f32 v[8:9], v[4:5], v[8:9]
	v_add_u32_e32 v89, s87, v89
	s_cmpk_gt_i32 s2, 0x1fff
	v_cvt_pk_bf16_f32 v4, v14, v15
	v_cvt_pk_bf16_f32 v5, v6, v7
	v_cvt_pk_bf16_f32 v6, v128, v129
	v_cvt_pk_bf16_f32 v7, v8, v9
	global_store_dwordx4 v[84:85], v[0:3], off offset:3072 nt
	global_store_dwordx4 v[86:87], v[4:7], off offset:3072 nt
	s_cbranch_scc0 .LBB0_383
	s_add_i32 s16, s81, s34

; template <int W, int NI> __device__ __forceinline__ void pool_items(bf16_t* PB, const float* pscale, const int (&rps)[NI], int g, int lane) {
;     const int ch = g * 256 + (lane & 31) * 8;
;     u32x4 v[NI][W], zw[NI]; int t[NI]; bf16_t* zp[NI];
; #pragma unroll
;     for (int q = 0; q < NI; ++q) { const int row = 2 * rps[q] + (lane >> 5); t[q] = row & (SEQ - 1);
;         const bf16_t* xp = PB + (size_t)row * PBW + C_XA + ch;
; #pragma unroll
;         for (int jj = 0; jj < W; ++jj) { const int back = (jj <= t[q]) ? jj : 0; v[q][jj] = *(const u32x4*)(xp - (size_t)back * PBW); }
;         zp[q] = PB + (size_t)row * PBW + C_ZA + ch; zw[q] = *(const u32x4*)zp[q]; }
;     const f32x4 p0 = *(const f32x4*)(pscale + ch), p1 = *(const f32x4*)(pscale + ch + 4);
;     u32x4 outw[NI];
; #pragma unroll
;     for (int q = 0; q < NI; ++q) {
;         float za[8], sum[8], x0[8]; unpack8(zw[q], za); unpack8(v[q][0], x0);
; #pragma unroll
;         for (int e = 0; e < 8; ++e) sum[e] = x0[e];
; #pragma unroll
;         for (int jj = 1; jj < W; ++jj) { float f[8]; unpack8(v[q][jj], f); const float mk = (jj <= t[q]) ? 1.f : 0.f;
; #pragma unroll
;             for (int e = 0; e < 8; ++e) sum[e] += mk * f[e]; }
;         const int cnt = (t[q] + 1 < W) ? (t[q] + 1) : W;
;         const float inv = 1.f / (float)cnt;
.LBB0_387:
	v_mad_i64_i32 v[40:41], s[2:3], v42, s65, v[38:39]
	global_load_dwordx4 v[4:7], v[40:41], off offset:3072
	global_load_dwordx4 v[0:3], v[40:41], off offset:1024
	v_and_b32_e32 v43, 0xfff, v42
	v_cmp_eq_u32_e64 s[2:3], 0, v43
	v_cmp_gt_u32_e64 s[4:5], 2, v43
	v_cmp_gt_u32_e64 s[6:7], 3, v43
	v_cndmask_b32_e64 v9, -1, 0, s[2:3]
	v_cndmask_b32_e64 v8, v225, 0, s[2:3]
	v_cndmask_b32_e64 v13, -1, 0, s[4:5]
	v_cndmask_b32_e64 v12, v227, 0, s[4:5]
	v_lshl_add_u64 v[8:9], v[40:41], 0, v[8:9]
	v_lshl_add_u64 v[12:13], v[40:41], 0, v[12:13]
	v_cmp_gt_u32_e64 s[12:13], 6, v43
	global_load_dwordx4 v[8:11], v[8:9], off offset:1024
	v_cmp_gt_u32_e64 s[8:9], 4, v43
	global_load_dwordx4 v[16:19], v[12:13], off offset:1024
	v_cndmask_b32_e64 v13, -1, 0, s[6:7]
	v_cndmask_b32_e64 v12, v229, 0, s[6:7]
	v_cndmask_b32_e64 v21, -1, 0, s[12:13]
	v_cndmask_b32_e64 v20, v253, 0, s[12:13]
	v_lshl_add_u64 v[12:13], v[40:41], 0, v[12:13]
	v_lshl_add_u64 v[20:21], v[40:41], 0, v[20:21]
	global_load_dwordx4 v[28:31], v[12:13], off offset:1024
	v_cmp_gt_u32_e64 s[10:11], 5, v43
	global_load_dwordx4 v[20:23], v[20:21], off offset:1024
	v_cndmask_b32_e64 v13, -1, 0, s[8:9]
	v_cndmask_b32_e64 v12, v251, 0, s[8:9]
	v_lshl_add_u64 v[12:13], v[40:41], 0, v[12:13]
	global_load_dwordx4 v[32:35], v[12:13], off offset:1024
	v_cndmask_b32_e64 v13, -1, 0, s[10:11]
	v_cndmask_b32_e64 v12, v252, 0, s[10:11]
	v_lshl_add_u64 v[12:13], v[40:41], 0, v[12:13]
	global_load_dwordx4 v[12:15], v[12:13], off offset:1024
	v_cmp_gt_u32_e64 s[14:15], 7, v43
	v_add_u32_e32 v43, 1, v43
	v_cvt_f32_u32_e32 v43, v43
	v_cndmask_b32_e64 v25, -1, 0, s[14:15]
	v_cndmask_b32_e64 v24, v234, 0, s[14:15]
	v_lshl_add_u64 v[24:25], v[40:41], 0, v[24:25]
	global_load_dwordx4 v[24:27], v[24:25], off offset:1024
	s_nop 0
	global_load_dwordx4 v[44:47], v[36:37], off offset:2064
	global_load_dwordx4 v[48:51], v[36:37], off offset:2048
	v_div_scale_f32 v52, s[18:19], v43, v43, 1.0
	v_rcp_f32_e32 v53, v52
	v_cndmask_b32_e64 v60, 1.0, 0, s[6:7]
	v_cndmask_b32_e64 v64, 1.0, 0, s[8:9]
	v_cndmask_b32_e64 v68, 1.0, 0, s[10:11]
	v_fma_f32 v54, -v52, v53, 1.0
	v_fmac_f32_e32 v53, v54, v53
	v_div_scale_f32 v54, vcc, 1.0, v43, 1.0
	v_mul_f32_e32 v55, v54, v53
	v_fma_f32 v56, -v52, v55, v54
	v_fmac_f32_e32 v55, v56, v53
	v_fma_f32 v52, -v52, v55, v54
	v_cndmask_b32_e64 v54, 1.0, 0, s[2:3]
	v_cndmask_b32_e64 v56, 1.0, 0, s[4:5]
	v_div_fmas_f32 v52, v52, v53, v55
	v_cndmask_b32_e64 v70, 1.0, 0, s[12:13]
	v_div_fixup_f32 v43, v52, v43, 1.0
	v_cndmask_b32_e64 v72, 1.0, 0, s[14:15]
	v_cndmask_b32_e64 v52, v224, v43, s[14:15]
	s_add_i32 s16, s16, s74
	v_add_u32_e32 v42, s82, v42
	s_cmpk_gt_i32 s16, 0x1fff
	s_waitcnt vmcnt(10)
	v_lshlrev_b32_e32 v82, 16, v6
	v_and_b32_e32 v83, 0xffff0000, v6
	v_mul_f32_e32 v6, 0xbfb8aa3b, v82
	v_exp_f32_e32 v6, v6
	s_waitcnt vmcnt(8)
	v_lshlrev_b32_e32 v80, 16, v10
	v_add_f32_e32 v6, 1.0, v6
	v_rcp_f32_e32 v84, v6
	v_mul_f32_e32 v6, 0xbfb8aa3b, v83
	v_exp_f32_e32 v6, v6
	v_and_b32_e32 v81, 0xffff0000, v10
	s_waitcnt vmcnt(7)
	v_lshlrev_b32_e32 v74, 16, v18
	v_and_b32_e32 v75, 0xffff0000, v18
	v_add_f32_e32 v6, 1.0, v6
	v_rcp_f32_e32 v85, v6
	s_waitcnt vmcnt(6)
	v_lshlrev_b32_e32 v76, 16, v30
	v_and_b32_e32 v77, 0xffff0000, v30
	v_lshlrev_b32_e32 v6, 16, v7
	v_pk_mul_f32 v[82:83], v[84:85], v[82:83]
	v_lshlrev_b32_e32 v84, 16, v2
	v_and_b32_e32 v85, 0xffff0000, v2
	v_pk_fma_f32 v[80:81], v[54:55], v[80:81], v[84:85] op_sel_hi:[0,1,1]
	v_pk_fma_f32 v[74:75], v[56:57], v[74:75], v[80:81] op_sel_hi:[0,1,1]
	s_waitcnt vmcnt(4)
	v_lshlrev_b32_e32 v78, 16, v34
	v_and_b32_e32 v79, 0xffff0000, v34
	v_pk_fma_f32 v[74:75], v[60:61], v[76:77], v[74:75] op_sel_hi:[0,1,1]
	v_pk_fma_f32 v[74:75], v[64:65], v[78:79], v[74:75] op_sel_hi:[0,1,1]
	s_waitcnt vmcnt(3)
	v_lshlrev_b32_e32 v76, 16, v14
	v_and_b32_e32 v77, 0xffff0000, v14
	v_pk_fma_f32 v[74:75], v[68:69], v[76:77], v[74:75] op_sel_hi:[0,1,1]
	v_lshlrev_b32_e32 v76, 16, v22
	v_and_b32_e32 v77, 0xffff0000, v22
	v_pk_fma_f32 v[74:75], v[70:71], v[76:77], v[74:75] op_sel_hi:[0,1,1]
	s_waitcnt vmcnt(2)
	v_lshlrev_b32_e32 v76, 16, v26
	v_and_b32_e32 v77, 0xffff0000, v26
	v_pk_fma_f32 v[74:75], v[72:73], v[76:77], v[74:75] op_sel_hi:[0,1,1]
	v_pk_fma_f32 v[74:75], v[52:53], v[74:75], v[84:85] op_sel_hi:[0,1,1] neg_lo:[0,0,1] neg_hi:[0,0,1]
	s_waitcnt vmcnt(1)
; __device__ __forceinline__ float fsigmoid(float v) { return __builtin_amdgcn_rcpf(1.f + __builtin_amdgcn_exp2f(-v * LOG2E)); }
; __device__ __forceinline__ u32x4 pack8(const float (&f)[8]) { u32x4 w; w.x = cvtpk(f[0], f[1]); w.y = cvtpk(f[2], f[3]); w.z = cvtpk(f[4], f[5]); w.w = cvtpk(f[6], f[7]); return w; }
; template <int W, int NI> __device__ __forceinline__ void pool_items(bf16_t* PB, const float* pscale, const int (&rps)[NI], int g, int lane) {
;     ...
;         for (int jj = 1; jj < W; ++jj) { float f[8]; unpack8(v[q][jj], f); const float mk = (jj <= t[q]) ? 1.f : 0.f;
; #pragma unroll
;             for (int e = 0; e < 8; ++e) sum[e] += mk * f[e]; }
;         const int cnt = (t[q] + 1 < W) ? (t[q] + 1) : W;
;         const float inv = 1.f / (float)cnt;
;         float y[8];
; #pragma unroll
;         for (int e = 0; e < 8; ++e) { const float ps = (e < 4) ? p0[e & 3] : p1[e & 3]; y[e] = (sum[e] * inv - x0[e]) * ps * (za[e] * fsigmoid(za[e])); }
;         outw[q] = pack8(y); }
; #pragma unroll
;     for (int q = 0; q < NI; ++q) *(u32x4*)zp[q] = outw[q];
	v_pk_mul_f32 v[44:45], v[44:45], v[74:75]
	v_lshlrev_b32_e32 v80, 16, v9
	v_pk_mul_f32 v[44:45], v[82:83], v[44:45]
	v_lshlrev_b32_e32 v82, 16, v5
	v_mul_f32_e32 v2, 0xbfb8aa3b, v82
	v_exp_f32_e32 v2, v2
	v_and_b32_e32 v83, 0xffff0000, v5
	v_and_b32_e32 v81, 0xffff0000, v9
	v_lshlrev_b32_e32 v74, 16, v17
	v_add_f32_e32 v2, 1.0, v2
	v_rcp_f32_e32 v84, v2
	v_mul_f32_e32 v2, 0xbfb8aa3b, v83
	v_exp_f32_e32 v2, v2
	v_and_b32_e32 v75, 0xffff0000, v17
	v_and_b32_e32 v9, 0xffff0000, v4
	v_lshlrev_b32_e32 v76, 16, v29
	v_add_f32_e32 v2, 1.0, v2
	v_rcp_f32_e32 v85, v2
	v_and_b32_e32 v77, 0xffff0000, v29
	v_lshlrev_b32_e32 v78, 16, v33
	v_and_b32_e32 v79, 0xffff0000, v33
	v_pk_mul_f32 v[82:83], v[84:85], v[82:83]
	v_lshlrev_b32_e32 v84, 16, v1
	v_and_b32_e32 v85, 0xffff0000, v1
	v_pk_fma_f32 v[80:81], v[54:55], v[80:81], v[84:85] op_sel_hi:[0,1,1]
	v_pk_fma_f32 v[74:75], v[56:57], v[74:75], v[80:81] op_sel_hi:[0,1,1]
	v_lshlrev_b32_e32 v80, 16, v8
	v_and_b32_e32 v81, 0xffff0000, v8
	v_lshlrev_b32_e32 v8, 16, v4
	v_mul_f32_e32 v1, 0xbfb8aa3b, v8
	v_exp_f32_e32 v1, v1
	v_pk_fma_f32 v[74:75], v[60:61], v[76:77], v[74:75] op_sel_hi:[0,1,1]
	v_pk_fma_f32 v[74:75], v[64:65], v[78:79], v[74:75] op_sel_hi:[0,1,1]
	v_lshlrev_b32_e32 v76, 16, v13
	v_add_f32_e32 v1, 1.0, v1
	v_rcp_f32_e32 v4, v1
	v_mul_f32_e32 v1, 0xbfb8aa3b, v9
	v_exp_f32_e32 v1, v1
	v_and_b32_e32 v77, 0xffff0000, v13
	v_pk_fma_f32 v[74:75], v[68:69], v[76:77], v[74:75] op_sel_hi:[0,1,1]
	v_lshlrev_b32_e32 v76, 16, v21
	v_add_f32_e32 v1, 1.0, v1
	v_rcp_f32_e32 v5, v1
	v_and_b32_e32 v77, 0xffff0000, v21
	v_pk_fma_f32 v[74:75], v[70:71], v[76:77], v[74:75] op_sel_hi:[0,1,1]
	v_lshlrev_b32_e32 v76, 16, v25
	v_and_b32_e32 v77, 0xffff0000, v25
	v_pk_fma_f32 v[74:75], v[72:73], v[76:77], v[74:75] op_sel_hi:[0,1,1]
	v_pk_fma_f32 v[74:75], v[52:53], v[74:75], v[84:85] op_sel_hi:[0,1,1] neg_lo:[0,0,1] neg_hi:[0,0,1]
	v_pk_mul_f32 v[4:5], v[4:5], v[8:9]
	v_lshlrev_b32_e32 v8, 16, v0
	v_and_b32_e32 v9, 0xffff0000, v0
	s_waitcnt vmcnt(0)
	v_pk_mul_f32 v[50:51], v[50:51], v[74:75]
	v_lshlrev_b32_e32 v74, 16, v16
	v_and_b32_e32 v75, 0xffff0000, v16
	v_pk_fma_f32 v[0:1], v[54:55], v[80:81], v[8:9] op_sel_hi:[0,1,1]
	v_lshlrev_b32_e32 v76, 16, v28
	v_and_b32_e32 v77, 0xffff0000, v28
	v_pk_fma_f32 v[0:1], v[56:57], v[74:75], v[0:1] op_sel_hi:[0,1,1]
	v_lshlrev_b32_e32 v78, 16, v32
	v_and_b32_e32 v79, 0xffff0000, v32
	v_pk_fma_f32 v[0:1], v[60:61], v[76:77], v[0:1] op_sel_hi:[0,1,1]
	v_pk_fma_f32 v[0:1], v[64:65], v[78:79], v[0:1] op_sel_hi:[0,1,1]
	v_lshlrev_b32_e32 v16, 16, v12
	v_and_b32_e32 v17, 0xffff0000, v12
	v_pk_fma_f32 v[0:1], v[68:69], v[16:17], v[0:1] op_sel_hi:[0,1,1]
	v_lshlrev_b32_e32 v12, 16, v20
	v_and_b32_e32 v13, 0xffff0000, v20
	v_pk_fma_f32 v[0:1], v[70:71], v[12:13], v[0:1] op_sel_hi:[0,1,1]
	v_lshlrev_b32_e32 v12, 16, v24
	v_and_b32_e32 v13, 0xffff0000, v24
	v_pk_fma_f32 v[0:1], v[72:73], v[12:13], v[0:1] op_sel_hi:[0,1,1]
	v_pk_fma_f32 v[0:1], v[52:53], v[0:1], v[8:9] op_sel_hi:[0,1,1] neg_lo:[0,0,1] neg_hi:[0,0,1]
	v_and_b32_e32 v7, 0xffff0000, v7
	v_pk_mul_f32 v[0:1], v[48:49], v[0:1]
	v_mul_f32_e32 v2, 0xbfb8aa3b, v6
	v_lshlrev_b32_e32 v8, 16, v3
	v_and_b32_e32 v9, 0xffff0000, v3
	v_mul_f32_e32 v3, 0xbfb8aa3b, v7
	v_pk_mul_f32 v[0:1], v[4:5], v[0:1]
	v_lshlrev_b32_e32 v4, 16, v11
	v_and_b32_e32 v5, 0xffff0000, v11
	v_exp_f32_e32 v2, v2
	v_exp_f32_e32 v3, v3
	v_lshlrev_b32_e32 v58, 16, v19
	v_and_b32_e32 v59, 0xffff0000, v19
	v_pk_fma_f32 v[4:5], v[54:55], v[4:5], v[8:9] op_sel_hi:[0,1,1]
	v_lshlrev_b32_e32 v62, 16, v31
	v_and_b32_e32 v63, 0xffff0000, v31
	v_pk_fma_f32 v[4:5], v[56:57], v[58:59], v[4:5] op_sel_hi:[0,1,1]
	v_lshlrev_b32_e32 v66, 16, v35
	v_and_b32_e32 v67, 0xffff0000, v35
	v_pk_fma_f32 v[4:5], v[60:61], v[62:63], v[4:5] op_sel_hi:[0,1,1]
	v_add_f32_e32 v2, 1.0, v2
	v_pk_fma_f32 v[4:5], v[64:65], v[66:67], v[4:5] op_sel_hi:[0,1,1]
	v_lshlrev_b32_e32 v10, 16, v15
	v_and_b32_e32 v11, 0xffff0000, v15
	v_add_f32_e32 v3, 1.0, v3
	v_rcp_f32_e32 v2, v2
	v_pk_fma_f32 v[4:5], v[68:69], v[10:11], v[4:5] op_sel_hi:[0,1,1]
	v_lshlrev_b32_e32 v10, 16, v23
	v_and_b32_e32 v11, 0xffff0000, v23
	v_rcp_f32_e32 v3, v3
	v_pk_fma_f32 v[4:5], v[70:71], v[10:11], v[4:5] op_sel_hi:[0,1,1]
	v_lshlrev_b32_e32 v10, 16, v27
	v_and_b32_e32 v11, 0xffff0000, v27
	v_pk_fma_f32 v[4:5], v[72:73], v[10:11], v[4:5] op_sel_hi:[0,1,1]
	v_pk_fma_f32 v[4:5], v[52:53], v[4:5], v[8:9] op_sel_hi:[0,1,1] neg_lo:[0,0,1] neg_hi:[0,0,1]
	v_pk_mul_f32 v[4:5], v[46:47], v[4:5]
	v_pk_mul_f32 v[2:3], v[2:3], v[6:7]
	v_pk_mul_f32 v[50:51], v[82:83], v[50:51]
	v_pk_mul_f32 v[4:5], v[2:3], v[4:5]
	v_cvt_pk_bf16_f32 v0, v0, v1
	v_cvt_pk_bf16_f32 v1, v50, v51
	v_cvt_pk_bf16_f32 v2, v44, v45
	v_cvt_pk_bf16_f32 v3, v4, v5
	global_store_dwordx4 v[40:41], v[0:3], off offset:3072 nt
	s_cbranch_scc0 .LBB0_387

; template <int W, int NI> __device__ __forceinline__ void pool_items(bf16_t* PB, const float* pscale, const int (&rps)[NI], int g, int lane) {
;     const int ch = g * 256 + (lane & 31) * 8;
;     u32x4 v[NI][W], zw[NI]; int t[NI]; bf16_t* zp[NI];
; #pragma unroll
;     for (int q = 0; q < NI; ++q) { const int row = 2 * rps[q] + (lane >> 5); t[q] = row & (SEQ - 1);
;         const bf16_t* xp = PB + (size_t)row * PBW + C_XA + ch;
; #pragma unroll
;         for (int jj = 0; jj < W; ++jj) { const int back = (jj <= t[q]) ? jj : 0; v[q][jj] = *(const u32x4*)(xp - (size_t)back * PBW); }
;         zp[q] = PB + (size_t)row * PBW + C_ZA + ch; zw[q] = *(const u32x4*)zp[q]; }
;     const f32x4 p0 = *(const f32x4*)(pscale + ch), p1 = *(const f32x4*)(pscale + ch + 4);
.LBB0_390:
	v_and_b32_e32 v152, 0xfff, v169
	v_mad_i64_i32 v[148:149], s[2:3], v169, s65, v[146:147]
	v_cmp_eq_u32_e64 s[2:3], 0, v152
	v_cmp_gt_u32_e64 s[4:5], 2, v152
	global_load_dwordx4 v[88:91], v[148:149], off offset:1536
	v_cndmask_b32_e64 v1, -1, 0, s[2:3]
	v_cndmask_b32_e64 v0, v225, 0, s[2:3]
	v_lshl_add_u64 v[0:1], v[148:149], 0, v[0:1]
	global_load_dwordx4 v[116:119], v[0:1], off offset:1536
	v_cndmask_b32_e64 v1, -1, 0, s[4:5]
	v_cndmask_b32_e64 v0, v227, 0, s[4:5]
	v_lshl_add_u64 v[0:1], v[148:149], 0, v[0:1]
	v_cmp_gt_u32_e64 s[6:7], 3, v152
	global_load_dwordx4 v[44:47], v[0:1], off offset:1536
	v_cmp_gt_u32_e64 s[8:9], 4, v152
	v_cndmask_b32_e64 v1, -1, 0, s[6:7]
	v_cndmask_b32_e64 v0, v229, 0, s[6:7]
	v_lshl_add_u64 v[0:1], v[148:149], 0, v[0:1]
	global_load_dwordx4 v[48:51], v[0:1], off offset:1536
	v_cndmask_b32_e64 v1, -1, 0, s[8:9]
	v_cndmask_b32_e64 v0, v251, 0, s[8:9]
	v_lshl_add_u64 v[0:1], v[148:149], 0, v[0:1]
	v_cmp_gt_u32_e64 s[10:11], 5, v152
	global_load_dwordx4 v[64:67], v[0:1], off offset:1536
	v_cmp_gt_u32_e64 s[12:13], 6, v152
	v_cndmask_b32_e64 v1, -1, 0, s[10:11]
	v_cndmask_b32_e64 v0, v252, 0, s[10:11]
	v_lshl_add_u64 v[0:1], v[148:149], 0, v[0:1]
	global_load_dwordx4 v[68:71], v[0:1], off offset:1536
	v_cndmask_b32_e64 v1, -1, 0, s[12:13]
	v_cndmask_b32_e64 v0, v253, 0, s[12:13]
	v_lshl_add_u64 v[0:1], v[148:149], 0, v[0:1]
	v_cmp_gt_u32_e64 s[14:15], 7, v152
	global_load_dwordx4 v[72:75], v[0:1], off offset:1536
	v_cmp_gt_u32_e64 s[16:17], 8, v152
	v_cndmask_b32_e64 v1, -1, 0, s[14:15]
	v_cndmask_b32_e64 v0, v234, 0, s[14:15]
	v_lshl_add_u64 v[0:1], v[148:149], 0, v[0:1]
	global_load_dwordx4 v[76:79], v[0:1], off offset:1536
	v_cndmask_b32_e64 v1, -1, 0, s[16:17]
	v_cndmask_b32_e64 v0, v235, 0, s[16:17]
	v_lshl_add_u64 v[0:1], v[148:149], 0, v[0:1]
	v_cmp_gt_u32_e64 s[18:19], 9, v152
	global_load_dwordx4 v[80:83], v[0:1], off offset:1536
	v_cmp_gt_u32_e64 s[20:21], 10, v152
	v_cndmask_b32_e64 v1, -1, 0, s[18:19]
	v_cndmask_b32_e64 v0, v236, 0, s[18:19]
	v_lshl_add_u64 v[0:1], v[148:149], 0, v[0:1]
	global_load_dwordx4 v[120:123], v[0:1], off offset:1536
	v_cndmask_b32_e64 v1, -1, 0, s[20:21]
	v_cndmask_b32_e64 v0, v240, 0, s[20:21]
	v_lshl_add_u64 v[0:1], v[148:149], 0, v[0:1]
	v_cmp_gt_u32_e64 s[22:23], 11, v152
	global_load_dwordx4 v[124:127], v[0:1], off offset:1536
	v_cmp_gt_u32_e64 s[24:25], 12, v152
	v_cndmask_b32_e64 v1, -1, 0, s[22:23]
	v_cndmask_b32_e64 v0, v241, 0, s[22:23]
	v_lshl_add_u64 v[0:1], v[148:149], 0, v[0:1]
	global_load_dwordx4 v[128:131], v[0:1], off offset:1536
	v_cndmask_b32_e64 v1, -1, 0, s[24:25]
	v_cndmask_b32_e64 v0, v242, 0, s[24:25]
	v_lshl_add_u64 v[0:1], v[148:149], 0, v[0:1]
	v_cmp_gt_u32_e64 s[26:27], 13, v152
	global_load_dwordx4 v[132:135], v[0:1], off offset:1536
	v_cmp_gt_u32_e64 s[28:29], 14, v152
	v_cndmask_b32_e64 v1, -1, 0, s[26:27]
	v_cndmask_b32_e64 v0, v226, 0, s[26:27]
	v_lshl_add_u64 v[0:1], v[148:149], 0, v[0:1]
	global_load_dwordx4 v[52:55], v[0:1], off offset:1536
	v_cndmask_b32_e64 v1, -1, 0, s[28:29]
	v_cndmask_b32_e64 v0, v228, 0, s[28:29]
	v_lshl_add_u64 v[0:1], v[148:149], 0, v[0:1]
	v_cmp_gt_u32_e64 s[30:31], 15, v152
	global_load_dwordx4 v[56:59], v[0:1], off offset:1536
	v_add_u32_e32 v152, 1, v152
	v_cndmask_b32_e64 v1, -1, 0, s[30:31]
	v_cndmask_b32_e64 v0, v230, 0, s[30:31]
	v_lshl_add_u64 v[0:1], v[148:149], 0, v[0:1]
	global_load_dwordx4 v[60:63], v[0:1], off offset:1536
	global_load_dwordx4 v[92:95], v[148:149], off offset:3584
	v_lshl_add_u32 v0, s33, 1, v165
	v_and_b32_e32 v162, 0xfff, v0
	v_mad_i64_i32 v[150:151], s[34:35], v0, s65, v[146:147]
	v_cmp_eq_u32_e64 s[34:35], 0, v162
	v_cmp_gt_u32_e64 s[50:51], 9, v162
	v_cmp_gt_u32_e64 s[36:37], 2, v162
	v_cndmask_b32_e64 v1, -1, 0, s[34:35]
	v_cndmask_b32_e64 v0, v225, 0, s[34:35]
	v_cndmask_b32_e64 v13, -1, 0, s[50:51]
	v_cndmask_b32_e64 v12, v236, 0, s[50:51]
	v_lshl_add_u64 v[0:1], v[150:151], 0, v[0:1]
	v_lshl_add_u64 v[12:13], v[150:151], 0, v[12:13]
	v_cmp_gt_u32_e64 s[52:53], 10, v162
	global_load_dwordx4 v[96:99], v[0:1], off offset:1536
	global_load_dwordx4 v[100:103], v[12:13], off offset:1536
	v_cndmask_b32_e64 v1, -1, 0, s[36:37]
	v_cndmask_b32_e64 v0, v227, 0, s[36:37]
	v_cndmask_b32_e64 v13, -1, 0, s[52:53]
	v_cndmask_b32_e64 v12, v240, 0, s[52:53]
	v_lshl_add_u64 v[0:1], v[150:151], 0, v[0:1]
	v_cmp_gt_u32_e64 s[38:39], 3, v162
	v_lshl_add_u64 v[12:13], v[150:151], 0, v[12:13]
	v_cmp_gt_u32_e64 s[54:55], 11, v162
	global_load_dwordx4 v[24:27], v[0:1], off offset:1536
	global_load_dwordx4 v[104:107], v[12:13], off offset:1536
	v_cndmask_b32_e64 v1, -1, 0, s[38:39]
	v_cndmask_b32_e64 v0, v229, 0, s[38:39]
	v_cndmask_b32_e64 v13, -1, 0, s[54:55]
	v_cndmask_b32_e64 v12, v241, 0, s[54:55]
	v_lshl_add_u64 v[0:1], v[150:151], 0, v[0:1]
	v_cmp_gt_u32_e64 s[40:41], 4, v162
	v_lshl_add_u64 v[12:13], v[150:151], 0, v[12:13]
	v_cmp_gt_u32_e64 s[56:57], 12, v162
	global_load_dwordx4 v[32:35], v[0:1], off offset:1536
	global_load_dwordx4 v[108:111], v[12:13], off offset:1536
	v_cndmask_b32_e64 v1, -1, 0, s[40:41]
	v_cndmask_b32_e64 v0, v251, 0, s[40:41]
	v_cndmask_b32_e64 v13, -1, 0, s[56:57]
	v_cndmask_b32_e64 v12, v242, 0, s[56:57]
	v_lshl_add_u64 v[0:1], v[150:151], 0, v[0:1]
	v_cmp_gt_u32_e64 s[42:43], 5, v162
	v_lshl_add_u64 v[12:13], v[150:151], 0, v[12:13]
	v_cmp_gt_u32_e64 s[58:59], 13, v162
	global_load_dwordx4 v[28:31], v[0:1], off offset:1536
	global_load_dwordx4 v[112:115], v[12:13], off offset:1536
	v_cndmask_b32_e64 v1, -1, 0, s[42:43]
	v_cndmask_b32_e64 v0, v252, 0, s[42:43]
	v_cndmask_b32_e64 v13, -1, 0, s[58:59]
	v_cndmask_b32_e64 v12, v226, 0, s[58:59]
; __device__ __forceinline__ float fsigmoid(float v) { return __builtin_amdgcn_rcpf(1.f + __builtin_amdgcn_exp2f(-v * LOG2E)); }
; template <int W, int NI> __device__ __forceinline__ void pool_items(bf16_t* PB, const float* pscale, const int (&rps)[NI], int g, int lane) {
;     ...
;     for (int q = 0; q < NI; ++q) { const int row = 2 * rps[q] + (lane >> 5); t[q] = row & (SEQ - 1);
;         const bf16_t* xp = PB + (size_t)row * PBW + C_XA + ch;
; #pragma unroll
;         for (int jj = 0; jj < W; ++jj) { const int back = (jj <= t[q]) ? jj : 0; v[q][jj] = *(const u32x4*)(xp - (size_t)back * PBW); }
;         zp[q] = PB + (size_t)row * PBW + C_ZA + ch; zw[q] = *(const u32x4*)zp[q]; }
;     const f32x4 p0 = *(const f32x4*)(pscale + ch), p1 = *(const f32x4*)(pscale + ch + 4);
;     u32x4 outw[NI];
; #pragma unroll
;     for (int q = 0; q < NI; ++q) {
;         float za[8], sum[8], x0[8]; unpack8(zw[q], za); unpack8(v[q][0], x0);
; #pragma unroll
;         for (int e = 0; e < 8; ++e) sum[e] = x0[e];
; #pragma unroll
;         for (int jj = 1; jj < W; ++jj) { float f[8]; unpack8(v[q][jj], f); const float mk = (jj <= t[q]) ? 1.f : 0.f;
; #pragma unroll
;             for (int e = 0; e < 8; ++e) sum[e] += mk * f[e]; }
;         const int cnt = (t[q] + 1 < W) ? (t[q] + 1) : W;
;         const float inv = 1.f / (float)cnt;
;         float y[8];
; #pragma unroll
;         for (int e = 0; e < 8; ++e) { const float ps = (e < 4) ? p0[e & 3] : p1[e & 3]; y[e] = (sum[e] * inv - x0[e]) * ps * (za[e] * fsigmoid(za[e])); }
	v_lshl_add_u64 v[0:1], v[150:151], 0, v[0:1]
	v_cmp_gt_u32_e64 s[44:45], 6, v162
	v_lshl_add_u64 v[12:13], v[150:151], 0, v[12:13]
	v_cmp_gt_u32_e64 s[60:61], 14, v162
	global_load_dwordx4 v[20:23], v[0:1], off offset:1536
	global_load_dwordx4 v[36:39], v[12:13], off offset:1536
	v_cndmask_b32_e64 v1, -1, 0, s[44:45]
	v_cndmask_b32_e64 v0, v253, 0, s[44:45]
	v_cndmask_b32_e64 v13, -1, 0, s[60:61]
	v_cndmask_b32_e64 v12, v228, 0, s[60:61]
	v_lshl_add_u64 v[0:1], v[150:151], 0, v[0:1]
	v_cmp_gt_u32_e64 s[46:47], 7, v162
	v_lshl_add_u64 v[12:13], v[150:151], 0, v[12:13]
	global_load_dwordx4 v[8:11], v[0:1], off offset:1536
	global_load_dwordx4 v[16:19], v[12:13], off offset:1536
	v_cndmask_b32_e64 v1, -1, 0, s[46:47]
	v_cndmask_b32_e64 v0, v234, 0, s[46:47]
	v_lshl_add_u64 v[0:1], v[150:151], 0, v[0:1]
	v_cmp_gt_u32_e64 s[48:49], 8, v162
	v_cmp_gt_u32_e64 s[62:63], 15, v162
	global_load_dwordx4 v[84:87], v[150:151], off offset:1536
	global_load_dwordx4 v[4:7], v[0:1], off offset:1536
	v_cndmask_b32_e64 v1, -1, 0, s[48:49]
	v_cndmask_b32_e64 v0, v235, 0, s[48:49]
	v_cndmask_b32_e64 v13, -1, 0, s[62:63]
	v_cndmask_b32_e64 v12, v230, 0, s[62:63]
	v_lshl_add_u64 v[0:1], v[150:151], 0, v[0:1]
	v_lshl_add_u64 v[12:13], v[150:151], 0, v[12:13]
	global_load_dwordx4 v[0:3], v[0:1], off offset:1536
	s_nop 0
	global_load_dwordx4 v[12:15], v[12:13], off offset:1536
	s_nop 0
	global_load_dwordx4 v[136:139], v[150:151], off offset:3584
	global_load_dwordx4 v[140:143], v[144:145], off offset:3072
	global_load_dwordx4 v[40:43], v[144:145], off offset:3088
	v_cvt_f32_u32_e32 v152, v152
	s_waitcnt vmcnt(19)
	v_lshlrev_b32_e32 v170, 16, v95
	v_and_b32_e32 v171, 0xffff0000, v95
	v_mul_f32_e32 v95, 0xbfb8aa3b, v170
	v_div_scale_f32 v153, s[66:67], v152, v152, 1.0
	v_rcp_f32_e32 v154, v153
	v_lshlrev_b32_e32 v174, 16, v91
	v_and_b32_e32 v175, 0xffff0000, v91
	v_mul_f32_e32 v91, 0xbfb8aa3b, v171
	v_fma_f32 v155, -v153, v154, 1.0
	v_exp_f32_e32 v95, v95
	v_exp_f32_e32 v91, v91
	v_fmac_f32_e32 v154, v155, v154
	v_div_scale_f32 v155, vcc, 1.0, v152, 1.0
	v_mul_f32_e32 v156, v155, v154
	v_fma_f32 v157, -v153, v156, v155
	v_fmac_f32_e32 v156, v157, v154
	v_add_f32_e32 v95, 1.0, v95
	v_add_f32_e32 v91, 1.0, v91
	v_fma_f32 v153, -v153, v156, v155
	v_rcp_f32_e32 v172, v95
	v_rcp_f32_e32 v173, v91
	v_div_fmas_f32 v153, v153, v154, v156
	v_div_fixup_f32 v152, v153, v152, 1.0
	v_cndmask_b32_e64 v194, v244, v152, s[30:31]
	v_cndmask_b32_e64 v206, 1.0, 0, s[2:3]
	v_lshlrev_b32_e32 v152, 16, v119
	v_and_b32_e32 v153, 0xffff0000, v119
	v_cndmask_b32_e64 v210, 1.0, 0, s[4:5]
	v_pk_mul_f32 v[170:171], v[172:173], v[170:171]
	v_lshlrev_b32_e32 v172, 16, v47
	v_and_b32_e32 v173, 0xffff0000, v47
	v_pk_fma_f32 v[152:153], v[206:207], v[152:153], v[174:175] op_sel_hi:[0,1,1]
	v_cndmask_b32_e64 v212, 1.0, 0, s[6:7]
	v_lshlrev_b32_e32 v176, 16, v51
	v_and_b32_e32 v177, 0xffff0000, v51
	v_pk_fma_f32 v[152:153], v[210:211], v[172:173], v[152:153] op_sel_hi:[0,1,1]
	v_cndmask_b32_e64 v214, 1.0, 0, s[8:9]
	v_lshlrev_b32_e32 v178, 16, v67
	v_and_b32_e32 v179, 0xffff0000, v67
	v_pk_fma_f32 v[152:153], v[212:213], v[176:177], v[152:153] op_sel_hi:[0,1,1]
	v_cndmask_b32_e64 v216, 1.0, 0, s[10:11]
	v_lshlrev_b32_e32 v180, 16, v71
	v_and_b32_e32 v181, 0xffff0000, v71
	v_pk_fma_f32 v[152:153], v[214:215], v[178:179], v[152:153] op_sel_hi:[0,1,1]
	v_add_u32_e32 v47, 1, v162
	v_cndmask_b32_e64 v218, 1.0, 0, s[12:13]
	v_lshlrev_b32_e32 v182, 16, v75
	v_and_b32_e32 v183, 0xffff0000, v75
	v_pk_fma_f32 v[152:153], v[216:217], v[180:181], v[152:153] op_sel_hi:[0,1,1]
	v_cvt_f32_u32_e32 v47, v47
	v_cndmask_b32_e64 v220, 1.0, 0, s[14:15]
	v_lshlrev_b32_e32 v184, 16, v79
	v_and_b32_e32 v185, 0xffff0000, v79
	v_pk_fma_f32 v[152:153], v[218:219], v[182:183], v[152:153] op_sel_hi:[0,1,1]
	v_cndmask_b32_e64 v222, 1.0, 0, s[16:17]
	v_lshlrev_b32_e32 v186, 16, v83
	v_and_b32_e32 v187, 0xffff0000, v83
	v_pk_fma_f32 v[152:153], v[220:221], v[184:185], v[152:153] op_sel_hi:[0,1,1]
	v_cndmask_b32_e64 v208, 1.0, 0, s[18:19]
	v_lshlrev_b32_e32 v160, 16, v123
	v_and_b32_e32 v161, 0xffff0000, v123
	v_pk_fma_f32 v[152:153], v[222:223], v[186:187], v[152:153] op_sel_hi:[0,1,1]
	v_cndmask_b32_e64 v224, 1.0, 0, s[20:21]
	v_lshlrev_b32_e32 v154, 16, v127
	v_and_b32_e32 v155, 0xffff0000, v127
	v_pk_fma_f32 v[152:153], v[208:209], v[160:161], v[152:153] op_sel_hi:[0,1,1]
	v_div_scale_f32 v51, s[2:3], v47, v47, 1.0
	v_pk_fma_f32 v[152:153], v[224:225], v[154:155], v[152:153] op_sel_hi:[0,1,1]
	v_lshlrev_b32_e32 v154, 16, v55
	v_and_b32_e32 v155, 0xffff0000, v55
	v_rcp_f32_e32 v55, v51
	v_mov_b32_e32 v191, v226
	v_cndmask_b32_e64 v226, 1.0, 0, s[22:23]
	v_lshlrev_b32_e32 v156, 16, v131
	v_and_b32_e32 v157, 0xffff0000, v131
	v_mov_b32_e32 v193, v228
	v_cndmask_b32_e64 v228, 1.0, 0, s[24:25]
	v_lshlrev_b32_e32 v158, 16, v135
	v_and_b32_e32 v159, 0xffff0000, v135
	v_pk_fma_f32 v[152:153], v[226:227], v[156:157], v[152:153] op_sel_hi:[0,1,1]
	v_cndmask_b32_e64 v204, 1.0, 0, s[26:27]
	v_pk_fma_f32 v[152:153], v[228:229], v[158:159], v[152:153] op_sel_hi:[0,1,1]
	v_pk_fma_f32 v[152:153], v[204:205], v[154:155], v[152:153] op_sel_hi:[0,1,1]
	v_lshlrev_b32_e32 v154, 16, v59
	v_and_b32_e32 v155, 0xffff0000, v59
	v_fma_f32 v59, -v51, v55, 1.0
	v_cndmask_b32_e64 v202, 1.0, 0, s[28:29]
	v_fmac_f32_e32 v55, v59, v55
	v_div_scale_f32 v59, vcc, 1.0, v47, 1.0
	v_pk_fma_f32 v[152:153], v[202:203], v[154:155], v[152:153] op_sel_hi:[0,1,1]
	v_lshlrev_b32_e32 v154, 16, v63
	v_and_b32_e32 v155, 0xffff0000, v63
	v_mul_f32_e32 v63, v59, v55
	v_fma_f32 v67, -v51, v63, v59
	v_cndmask_b32_e64 v200, 1.0, 0, s[30:31]
	v_fmac_f32_e32 v63, v67, v55
	v_pk_fma_f32 v[152:153], v[200:201], v[154:155], v[152:153] op_sel_hi:[0,1,1]
	v_fma_f32 v51, -v51, v63, v59
	v_pk_fma_f32 v[152:153], v[194:195], v[152:153], v[174:175] op_sel_hi:[0,1,1] neg_lo:[0,0,1] neg_hi:[0,0,1]
	v_div_fmas_f32 v51, v51, v55, v63
	s_waitcnt vmcnt(0)
; __device__ __forceinline__ float fsigmoid(float v) { return __builtin_amdgcn_rcpf(1.f + __builtin_amdgcn_exp2f(-v * LOG2E)); }
; __device__ __forceinline__ u32x4 pack8(const float (&f)[8]) { u32x4 w; w.x = cvtpk(f[0], f[1]); w.y = cvtpk(f[2], f[3]); w.z = cvtpk(f[4], f[5]); w.w = cvtpk(f[6], f[7]); return w; }
; template <int W, int NI> __device__ __forceinline__ void pool_items(bf16_t* PB, const float* pscale, const int (&rps)[NI], int g, int lane) {
;     ...
;     for (int q = 0; q < NI; ++q) {
;         float za[8], sum[8], x0[8]; unpack8(zw[q], za); unpack8(v[q][0], x0);
; #pragma unroll
;         for (int e = 0; e < 8; ++e) sum[e] = x0[e];
; #pragma unroll
;         for (int jj = 1; jj < W; ++jj) { float f[8]; unpack8(v[q][jj], f); const float mk = (jj <= t[q]) ? 1.f : 0.f;
; #pragma unroll
;             for (int e = 0; e < 8; ++e) sum[e] += mk * f[e]; }
;         const int cnt = (t[q] + 1 < W) ? (t[q] + 1) : W;
;         const float inv = 1.f / (float)cnt;
;         float y[8];
; #pragma unroll
;         for (int e = 0; e < 8; ++e) { const float ps = (e < 4) ? p0[e & 3] : p1[e & 3]; y[e] = (sum[e] * inv - x0[e]) * ps * (za[e] * fsigmoid(za[e])); }
;         outw[q] = pack8(y); }
	v_pk_mul_f32 v[152:153], v[152:153], v[42:43]
	v_div_fixup_f32 v47, v51, v47, 1.0
	v_lshlrev_b32_e32 v198, 16, v138
	v_mov_b32_e32 v135, v230
	v_pk_mul_f32 v[230:231], v[170:171], v[152:153]
	v_cndmask_b32_e64 v152, v244, v47, s[62:63]
	v_mul_f32_e32 v47, 0xbfb8aa3b, v198
	v_exp_f32_e32 v47, v47
	v_and_b32_e32 v199, 0xffff0000, v138
	v_cndmask_b32_e64 v162, 1.0, 0, s[34:35]
	v_lshlrev_b32_e32 v158, 16, v98
	v_add_f32_e32 v47, 1.0, v47
	v_rcp_f32_e32 v196, v47
	v_mul_f32_e32 v47, 0xbfb8aa3b, v199
	v_exp_f32_e32 v47, v47
	v_and_b32_e32 v159, 0xffff0000, v98
	v_mov_b32_e32 v51, v252
	v_lshlrev_b32_e32 v252, 16, v86
	v_add_f32_e32 v47, 1.0, v47
	v_rcp_f32_e32 v197, v47
	v_mov_b32_e32 v55, v253
	v_and_b32_e32 v253, 0xffff0000, v86
	v_cndmask_b32_e64 v166, 1.0, 0, s[36:37]
	v_pk_mul_f32 v[196:197], v[196:197], v[198:199]
	v_lshlrev_b32_e32 v198, 16, v26
	v_and_b32_e32 v199, 0xffff0000, v26
	v_pk_fma_f32 v[158:159], v[162:163], v[158:159], v[252:253] op_sel_hi:[0,1,1]
	v_cndmask_b32_e64 v168, 1.0, 0, s[38:39]
	v_mov_b32_e32 v67, v242
	v_lshlrev_b32_e32 v242, 16, v34
	v_and_b32_e32 v243, 0xffff0000, v34
	v_pk_fma_f32 v[158:159], v[166:167], v[198:199], v[158:159] op_sel_hi:[0,1,1]
	v_cndmask_b32_e64 v170, 1.0, 0, s[40:41]
	v_mov_b32_e32 v34, v240
	v_lshlrev_b32_e32 v240, 16, v30
	v_mov_b32_e32 v47, v241
	v_and_b32_e32 v241, 0xffff0000, v30
	v_pk_fma_f32 v[158:159], v[168:169], v[242:243], v[158:159] op_sel_hi:[0,1,1]
	v_cndmask_b32_e64 v172, 1.0, 0, s[42:43]
	v_lshlrev_b32_e32 v250, 16, v22
	v_mov_b32_e32 v26, v251
	v_and_b32_e32 v251, 0xffff0000, v22
	v_pk_fma_f32 v[158:159], v[170:171], v[240:241], v[158:159] op_sel_hi:[0,1,1]
	v_cndmask_b32_e64 v174, 1.0, 0, s[44:45]
	v_lshlrev_b32_e32 v246, 16, v10
	v_and_b32_e32 v247, 0xffff0000, v10
	v_pk_fma_f32 v[158:159], v[172:173], v[250:251], v[158:159] op_sel_hi:[0,1,1]
	v_cndmask_b32_e64 v176, 1.0, 0, s[46:47]
	v_lshlrev_b32_e32 v248, 16, v6
	v_and_b32_e32 v249, 0xffff0000, v6
	v_pk_fma_f32 v[158:159], v[174:175], v[246:247], v[158:159] op_sel_hi:[0,1,1]
	v_cndmask_b32_e64 v178, 1.0, 0, s[48:49]
	v_mov_b32_e32 v153, v244
	v_lshlrev_b32_e32 v244, 16, v2
	v_and_b32_e32 v245, 0xffff0000, v2
	v_pk_fma_f32 v[158:159], v[176:177], v[248:249], v[158:159] op_sel_hi:[0,1,1]
	v_cndmask_b32_e64 v164, 1.0, 0, s[50:51]
	v_lshlrev_b32_e32 v238, 16, v102
	v_and_b32_e32 v239, 0xffff0000, v102
	v_pk_fma_f32 v[158:159], v[178:179], v[244:245], v[158:159] op_sel_hi:[0,1,1]
	v_pk_fma_f32 v[158:159], v[164:165], v[238:239], v[158:159] op_sel_hi:[0,1,1]
	v_lshlrev_b32_e32 v238, 16, v118
	v_and_b32_e32 v239, 0xffff0000, v118
	v_lshlrev_b32_e32 v118, 16, v122
	v_and_b32_e32 v119, 0xffff0000, v122
	v_lshlrev_b32_e32 v122, 16, v94
	v_mul_f32_e32 v2, 0xbfb8aa3b, v122
	v_exp_f32_e32 v2, v2
	v_and_b32_e32 v123, 0xffff0000, v94
	v_cndmask_b32_e64 v180, 1.0, 0, s[52:53]
	v_lshlrev_b32_e32 v232, 16, v106
	v_add_f32_e32 v2, 1.0, v2
	v_rcp_f32_e32 v94, v2
	v_mul_f32_e32 v2, 0xbfb8aa3b, v123
	v_exp_f32_e32 v2, v2
	v_and_b32_e32 v233, 0xffff0000, v106
	v_cndmask_b32_e64 v184, 1.0, 0, s[54:55]
	v_mov_b32_e32 v59, v234
	v_lshlrev_b32_e32 v234, 16, v110
	v_mov_b32_e32 v63, v235
	v_and_b32_e32 v235, 0xffff0000, v110
	v_pk_fma_f32 v[158:159], v[180:181], v[232:233], v[158:159] op_sel_hi:[0,1,1]
	v_cndmask_b32_e64 v188, 1.0, 0, s[56:57]
	v_mov_b32_e32 v131, v236
	v_lshlrev_b32_e32 v236, 16, v114
	v_and_b32_e32 v237, 0xffff0000, v114
	v_pk_fma_f32 v[158:159], v[184:185], v[234:235], v[158:159] op_sel_hi:[0,1,1]
	v_add_f32_e32 v2, 1.0, v2
	v_cndmask_b32_e64 v160, 1.0, 0, s[58:59]
	v_pk_fma_f32 v[158:159], v[188:189], v[236:237], v[158:159] op_sel_hi:[0,1,1]
	v_lshlrev_b32_e32 v198, 16, v38
	v_and_b32_e32 v199, 0xffff0000, v38
	v_rcp_f32_e32 v95, v2
	v_cndmask_b32_e64 v156, 1.0, 0, s[60:61]
	v_pk_fma_f32 v[158:159], v[160:161], v[198:199], v[158:159] op_sel_hi:[0,1,1]
	v_lshlrev_b32_e32 v198, 16, v18
	v_and_b32_e32 v199, 0xffff0000, v18
	v_cndmask_b32_e64 v154, 1.0, 0, s[62:63]
	v_pk_fma_f32 v[158:159], v[156:157], v[198:199], v[158:159] op_sel_hi:[0,1,1]
	v_lshlrev_b32_e32 v198, 16, v14
	v_and_b32_e32 v199, 0xffff0000, v14
	v_pk_fma_f32 v[158:159], v[154:155], v[198:199], v[158:159] op_sel_hi:[0,1,1]
	v_lshlrev_b32_e32 v236, 16, v126
	v_and_b32_e32 v237, 0xffff0000, v126
	v_lshlrev_b32_e32 v126, 16, v90
	v_and_b32_e32 v127, 0xffff0000, v90
	v_mov_b32_e32 v242, v67
	v_mov_b32_e32 v241, v47
	v_pk_fma_f32 v[158:159], v[152:153], v[158:159], v[252:253] op_sel_hi:[0,1,1] neg_lo:[0,0,1] neg_hi:[0,0,1]
	v_mov_b32_e32 v252, v51
	v_pk_mul_f32 v[90:91], v[94:95], v[122:123]
	v_lshlrev_b32_e32 v94, 16, v46
	v_and_b32_e32 v95, 0xffff0000, v46
	v_lshlrev_b32_e32 v46, 16, v50
	v_and_b32_e32 v47, 0xffff0000, v50
	v_lshlrev_b32_e32 v50, 16, v66
	v_and_b32_e32 v51, 0xffff0000, v66
	v_lshlrev_b32_e32 v66, 16, v70
	v_and_b32_e32 v67, 0xffff0000, v70
	v_lshlrev_b32_e32 v70, 16, v74
	v_and_b32_e32 v71, 0xffff0000, v74
	v_lshlrev_b32_e32 v74, 16, v78
	v_and_b32_e32 v75, 0xffff0000, v78
	v_lshlrev_b32_e32 v78, 16, v82
	v_and_b32_e32 v79, 0xffff0000, v82
	v_pk_fma_f32 v[82:83], v[206:207], v[238:239], v[126:127] op_sel_hi:[0,1,1]
	v_pk_fma_f32 v[82:83], v[210:211], v[94:95], v[82:83] op_sel_hi:[0,1,1]
	v_pk_fma_f32 v[46:47], v[212:213], v[46:47], v[82:83] op_sel_hi:[0,1,1]
	v_pk_fma_f32 v[46:47], v[214:215], v[50:51], v[46:47] op_sel_hi:[0,1,1]
	v_pk_fma_f32 v[46:47], v[216:217], v[66:67], v[46:47] op_sel_hi:[0,1,1]
	v_lshlrev_b32_e32 v66, 16, v137
	v_mul_f32_e32 v2, 0xbfb8aa3b, v66
	v_exp_f32_e32 v2, v2
	v_pk_fma_f32 v[46:47], v[218:219], v[70:71], v[46:47] op_sel_hi:[0,1,1]
	v_pk_fma_f32 v[46:47], v[220:221], v[74:75], v[46:47] op_sel_hi:[0,1,1]
; __device__ __forceinline__ float fsigmoid(float v) { return __builtin_amdgcn_rcpf(1.f + __builtin_amdgcn_exp2f(-v * LOG2E)); }
; __device__ __forceinline__ u32x4 pack8(const float (&f)[8]) { u32x4 w; w.x = cvtpk(f[0], f[1]); w.y = cvtpk(f[2], f[3]); w.z = cvtpk(f[4], f[5]); w.w = cvtpk(f[6], f[7]); return w; }
; template <int W, int NI> __device__ __forceinline__ void pool_items(bf16_t* PB, const float* pscale, const int (&rps)[NI], int g, int lane) {
;     ...
;     for (int q = 0; q < NI; ++q) {
;         float za[8], sum[8], x0[8]; unpack8(zw[q], za); unpack8(v[q][0], x0);
; #pragma unroll
;         for (int e = 0; e < 8; ++e) sum[e] = x0[e];
; #pragma unroll
;         for (int jj = 1; jj < W; ++jj) { float f[8]; unpack8(v[q][jj], f); const float mk = (jj <= t[q]) ? 1.f : 0.f;
; #pragma unroll
;             for (int e = 0; e < 8; ++e) sum[e] += mk * f[e]; }
;         const int cnt = (t[q] + 1 < W) ? (t[q] + 1) : W;
;         const float inv = 1.f / (float)cnt;
;         float y[8];
; #pragma unroll
;         for (int e = 0; e < 8; ++e) { const float ps = (e < 4) ? p0[e & 3] : p1[e & 3]; y[e] = (sum[e] * inv - x0[e]) * ps * (za[e] * fsigmoid(za[e])); }
;         outw[q] = pack8(y); }
	v_pk_fma_f32 v[46:47], v[222:223], v[78:79], v[46:47] op_sel_hi:[0,1,1]
	v_and_b32_e32 v67, 0xffff0000, v137
	v_add_f32_e32 v2, 1.0, v2
	v_pk_fma_f32 v[46:47], v[208:209], v[118:119], v[46:47] op_sel_hi:[0,1,1]
	v_rcp_f32_e32 v70, v2
	v_mul_f32_e32 v2, 0xbfb8aa3b, v67
	v_lshlrev_b32_e32 v234, 16, v130
	v_and_b32_e32 v235, 0xffff0000, v130
	v_pk_fma_f32 v[46:47], v[224:225], v[236:237], v[46:47] op_sel_hi:[0,1,1]
	v_exp_f32_e32 v2, v2
	v_lshlrev_b32_e32 v232, 16, v134
	v_and_b32_e32 v233, 0xffff0000, v134
	v_pk_fma_f32 v[46:47], v[226:227], v[234:235], v[46:47] op_sel_hi:[0,1,1]
	v_pk_fma_f32 v[46:47], v[228:229], v[232:233], v[46:47] op_sel_hi:[0,1,1]
	v_lshlrev_b32_e32 v50, 16, v54
	v_and_b32_e32 v51, 0xffff0000, v54
	v_pk_fma_f32 v[46:47], v[204:205], v[50:51], v[46:47] op_sel_hi:[0,1,1]
	v_lshlrev_b32_e32 v50, 16, v58
	v_and_b32_e32 v51, 0xffff0000, v58
	v_pk_fma_f32 v[46:47], v[202:203], v[50:51], v[46:47] op_sel_hi:[0,1,1]
	v_lshlrev_b32_e32 v50, 16, v62
	v_and_b32_e32 v51, 0xffff0000, v62
	v_add_f32_e32 v2, 1.0, v2
	v_pk_fma_f32 v[46:47], v[200:201], v[50:51], v[46:47] op_sel_hi:[0,1,1]
	v_rcp_f32_e32 v71, v2
	v_pk_fma_f32 v[46:47], v[194:195], v[46:47], v[126:127] op_sel_hi:[0,1,1] neg_lo:[0,0,1] neg_hi:[0,0,1]
	v_pk_mul_f32 v[158:159], v[40:41], v[158:159]
	v_pk_mul_f32 v[40:41], v[46:47], v[40:41]
	v_lshlrev_b32_e32 v74, 16, v85
	v_pk_mul_f32 v[46:47], v[90:91], v[40:41]
	v_lshlrev_b32_e32 v40, 16, v97
	v_and_b32_e32 v41, 0xffff0000, v97
	v_and_b32_e32 v75, 0xffff0000, v85
	v_pk_mul_f32 v[66:67], v[70:71], v[66:67]
	v_lshlrev_b32_e32 v70, 16, v25
	v_and_b32_e32 v71, 0xffff0000, v25
	v_pk_fma_f32 v[40:41], v[162:163], v[40:41], v[74:75] op_sel_hi:[0,1,1]
	v_lshlrev_b32_e32 v78, 16, v33
	v_and_b32_e32 v79, 0xffff0000, v33
	v_pk_fma_f32 v[40:41], v[166:167], v[70:71], v[40:41] op_sel_hi:[0,1,1]
	v_lshlrev_b32_e32 v82, 16, v29
	v_and_b32_e32 v83, 0xffff0000, v29
	v_pk_fma_f32 v[40:41], v[168:169], v[78:79], v[40:41] op_sel_hi:[0,1,1]
	v_lshlrev_b32_e32 v90, 16, v21
	v_and_b32_e32 v91, 0xffff0000, v21
	v_pk_fma_f32 v[40:41], v[170:171], v[82:83], v[40:41] op_sel_hi:[0,1,1]
	v_lshlrev_b32_e32 v94, 16, v9
	v_and_b32_e32 v95, 0xffff0000, v9
	v_pk_fma_f32 v[40:41], v[172:173], v[90:91], v[40:41] op_sel_hi:[0,1,1]
	v_lshlrev_b32_e32 v118, 16, v5
	v_and_b32_e32 v119, 0xffff0000, v5
	v_pk_fma_f32 v[40:41], v[174:175], v[94:95], v[40:41] op_sel_hi:[0,1,1]
	v_lshlrev_b32_e32 v122, 16, v1
	v_and_b32_e32 v123, 0xffff0000, v1
	v_pk_fma_f32 v[40:41], v[176:177], v[118:119], v[40:41] op_sel_hi:[0,1,1]
	v_mov_b32_e32 v235, v63
	v_lshlrev_b32_e32 v62, 16, v101
	v_and_b32_e32 v63, 0xffff0000, v101
	v_pk_fma_f32 v[40:41], v[178:179], v[122:123], v[40:41] op_sel_hi:[0,1,1]
	v_lshlrev_b32_e32 v50, 16, v105
	v_and_b32_e32 v51, 0xffff0000, v105
	v_pk_fma_f32 v[40:41], v[164:165], v[62:63], v[40:41] op_sel_hi:[0,1,1]
	v_lshlrev_b32_e32 v70, 16, v93
	v_mov_b32_e32 v253, v55
	v_lshlrev_b32_e32 v54, 16, v109
	v_and_b32_e32 v55, 0xffff0000, v109
	v_pk_fma_f32 v[40:41], v[180:181], v[50:51], v[40:41] op_sel_hi:[0,1,1]
	v_mul_f32_e32 v1, 0xbfb8aa3b, v70
	v_mov_b32_e32 v234, v59
	v_lshlrev_b32_e32 v58, 16, v113
	v_and_b32_e32 v59, 0xffff0000, v113
	v_pk_fma_f32 v[40:41], v[184:185], v[54:55], v[40:41] op_sel_hi:[0,1,1]
	v_exp_f32_e32 v1, v1
	v_pk_fma_f32 v[40:41], v[188:189], v[58:59], v[40:41] op_sel_hi:[0,1,1]
	v_lshlrev_b32_e32 v50, 16, v37
	v_and_b32_e32 v51, 0xffff0000, v37
	v_pk_fma_f32 v[40:41], v[160:161], v[50:51], v[40:41] op_sel_hi:[0,1,1]
	v_lshlrev_b32_e32 v50, 16, v17
	v_and_b32_e32 v51, 0xffff0000, v17
	v_pk_fma_f32 v[40:41], v[156:157], v[50:51], v[40:41] op_sel_hi:[0,1,1]
	v_lshlrev_b32_e32 v50, 16, v13
	v_and_b32_e32 v51, 0xffff0000, v13
	v_pk_fma_f32 v[40:41], v[154:155], v[50:51], v[40:41] op_sel_hi:[0,1,1]
	v_and_b32_e32 v71, 0xffff0000, v93
	v_add_f32_e32 v1, 1.0, v1
	v_pk_fma_f32 v[40:41], v[152:153], v[40:41], v[74:75] op_sel_hi:[0,1,1] neg_lo:[0,0,1] neg_hi:[0,0,1]
	v_rcp_f32_e32 v74, v1
	v_mul_f32_e32 v1, 0xbfb8aa3b, v71
	v_exp_f32_e32 v1, v1
	v_pk_mul_f32 v[40:41], v[142:143], v[40:41]
	v_lshlrev_b32_e32 v78, 16, v89
	v_pk_mul_f32 v[40:41], v[40:41], v[66:67]
	v_add_f32_e32 v1, 1.0, v1
	v_rcp_f32_e32 v75, v1
	v_lshlrev_b32_e32 v66, 16, v117
	v_and_b32_e32 v67, 0xffff0000, v117
	v_and_b32_e32 v79, 0xffff0000, v89
	v_pk_mul_f32 v[70:71], v[74:75], v[70:71]
	v_lshlrev_b32_e32 v74, 16, v45
	v_and_b32_e32 v75, 0xffff0000, v45
	v_pk_fma_f32 v[66:67], v[206:207], v[66:67], v[78:79] op_sel_hi:[0,1,1]
	v_lshlrev_b32_e32 v82, 16, v49
	v_and_b32_e32 v83, 0xffff0000, v49
	v_pk_fma_f32 v[66:67], v[210:211], v[74:75], v[66:67] op_sel_hi:[0,1,1]
	v_lshlrev_b32_e32 v90, 16, v65
	v_and_b32_e32 v91, 0xffff0000, v65
	v_pk_fma_f32 v[66:67], v[212:213], v[82:83], v[66:67] op_sel_hi:[0,1,1]
	v_lshlrev_b32_e32 v94, 16, v69
	v_and_b32_e32 v95, 0xffff0000, v69
	v_pk_fma_f32 v[66:67], v[214:215], v[90:91], v[66:67] op_sel_hi:[0,1,1]
	v_lshlrev_b32_e32 v118, 16, v73
	v_and_b32_e32 v119, 0xffff0000, v73
	v_pk_fma_f32 v[66:67], v[216:217], v[94:95], v[66:67] op_sel_hi:[0,1,1]
	v_lshlrev_b32_e32 v122, 16, v77
	v_and_b32_e32 v123, 0xffff0000, v77
	v_pk_fma_f32 v[66:67], v[218:219], v[118:119], v[66:67] op_sel_hi:[0,1,1]
	v_lshlrev_b32_e32 v126, 16, v81
	v_and_b32_e32 v127, 0xffff0000, v81
	v_pk_fma_f32 v[66:67], v[220:221], v[122:123], v[66:67] op_sel_hi:[0,1,1]
	v_lshlrev_b32_e32 v62, 16, v121
	v_and_b32_e32 v63, 0xffff0000, v121
	v_pk_fma_f32 v[66:67], v[222:223], v[126:127], v[66:67] op_sel_hi:[0,1,1]
	v_lshlrev_b32_e32 v58, 16, v125
	v_and_b32_e32 v59, 0xffff0000, v125
	v_pk_fma_f32 v[62:63], v[208:209], v[62:63], v[66:67] op_sel_hi:[0,1,1]
	v_lshlrev_b32_e32 v74, 16, v136
; __device__ __forceinline__ float fsigmoid(float v) { return __builtin_amdgcn_rcpf(1.f + __builtin_amdgcn_exp2f(-v * LOG2E)); }
; __device__ __forceinline__ u32x4 pack8(const float (&f)[8]) { u32x4 w; w.x = cvtpk(f[0], f[1]); w.y = cvtpk(f[2], f[3]); w.z = cvtpk(f[4], f[5]); w.w = cvtpk(f[6], f[7]); return w; }
; template <int W, int NI> __device__ __forceinline__ void pool_items(bf16_t* PB, const float* pscale, const int (&rps)[NI], int g, int lane) {
;     ...
;     for (int q = 0; q < NI; ++q) {
;         float za[8], sum[8], x0[8]; unpack8(zw[q], za); unpack8(v[q][0], x0);
; #pragma unroll
;         for (int e = 0; e < 8; ++e) sum[e] = x0[e];
; #pragma unroll
;         for (int jj = 1; jj < W; ++jj) { float f[8]; unpack8(v[q][jj], f); const float mk = (jj <= t[q]) ? 1.f : 0.f;
; #pragma unroll
;             for (int e = 0; e < 8; ++e) sum[e] += mk * f[e]; }
;         const int cnt = (t[q] + 1 < W) ? (t[q] + 1) : W;
;         const float inv = 1.f / (float)cnt;
;         float y[8];
; #pragma unroll
;         for (int e = 0; e < 8; ++e) { const float ps = (e < 4) ? p0[e & 3] : p1[e & 3]; y[e] = (sum[e] * inv - x0[e]) * ps * (za[e] * fsigmoid(za[e])); }
;         outw[q] = pack8(y); }
	v_lshlrev_b32_e32 v54, 16, v129
	v_and_b32_e32 v55, 0xffff0000, v129
	v_pk_fma_f32 v[58:59], v[224:225], v[58:59], v[62:63] op_sel_hi:[0,1,1]
	v_mul_f32_e32 v1, 0xbfb8aa3b, v74
	v_lshlrev_b32_e32 v50, 16, v133
	v_and_b32_e32 v51, 0xffff0000, v133
	v_pk_fma_f32 v[54:55], v[226:227], v[54:55], v[58:59] op_sel_hi:[0,1,1]
	v_exp_f32_e32 v1, v1
	v_pk_fma_f32 v[50:51], v[228:229], v[50:51], v[54:55] op_sel_hi:[0,1,1]
	v_lshlrev_b32_e32 v54, 16, v53
	v_and_b32_e32 v55, 0xffff0000, v53
	v_pk_fma_f32 v[50:51], v[204:205], v[54:55], v[50:51] op_sel_hi:[0,1,1]
	v_lshlrev_b32_e32 v54, 16, v57
	v_and_b32_e32 v55, 0xffff0000, v57
	v_pk_fma_f32 v[50:51], v[202:203], v[54:55], v[50:51] op_sel_hi:[0,1,1]
	v_lshlrev_b32_e32 v54, 16, v61
	v_and_b32_e32 v55, 0xffff0000, v61
	v_pk_fma_f32 v[50:51], v[200:201], v[54:55], v[50:51] op_sel_hi:[0,1,1]
	v_and_b32_e32 v75, 0xffff0000, v136
	v_add_f32_e32 v1, 1.0, v1
	v_pk_fma_f32 v[50:51], v[194:195], v[50:51], v[78:79] op_sel_hi:[0,1,1] neg_lo:[0,0,1] neg_hi:[0,0,1]
	v_rcp_f32_e32 v78, v1
	v_mul_f32_e32 v1, 0xbfb8aa3b, v75
	v_exp_f32_e32 v1, v1
	v_lshlrev_b32_e32 v54, 16, v96
	v_and_b32_e32 v55, 0xffff0000, v96
	v_lshlrev_b32_e32 v82, 16, v84
	v_add_f32_e32 v1, 1.0, v1
	v_rcp_f32_e32 v79, v1
	v_and_b32_e32 v83, 0xffff0000, v84
	v_and_b32_e32 v25, 0xffff0000, v32
	v_and_b32_e32 v33, 0xffff0000, v28
	v_pk_mul_f32 v[74:75], v[78:79], v[74:75]
	v_lshlrev_b32_e32 v78, 16, v24
	v_and_b32_e32 v79, 0xffff0000, v24
	v_lshlrev_b32_e32 v24, 16, v32
	v_lshlrev_b32_e32 v32, 16, v28
	v_lshlrev_b32_e32 v28, 16, v20
	v_and_b32_e32 v29, 0xffff0000, v20
	v_lshlrev_b32_e32 v20, 16, v8
	v_and_b32_e32 v21, 0xffff0000, v8
	v_lshlrev_b32_e32 v8, 16, v4
	v_and_b32_e32 v9, 0xffff0000, v4
	v_lshlrev_b32_e32 v4, 16, v0
	v_and_b32_e32 v5, 0xffff0000, v0
	v_pk_fma_f32 v[0:1], v[162:163], v[54:55], v[82:83] op_sel_hi:[0,1,1]
	v_pk_fma_f32 v[0:1], v[166:167], v[78:79], v[0:1] op_sel_hi:[0,1,1]
	v_pk_fma_f32 v[0:1], v[168:169], v[24:25], v[0:1] op_sel_hi:[0,1,1]
	v_pk_fma_f32 v[0:1], v[170:171], v[32:33], v[0:1] op_sel_hi:[0,1,1]
	v_pk_fma_f32 v[0:1], v[172:173], v[28:29], v[0:1] op_sel_hi:[0,1,1]
	v_lshlrev_b32_e32 v28, 16, v92
	v_mul_f32_e32 v2, 0xbfb8aa3b, v28
	v_exp_f32_e32 v2, v2
	v_and_b32_e32 v29, 0xffff0000, v92
	v_pk_fma_f32 v[0:1], v[174:175], v[20:21], v[0:1] op_sel_hi:[0,1,1]
	v_lshlrev_b32_e32 v20, 16, v116
	v_add_f32_e32 v2, 1.0, v2
	v_rcp_f32_e32 v32, v2
	v_mul_f32_e32 v2, 0xbfb8aa3b, v29
	v_exp_f32_e32 v2, v2
	v_and_b32_e32 v21, 0xffff0000, v116
	v_lshlrev_b32_e32 v24, 16, v88
	v_and_b32_e32 v25, 0xffff0000, v88
	v_add_f32_e32 v2, 1.0, v2
	v_rcp_f32_e32 v33, v2
	v_pk_fma_f32 v[0:1], v[176:177], v[8:9], v[0:1] op_sel_hi:[0,1,1]
	v_pk_fma_f32 v[20:21], v[206:207], v[20:21], v[24:25] op_sel_hi:[0,1,1]
	v_pk_mul_f32 v[50:51], v[50:51], v[142:143]
	v_pk_mul_f32 v[28:29], v[32:33], v[28:29]
	v_lshlrev_b32_e32 v32, 16, v44
	v_and_b32_e32 v33, 0xffff0000, v44
	v_pk_fma_f32 v[0:1], v[178:179], v[4:5], v[0:1] op_sel_hi:[0,1,1]
	v_lshlrev_b32_e32 v4, 16, v36
	v_and_b32_e32 v5, 0xffff0000, v36
	v_lshlrev_b32_e32 v36, 16, v48
	v_and_b32_e32 v37, 0xffff0000, v48
	v_pk_fma_f32 v[20:21], v[210:211], v[32:33], v[20:21] op_sel_hi:[0,1,1]
	v_pk_mul_f32 v[50:51], v[70:71], v[50:51]
	v_lshlrev_b32_e32 v70, 16, v100
	v_and_b32_e32 v71, 0xffff0000, v100
	v_lshlrev_b32_e32 v44, 16, v64
	v_and_b32_e32 v45, 0xffff0000, v64
	v_pk_fma_f32 v[20:21], v[212:213], v[36:37], v[20:21] op_sel_hi:[0,1,1]
	v_lshlrev_b32_e32 v58, 16, v104
	v_and_b32_e32 v59, 0xffff0000, v104
	v_pk_fma_f32 v[0:1], v[164:165], v[70:71], v[0:1] op_sel_hi:[0,1,1]
	v_lshlrev_b32_e32 v48, 16, v68
	v_and_b32_e32 v49, 0xffff0000, v68
	v_pk_fma_f32 v[20:21], v[214:215], v[44:45], v[20:21] op_sel_hi:[0,1,1]
	v_lshlrev_b32_e32 v62, 16, v108
	v_and_b32_e32 v63, 0xffff0000, v108
	v_pk_fma_f32 v[0:1], v[180:181], v[58:59], v[0:1] op_sel_hi:[0,1,1]
	v_lshlrev_b32_e32 v54, 16, v72
	v_and_b32_e32 v55, 0xffff0000, v72
	v_pk_fma_f32 v[20:21], v[216:217], v[48:49], v[20:21] op_sel_hi:[0,1,1]
	v_lshlrev_b32_e32 v66, 16, v112
	v_and_b32_e32 v67, 0xffff0000, v112
	v_pk_fma_f32 v[0:1], v[184:185], v[62:63], v[0:1] op_sel_hi:[0,1,1]
	v_lshlrev_b32_e32 v58, 16, v76
	v_and_b32_e32 v59, 0xffff0000, v76
	v_pk_fma_f32 v[20:21], v[218:219], v[54:55], v[20:21] op_sel_hi:[0,1,1]
	v_pk_fma_f32 v[0:1], v[188:189], v[66:67], v[0:1] op_sel_hi:[0,1,1]
	v_lshlrev_b32_e32 v62, 16, v80
	v_and_b32_e32 v63, 0xffff0000, v80
	v_pk_fma_f32 v[20:21], v[220:221], v[58:59], v[20:21] op_sel_hi:[0,1,1]
	v_pk_fma_f32 v[0:1], v[160:161], v[4:5], v[0:1] op_sel_hi:[0,1,1]
	v_lshlrev_b32_e32 v4, 16, v16
	v_and_b32_e32 v5, 0xffff0000, v16
	v_lshlrev_b32_e32 v16, 16, v120
	v_and_b32_e32 v17, 0xffff0000, v120
	v_pk_fma_f32 v[20:21], v[222:223], v[62:63], v[20:21] op_sel_hi:[0,1,1]
	v_pk_fma_f32 v[0:1], v[156:157], v[4:5], v[0:1] op_sel_hi:[0,1,1]
	v_lshlrev_b32_e32 v4, 16, v12
	v_and_b32_e32 v5, 0xffff0000, v12
	v_lshlrev_b32_e32 v12, 16, v124
	v_and_b32_e32 v13, 0xffff0000, v124
	v_pk_fma_f32 v[16:17], v[208:209], v[16:17], v[20:21] op_sel_hi:[0,1,1]
	v_lshlrev_b32_e32 v8, 16, v128
	v_and_b32_e32 v9, 0xffff0000, v128
; __device__ __forceinline__ float fsigmoid(float v) { return __builtin_amdgcn_rcpf(1.f + __builtin_amdgcn_exp2f(-v * LOG2E)); }
; __device__ __forceinline__ u32x4 pack8(const float (&f)[8]) { u32x4 w; w.x = cvtpk(f[0], f[1]); w.y = cvtpk(f[2], f[3]); w.z = cvtpk(f[4], f[5]); w.w = cvtpk(f[6], f[7]); return w; }
; template <int W, int NI> __device__ __forceinline__ void pool_items(bf16_t* PB, const float* pscale, const int (&rps)[NI], int g, int lane) {
;     ...
;         for (int jj = 1; jj < W; ++jj) { float f[8]; unpack8(v[q][jj], f); const float mk = (jj <= t[q]) ? 1.f : 0.f;
; #pragma unroll
;             for (int e = 0; e < 8; ++e) sum[e] += mk * f[e]; }
;         const int cnt = (t[q] + 1 < W) ? (t[q] + 1) : W;
;         const float inv = 1.f / (float)cnt;
;         float y[8];
; #pragma unroll
;         for (int e = 0; e < 8; ++e) { const float ps = (e < 4) ? p0[e & 3] : p1[e & 3]; y[e] = (sum[e] * inv - x0[e]) * ps * (za[e] * fsigmoid(za[e])); }
;         outw[q] = pack8(y); }
; #pragma unroll
;     for (int q = 0; q < NI; ++q) *(u32x4*)zp[q] = outw[q];
	v_pk_fma_f32 v[12:13], v[224:225], v[12:13], v[16:17] op_sel_hi:[0,1,1]
	v_pk_fma_f32 v[0:1], v[154:155], v[4:5], v[0:1] op_sel_hi:[0,1,1]
	v_lshlrev_b32_e32 v4, 16, v132
	v_and_b32_e32 v5, 0xffff0000, v132
	v_pk_fma_f32 v[8:9], v[226:227], v[8:9], v[12:13] op_sel_hi:[0,1,1]
	v_pk_fma_f32 v[4:5], v[228:229], v[4:5], v[8:9] op_sel_hi:[0,1,1]
	v_lshlrev_b32_e32 v8, 16, v52
	v_and_b32_e32 v9, 0xffff0000, v52
	v_pk_fma_f32 v[4:5], v[204:205], v[8:9], v[4:5] op_sel_hi:[0,1,1]
	v_lshlrev_b32_e32 v8, 16, v56
	v_and_b32_e32 v9, 0xffff0000, v56
	v_pk_fma_f32 v[4:5], v[202:203], v[8:9], v[4:5] op_sel_hi:[0,1,1]
	v_lshlrev_b32_e32 v8, 16, v60
	v_and_b32_e32 v9, 0xffff0000, v60
	v_pk_fma_f32 v[4:5], v[200:201], v[8:9], v[4:5] op_sel_hi:[0,1,1]
	v_pk_fma_f32 v[4:5], v[194:195], v[4:5], v[24:25] op_sel_hi:[0,1,1] neg_lo:[0,0,1] neg_hi:[0,0,1]
	v_lshlrev_b32_e32 v182, 16, v99
	v_pk_mul_f32 v[4:5], v[4:5], v[140:141]
	v_and_b32_e32 v183, 0xffff0000, v99
	v_lshlrev_b32_e32 v12, 16, v87
	v_and_b32_e32 v13, 0xffff0000, v87
	v_pk_mul_f32 v[4:5], v[28:29], v[4:5]
	v_lshlrev_b32_e32 v16, 16, v27
	v_and_b32_e32 v17, 0xffff0000, v27
	v_pk_fma_f32 v[28:29], v[162:163], v[182:183], v[12:13] op_sel_hi:[0,1,1]
	v_lshlrev_b32_e32 v20, 16, v35
	v_and_b32_e32 v21, 0xffff0000, v35
	v_pk_fma_f32 v[16:17], v[166:167], v[16:17], v[28:29] op_sel_hi:[0,1,1]
	v_lshlrev_b32_e32 v24, 16, v31
	v_and_b32_e32 v25, 0xffff0000, v31
	v_pk_fma_f32 v[16:17], v[168:169], v[20:21], v[16:17] op_sel_hi:[0,1,1]
	v_lshlrev_b32_e32 v22, 16, v23
	v_and_b32_e32 v23, 0xffff0000, v23
	v_pk_fma_f32 v[16:17], v[170:171], v[24:25], v[16:17] op_sel_hi:[0,1,1]
	v_lshlrev_b32_e32 v10, 16, v11
	v_and_b32_e32 v11, 0xffff0000, v11
	v_pk_fma_f32 v[16:17], v[172:173], v[22:23], v[16:17] op_sel_hi:[0,1,1]
	v_cvt_pk_bf16_f32 v44, v4, v5
	v_lshlrev_b32_e32 v4, 16, v139
	v_and_b32_e32 v5, 0xffff0000, v139
	v_lshlrev_b32_e32 v6, 16, v7
	v_and_b32_e32 v7, 0xffff0000, v7
	v_pk_fma_f32 v[10:11], v[174:175], v[10:11], v[16:17] op_sel_hi:[0,1,1]
	v_mov_b32_e32 v251, v26
	v_mul_f32_e32 v2, 0xbfb8aa3b, v4
	v_lshlrev_b32_e32 v26, 16, v3
	v_and_b32_e32 v27, 0xffff0000, v3
	v_pk_fma_f32 v[6:7], v[176:177], v[6:7], v[10:11] op_sel_hi:[0,1,1]
	v_mul_f32_e32 v3, 0xbfb8aa3b, v5
	v_lshlrev_b32_e32 v8, 16, v103
	v_and_b32_e32 v9, 0xffff0000, v103
	v_exp_f32_e32 v2, v2
	v_pk_fma_f32 v[6:7], v[178:179], v[26:27], v[6:7] op_sel_hi:[0,1,1]
	v_exp_f32_e32 v3, v3
	v_lshlrev_b32_e32 v186, 16, v107
	v_and_b32_e32 v187, 0xffff0000, v107
	v_pk_fma_f32 v[6:7], v[164:165], v[8:9], v[6:7] op_sel_hi:[0,1,1]
	v_lshlrev_b32_e32 v190, 16, v111
	v_mov_b32_e32 v226, v191
	v_and_b32_e32 v191, 0xffff0000, v111
	v_pk_fma_f32 v[6:7], v[180:181], v[186:187], v[6:7] op_sel_hi:[0,1,1]
	v_lshlrev_b32_e32 v192, 16, v115
	v_mov_b32_e32 v228, v193
	v_and_b32_e32 v193, 0xffff0000, v115
	v_pk_fma_f32 v[6:7], v[184:185], v[190:191], v[6:7] op_sel_hi:[0,1,1]
	v_add_f32_e32 v2, 1.0, v2
	v_pk_fma_f32 v[6:7], v[188:189], v[192:193], v[6:7] op_sel_hi:[0,1,1]
	v_lshlrev_b32_e32 v8, 16, v39
	v_and_b32_e32 v9, 0xffff0000, v39
	v_add_f32_e32 v3, 1.0, v3
	v_rcp_f32_e32 v2, v2
	v_pk_fma_f32 v[6:7], v[160:161], v[8:9], v[6:7] op_sel_hi:[0,1,1]
	v_lshlrev_b32_e32 v8, 16, v19
	v_and_b32_e32 v9, 0xffff0000, v19
	v_rcp_f32_e32 v3, v3
	v_pk_fma_f32 v[6:7], v[156:157], v[8:9], v[6:7] op_sel_hi:[0,1,1]
	v_lshlrev_b32_e32 v8, 16, v15
	v_and_b32_e32 v9, 0xffff0000, v15
	v_pk_fma_f32 v[6:7], v[154:155], v[8:9], v[6:7] op_sel_hi:[0,1,1]
	v_pk_fma_f32 v[0:1], v[152:153], v[0:1], v[82:83] op_sel_hi:[0,1,1] neg_lo:[0,0,1] neg_hi:[0,0,1]
	v_pk_fma_f32 v[6:7], v[152:153], v[6:7], v[12:13] op_sel_hi:[0,1,1] neg_lo:[0,0,1] neg_hi:[0,0,1]
	s_add_i32 s91, s91, s82
	s_add_i32 s97, s97, s82
	v_pk_mul_f32 v[0:1], v[140:141], v[0:1]
	v_pk_mul_f32 v[6:7], v[42:43], v[6:7]
	v_pk_mul_f32 v[2:3], v[2:3], v[4:5]
	s_add_i32 s33, s91, s74
	s_add_i32 s2, s88, s97
	v_mov_b32_e32 v240, v34
	v_pk_mul_f32 v[158:159], v[158:159], v[196:197]
	v_mov_b32_e32 v236, v131
	v_mov_b32_e32 v244, v153
	v_pk_mul_f32 v[0:1], v[0:1], v[74:75]
	v_cvt_pk_bf16_f32 v45, v50, v51
	v_cvt_pk_bf16_f32 v46, v46, v47
	v_cvt_pk_bf16_f32 v47, v230, v231
	v_mov_b32_e32 v230, v135
	v_pk_mul_f32 v[4:5], v[6:7], v[2:3]
	v_add_u32_e32 v169, s87, v169
	s_cmpk_gt_i32 s2, 0x1fff
	v_cvt_pk_bf16_f32 v0, v0, v1
	v_cvt_pk_bf16_f32 v1, v40, v41
	v_cvt_pk_bf16_f32 v2, v158, v159
	v_cvt_pk_bf16_f32 v3, v4, v5
	global_store_dwordx4 v[148:149], v[44:47], off offset:3584 nt
	global_store_dwordx4 v[150:151], v[0:3], off offset:3584 nt
	s_cbranch_scc0 .LBB0_390
	v_readlane_b32 s44, v255, 54
	v_readlane_b32 s45, v255, 55
	v_readlane_b32 s44, v255, 58
	s_add_i32 s34, s81, s97
	s_movk_i32 s52, 0x2000
	s_movk_i32 s33, 0x4000
	s_mov_b64 s[38:39], 0x2000
	s_mov_b64 s[40:41], 0x1000
	v_readlane_b32 s42, v255, 52
	v_readlane_b32 s46, v255, 56
	v_readlane_b32 s47, v255, 57
	v_readlane_b32 s45, v255, 59
	v_mov_b32_e32 v239, v189
	v_mov_b32_e32 v245, v201
	v_mov_b32_e32 v243, v207
	v_mov_b32_e32 v246, v209
	v_mov_b32_e32 v250, v211
	v_mov_b32_e32 v224, v213
	v_readlane_b32 s91, v255, 47
	v_readlane_b32 s43, v255, 53

; __device__ __forceinline__ float fsigmoid(float v) { return __builtin_amdgcn_rcpf(1.f + __builtin_amdgcn_exp2f(-v * LOG2E)); }
; template <int W, int NI> __device__ __forceinline__ void pool_items(bf16_t* PB, const float* pscale, const int (&rps)[NI], int g, int lane) {
;     const int ch = g * 256 + (lane & 31) * 8;
;     u32x4 v[NI][W], zw[NI]; int t[NI]; bf16_t* zp[NI];
; #pragma unroll
;     for (int q = 0; q < NI; ++q) { const int row = 2 * rps[q] + (lane >> 5); t[q] = row & (SEQ - 1);
;         const bf16_t* xp = PB + (size_t)row * PBW + C_XA + ch;
; #pragma unroll
;         for (int jj = 0; jj < W; ++jj) { const int back = (jj <= t[q]) ? jj : 0; v[q][jj] = *(const u32x4*)(xp - (size_t)back * PBW); }
;         zp[q] = PB + (size_t)row * PBW + C_ZA + ch; zw[q] = *(const u32x4*)zp[q]; }
;     const f32x4 p0 = *(const f32x4*)(pscale + ch), p1 = *(const f32x4*)(pscale + ch + 4);
;     u32x4 outw[NI];
; #pragma unroll
;     for (int q = 0; q < NI; ++q) {
;         float za[8], sum[8], x0[8]; unpack8(zw[q], za); unpack8(v[q][0], x0);
; #pragma unroll
;         for (int e = 0; e < 8; ++e) sum[e] = x0[e];
; #pragma unroll
;         for (int jj = 1; jj < W; ++jj) { float f[8]; unpack8(v[q][jj], f); const float mk = (jj <= t[q]) ? 1.f : 0.f;
; #pragma unroll
;             for (int e = 0; e < 8; ++e) sum[e] += mk * f[e]; }
;         const int cnt = (t[q] + 1 < W) ? (t[q] + 1) : W;
;         const float inv = 1.f / (float)cnt;
;         float y[8];
; #pragma unroll
;         for (int e = 0; e < 8; ++e) { const float ps = (e < 4) ? p0[e & 3] : p1[e & 3]; y[e] = (sum[e] * inv - x0[e]) * ps * (za[e] * fsigmoid(za[e])); }
.LBB0_394:
	v_mad_i64_i32 v[76:77], s[2:3], v78, s65, v[74:75]
	global_load_dwordx4 v[4:7], v[76:77], off offset:3584
	global_load_dwordx4 v[0:3], v[76:77], off offset:1536
	v_and_b32_e32 v79, 0xfff, v78
	v_cmp_eq_u32_e64 s[2:3], 0, v79
	v_cmp_gt_u32_e64 s[6:7], 3, v79
	v_cmp_gt_u32_e64 s[4:5], 2, v79
	v_cndmask_b32_e64 v9, -1, 0, s[2:3]
	v_cndmask_b32_e64 v8, v225, 0, s[2:3]
	v_cndmask_b32_e64 v13, -1, 0, s[6:7]
	v_cndmask_b32_e64 v12, v229, 0, s[6:7]
	v_lshl_add_u64 v[8:9], v[76:77], 0, v[8:9]
	v_lshl_add_u64 v[12:13], v[76:77], 0, v[12:13]
	global_load_dwordx4 v[24:27], v[8:9], off offset:1536
	v_cmp_gt_u32_e64 s[8:9], 4, v79
	global_load_dwordx4 v[12:15], v[12:13], off offset:1536
	v_cndmask_b32_e64 v9, -1, 0, s[4:5]
	v_cndmask_b32_e64 v8, v227, 0, s[4:5]
	v_lshl_add_u64 v[8:9], v[76:77], 0, v[8:9]
	global_load_dwordx4 v[8:11], v[8:9], off offset:1536
	v_cndmask_b32_e64 v17, -1, 0, s[8:9]
	v_cndmask_b32_e64 v16, v251, 0, s[8:9]
	v_cmp_gt_u32_e64 s[10:11], 5, v79
	v_cmp_gt_u32_e64 s[18:19], 9, v79
	v_cmp_gt_u32_e64 s[28:29], 14, v79
	v_lshl_add_u64 v[16:17], v[76:77], 0, v[16:17]
	v_cndmask_b32_e64 v21, -1, 0, s[10:11]
	v_cndmask_b32_e64 v20, v252, 0, s[10:11]
	v_cmp_gt_u32_e64 s[12:13], 6, v79
	v_cndmask_b32_e64 v41, -1, 0, s[18:19]
	v_cndmask_b32_e64 v40, v236, 0, s[18:19]
	v_cndmask_b32_e64 v45, -1, 0, s[28:29]
	v_cndmask_b32_e64 v44, v228, 0, s[28:29]
	global_load_dwordx4 v[16:19], v[16:17], off offset:1536
	v_lshl_add_u64 v[20:21], v[76:77], 0, v[20:21]
	v_cndmask_b32_e64 v29, -1, 0, s[12:13]
	v_cndmask_b32_e64 v28, v253, 0, s[12:13]
	v_cmp_gt_u32_e64 s[14:15], 7, v79
	v_lshl_add_u64 v[40:41], v[76:77], 0, v[40:41]
	v_cmp_gt_u32_e64 s[20:21], 10, v79
	v_lshl_add_u64 v[44:45], v[76:77], 0, v[44:45]
	global_load_dwordx4 v[20:23], v[20:21], off offset:1536
	v_lshl_add_u64 v[28:29], v[76:77], 0, v[28:29]
	v_cndmask_b32_e64 v33, -1, 0, s[14:15]
	v_cndmask_b32_e64 v32, v234, 0, s[14:15]
	v_cmp_gt_u32_e64 s[16:17], 8, v79
	global_load_dwordx4 v[52:55], v[40:41], off offset:1536
	v_lshl_add_u64 v[32:33], v[76:77], 0, v[32:33]
	global_load_dwordx4 v[44:47], v[44:45], off offset:1536
	v_cndmask_b32_e64 v41, -1, 0, s[20:21]
	v_cndmask_b32_e64 v40, v240, 0, s[20:21]
	global_load_dwordx4 v[28:31], v[28:29], off offset:1536
	v_cndmask_b32_e64 v37, -1, 0, s[16:17]
	v_cndmask_b32_e64 v36, v235, 0, s[16:17]
	v_lshl_add_u64 v[40:41], v[76:77], 0, v[40:41]
	v_cmp_gt_u32_e64 s[22:23], 11, v79
	global_load_dwordx4 v[32:35], v[32:33], off offset:1536
	v_lshl_add_u64 v[36:37], v[76:77], 0, v[36:37]
	global_load_dwordx4 v[56:59], v[40:41], off offset:1536
	v_cndmask_b32_e64 v41, -1, 0, s[22:23]
	v_cndmask_b32_e64 v40, v241, 0, s[22:23]
	global_load_dwordx4 v[36:39], v[36:37], off offset:1536
	v_lshl_add_u64 v[40:41], v[76:77], 0, v[40:41]
	v_cmp_gt_u32_e64 s[24:25], 12, v79
	global_load_dwordx4 v[60:63], v[40:41], off offset:1536
	v_cmp_gt_u32_e64 s[26:27], 13, v79
	v_cndmask_b32_e64 v41, -1, 0, s[24:25]
	v_cndmask_b32_e64 v40, v242, 0, s[24:25]
	v_lshl_add_u64 v[40:41], v[76:77], 0, v[40:41]
	global_load_dwordx4 v[64:67], v[40:41], off offset:1536
	v_cndmask_b32_e64 v41, -1, 0, s[26:27]
	v_cndmask_b32_e64 v40, v226, 0, s[26:27]
	v_lshl_add_u64 v[40:41], v[76:77], 0, v[40:41]
	global_load_dwordx4 v[40:43], v[40:41], off offset:1536
	v_cmp_gt_u32_e64 s[30:31], 15, v79
	v_add_u32_e32 v79, 1, v79
	v_cvt_f32_u32_e32 v79, v79
	v_cndmask_b32_e64 v49, -1, 0, s[30:31]
	v_cndmask_b32_e64 v48, v230, 0, s[30:31]
	v_lshl_add_u64 v[48:49], v[76:77], 0, v[48:49]
	global_load_dwordx4 v[48:51], v[48:49], off offset:1536
	s_nop 0
	global_load_dwordx4 v[68:71], v[72:73], off offset:3088
	global_load_dwordx4 v[80:83], v[72:73], off offset:3072
	v_div_scale_f32 v84, s[36:37], v79, v79, 1.0
	s_waitcnt vmcnt(18)
	v_lshlrev_b32_e32 v134, 16, v6
	v_and_b32_e32 v135, 0xffff0000, v6
	v_rcp_f32_e32 v85, v84
	v_mul_f32_e32 v6, 0xbfb8aa3b, v134
	s_waitcnt vmcnt(17)
	v_lshlrev_b32_e32 v138, 16, v2
	v_and_b32_e32 v139, 0xffff0000, v2
	v_mul_f32_e32 v2, 0xbfb8aa3b, v135
	v_exp_f32_e32 v6, v6
	v_exp_f32_e32 v2, v2
	v_fma_f32 v86, -v84, v85, 1.0
	v_fmac_f32_e32 v85, v86, v85
	v_div_scale_f32 v86, vcc, 1.0, v79, 1.0
	v_add_f32_e32 v6, 1.0, v6
	v_add_f32_e32 v2, 1.0, v2
	v_mul_f32_e32 v87, v86, v85
	v_rcp_f32_e32 v136, v6
	v_rcp_f32_e32 v137, v2
	v_fma_f32 v88, -v84, v87, v86
	v_fmac_f32_e32 v87, v88, v85
	v_fma_f32 v84, -v84, v87, v86
	v_cndmask_b32_e64 v86, 1.0, 0, s[2:3]
	s_waitcnt vmcnt(16)
	v_lshlrev_b32_e32 v124, 16, v26
	v_and_b32_e32 v125, 0xffff0000, v26
	v_cndmask_b32_e64 v90, 1.0, 0, s[4:5]
	v_pk_mul_f32 v[134:135], v[136:137], v[134:135]
	s_waitcnt vmcnt(14)
	v_lshlrev_b32_e32 v136, 16, v10
	v_and_b32_e32 v137, 0xffff0000, v10
	v_pk_fma_f32 v[124:125], v[86:87], v[124:125], v[138:139] op_sel_hi:[0,1,1]
	v_cndmask_b32_e64 v92, 1.0, 0, s[6:7]
	v_lshlrev_b32_e32 v140, 16, v14
	v_and_b32_e32 v141, 0xffff0000, v14
	v_pk_fma_f32 v[124:125], v[90:91], v[136:137], v[124:125] op_sel_hi:[0,1,1]
	v_cndmask_b32_e64 v94, 1.0, 0, s[8:9]
	s_waitcnt vmcnt(13)
	v_lshlrev_b32_e32 v142, 16, v18
	v_and_b32_e32 v143, 0xffff0000, v18
	v_pk_fma_f32 v[124:125], v[92:93], v[140:141], v[124:125] op_sel_hi:[0,1,1]
	v_cndmask_b32_e64 v96, 1.0, 0, s[10:11]
	s_waitcnt vmcnt(12)
	v_lshlrev_b32_e32 v144, 16, v22
	v_and_b32_e32 v145, 0xffff0000, v22
	v_pk_fma_f32 v[124:125], v[94:95], v[142:143], v[124:125] op_sel_hi:[0,1,1]
	v_cndmask_b32_e64 v98, 1.0, 0, s[12:13]
	v_pk_fma_f32 v[124:125], v[96:97], v[144:145], v[124:125] op_sel_hi:[0,1,1]
	v_cndmask_b32_e64 v100, 1.0, 0, s[14:15]
	v_cndmask_b32_e64 v102, 1.0, 0, s[16:17]
	v_cndmask_b32_e64 v104, 1.0, 0, s[18:19]
	s_waitcnt vmcnt(11)
; __device__ __forceinline__ float fsigmoid(float v) { return __builtin_amdgcn_rcpf(1.f + __builtin_amdgcn_exp2f(-v * LOG2E)); }
; template <int W, int NI> __device__ __forceinline__ void pool_items(bf16_t* PB, const float* pscale, const int (&rps)[NI], int g, int lane) {
;     ...
;     for (int q = 0; q < NI; ++q) {
;         float za[8], sum[8], x0[8]; unpack8(zw[q], za); unpack8(v[q][0], x0);
; #pragma unroll
;         for (int e = 0; e < 8; ++e) sum[e] = x0[e];
; #pragma unroll
;         for (int jj = 1; jj < W; ++jj) { float f[8]; unpack8(v[q][jj], f); const float mk = (jj <= t[q]) ? 1.f : 0.f;
; #pragma unroll
;             for (int e = 0; e < 8; ++e) sum[e] += mk * f[e]; }
;         const int cnt = (t[q] + 1 < W) ? (t[q] + 1) : W;
;         const float inv = 1.f / (float)cnt;
;         float y[8];
; #pragma unroll
;         for (int e = 0; e < 8; ++e) { const float ps = (e < 4) ? p0[e & 3] : p1[e & 3]; y[e] = (sum[e] * inv - x0[e]) * ps * (za[e] * fsigmoid(za[e])); }
	v_lshlrev_b32_e32 v132, 16, v54
	v_and_b32_e32 v133, 0xffff0000, v54
	s_waitcnt vmcnt(9)
	v_lshlrev_b32_e32 v146, 16, v30
	v_and_b32_e32 v147, 0xffff0000, v30
	v_pk_fma_f32 v[124:125], v[98:99], v[146:147], v[124:125] op_sel_hi:[0,1,1]
	v_cndmask_b32_e64 v106, 1.0, 0, s[20:21]
	v_cndmask_b32_e64 v110, 1.0, 0, s[22:23]
	s_waitcnt vmcnt(8)
	v_lshlrev_b32_e32 v148, 16, v34
	v_and_b32_e32 v149, 0xffff0000, v34
	v_pk_fma_f32 v[124:125], v[100:101], v[148:149], v[124:125] op_sel_hi:[0,1,1]
	s_waitcnt vmcnt(7)
	v_lshlrev_b32_e32 v126, 16, v58
	v_and_b32_e32 v127, 0xffff0000, v58
	s_waitcnt vmcnt(6)
	v_lshlrev_b32_e32 v150, 16, v38
	v_and_b32_e32 v151, 0xffff0000, v38
	v_pk_fma_f32 v[124:125], v[102:103], v[150:151], v[124:125] op_sel_hi:[0,1,1]
	v_pk_fma_f32 v[124:125], v[104:105], v[132:133], v[124:125] op_sel_hi:[0,1,1]
	s_waitcnt vmcnt(5)
	v_lshlrev_b32_e32 v128, 16, v62
	v_and_b32_e32 v129, 0xffff0000, v62
	v_pk_fma_f32 v[124:125], v[106:107], v[126:127], v[124:125] op_sel_hi:[0,1,1]
	v_cndmask_b32_e64 v114, 1.0, 0, s[24:25]
	s_waitcnt vmcnt(4)
	v_lshlrev_b32_e32 v130, 16, v66
	v_and_b32_e32 v131, 0xffff0000, v66
	v_pk_fma_f32 v[124:125], v[110:111], v[128:129], v[124:125] op_sel_hi:[0,1,1]
	v_cndmask_b32_e64 v118, 1.0, 0, s[26:27]
	v_pk_fma_f32 v[124:125], v[114:115], v[130:131], v[124:125] op_sel_hi:[0,1,1]
	s_waitcnt vmcnt(3)
	v_lshlrev_b32_e32 v126, 16, v42
	v_and_b32_e32 v127, 0xffff0000, v42
	v_div_fmas_f32 v84, v84, v85, v87
	v_cndmask_b32_e64 v120, 1.0, 0, s[28:29]
	v_pk_fma_f32 v[124:125], v[118:119], v[126:127], v[124:125] op_sel_hi:[0,1,1]
	v_lshlrev_b32_e32 v126, 16, v46
	v_and_b32_e32 v127, 0xffff0000, v46
	v_div_fixup_f32 v79, v84, v79, 1.0
	v_cndmask_b32_e64 v122, 1.0, 0, s[30:31]
	v_pk_fma_f32 v[124:125], v[120:121], v[126:127], v[124:125] op_sel_hi:[0,1,1]
	s_waitcnt vmcnt(2)
	v_lshlrev_b32_e32 v126, 16, v50
	v_and_b32_e32 v127, 0xffff0000, v50
	v_cndmask_b32_e64 v84, v244, v79, s[30:31]
	v_pk_fma_f32 v[124:125], v[122:123], v[126:127], v[124:125] op_sel_hi:[0,1,1]
	v_pk_fma_f32 v[124:125], v[84:85], v[124:125], v[138:139] op_sel_hi:[0,1,1] neg_lo:[0,0,1] neg_hi:[0,0,1]
	s_waitcnt vmcnt(1)
	v_pk_mul_f32 v[68:69], v[68:69], v[124:125]
	v_lshlrev_b32_e32 v138, 16, v1
	v_pk_mul_f32 v[68:69], v[134:135], v[68:69]
	v_lshlrev_b32_e32 v134, 16, v5
	v_and_b32_e32 v135, 0xffff0000, v5
	v_mul_f32_e32 v2, 0xbfb8aa3b, v134
	v_and_b32_e32 v139, 0xffff0000, v1
	v_mul_f32_e32 v1, 0xbfb8aa3b, v135
	v_exp_f32_e32 v2, v2
	v_exp_f32_e32 v1, v1
	v_lshlrev_b32_e32 v124, 16, v25
	v_and_b32_e32 v125, 0xffff0000, v25
	v_add_f32_e32 v2, 1.0, v2
	v_add_f32_e32 v1, 1.0, v1
	v_rcp_f32_e32 v136, v2
	v_rcp_f32_e32 v137, v1
	v_pk_fma_f32 v[124:125], v[86:87], v[124:125], v[138:139] op_sel_hi:[0,1,1]
	v_lshlrev_b32_e32 v140, 16, v13
	v_and_b32_e32 v141, 0xffff0000, v13
	v_pk_mul_f32 v[134:135], v[136:137], v[134:135]
	v_lshlrev_b32_e32 v136, 16, v9
	v_and_b32_e32 v137, 0xffff0000, v9
	v_pk_fma_f32 v[124:125], v[90:91], v[136:137], v[124:125] op_sel_hi:[0,1,1]
	v_lshlrev_b32_e32 v142, 16, v17
	v_and_b32_e32 v143, 0xffff0000, v17
	v_pk_fma_f32 v[124:125], v[92:93], v[140:141], v[124:125] op_sel_hi:[0,1,1]
	v_lshlrev_b32_e32 v144, 16, v21
	v_and_b32_e32 v145, 0xffff0000, v21
	v_pk_fma_f32 v[124:125], v[94:95], v[142:143], v[124:125] op_sel_hi:[0,1,1]
	v_lshlrev_b32_e32 v146, 16, v29
	v_and_b32_e32 v147, 0xffff0000, v29
	v_pk_fma_f32 v[124:125], v[96:97], v[144:145], v[124:125] op_sel_hi:[0,1,1]
	v_lshlrev_b32_e32 v148, 16, v33
	v_and_b32_e32 v149, 0xffff0000, v33
	v_pk_fma_f32 v[124:125], v[98:99], v[146:147], v[124:125] op_sel_hi:[0,1,1]
	v_lshlrev_b32_e32 v150, 16, v37
	v_and_b32_e32 v151, 0xffff0000, v37
	v_pk_fma_f32 v[124:125], v[100:101], v[148:149], v[124:125] op_sel_hi:[0,1,1]
	v_lshlrev_b32_e32 v132, 16, v53
	v_and_b32_e32 v133, 0xffff0000, v53
	v_pk_fma_f32 v[124:125], v[102:103], v[150:151], v[124:125] op_sel_hi:[0,1,1]
	v_lshlrev_b32_e32 v126, 16, v57
	v_and_b32_e32 v127, 0xffff0000, v57
	v_pk_fma_f32 v[124:125], v[104:105], v[132:133], v[124:125] op_sel_hi:[0,1,1]
	v_lshlrev_b32_e32 v128, 16, v61
	v_and_b32_e32 v129, 0xffff0000, v61
	v_pk_fma_f32 v[124:125], v[106:107], v[126:127], v[124:125] op_sel_hi:[0,1,1]
	v_lshlrev_b32_e32 v130, 16, v65
	v_and_b32_e32 v131, 0xffff0000, v65
	v_pk_fma_f32 v[124:125], v[110:111], v[128:129], v[124:125] op_sel_hi:[0,1,1]
	v_pk_fma_f32 v[124:125], v[114:115], v[130:131], v[124:125] op_sel_hi:[0,1,1]
	v_lshlrev_b32_e32 v126, 16, v41
	v_and_b32_e32 v127, 0xffff0000, v41
	v_pk_fma_f32 v[124:125], v[118:119], v[126:127], v[124:125] op_sel_hi:[0,1,1]
	v_lshlrev_b32_e32 v126, 16, v45
	v_and_b32_e32 v127, 0xffff0000, v45
	v_pk_fma_f32 v[124:125], v[120:121], v[126:127], v[124:125] op_sel_hi:[0,1,1]
	v_lshlrev_b32_e32 v126, 16, v49
	v_and_b32_e32 v127, 0xffff0000, v49
	v_pk_fma_f32 v[124:125], v[122:123], v[126:127], v[124:125] op_sel_hi:[0,1,1]
	v_pk_fma_f32 v[124:125], v[84:85], v[124:125], v[138:139] op_sel_hi:[0,1,1] neg_lo:[0,0,1] neg_hi:[0,0,1]
	s_waitcnt vmcnt(0)
; __device__ __forceinline__ float fsigmoid(float v) { return __builtin_amdgcn_rcpf(1.f + __builtin_amdgcn_exp2f(-v * LOG2E)); }
; __device__ __forceinline__ u32x4 pack8(const float (&f)[8]) { u32x4 w; w.x = cvtpk(f[0], f[1]); w.y = cvtpk(f[2], f[3]); w.z = cvtpk(f[4], f[5]); w.w = cvtpk(f[6], f[7]); return w; }
; template <int W, int NI> __device__ __forceinline__ void pool_items(bf16_t* PB, const float* pscale, const int (&rps)[NI], int g, int lane) {
;     ...
;         for (int jj = 1; jj < W; ++jj) { float f[8]; unpack8(v[q][jj], f); const float mk = (jj <= t[q]) ? 1.f : 0.f;
; #pragma unroll
;             for (int e = 0; e < 8; ++e) sum[e] += mk * f[e]; }
;         const int cnt = (t[q] + 1 < W) ? (t[q] + 1) : W;
;         const float inv = 1.f / (float)cnt;
;         float y[8];
; #pragma unroll
;         for (int e = 0; e < 8; ++e) { const float ps = (e < 4) ? p0[e & 3] : p1[e & 3]; y[e] = (sum[e] * inv - x0[e]) * ps * (za[e] * fsigmoid(za[e])); }
;         outw[q] = pack8(y); }
; #pragma unroll
;     for (int q = 0; q < NI; ++q) *(u32x4*)zp[q] = outw[q];
	v_pk_mul_f32 v[82:83], v[82:83], v[124:125]
	v_lshlrev_b32_e32 v124, 16, v24
	v_and_b32_e32 v125, 0xffff0000, v24
	v_lshlrev_b32_e32 v24, 16, v52
	v_and_b32_e32 v25, 0xffff0000, v52
	v_lshlrev_b32_e32 v52, 16, v4
	v_and_b32_e32 v53, 0xffff0000, v4
	v_lshlrev_b32_e32 v126, 16, v56
	v_and_b32_e32 v127, 0xffff0000, v56
	v_mul_f32_e32 v1, 0xbfb8aa3b, v52
	v_lshlrev_b32_e32 v56, 16, v0
	v_and_b32_e32 v57, 0xffff0000, v0
	v_mul_f32_e32 v0, 0xbfb8aa3b, v53
	v_exp_f32_e32 v1, v1
	v_exp_f32_e32 v0, v0
	v_and_b32_e32 v9, 0xffff0000, v12
	v_and_b32_e32 v13, 0xffff0000, v16
	v_add_f32_e32 v1, 1.0, v1
	v_add_f32_e32 v0, 1.0, v0
	v_rcp_f32_e32 v4, v1
	v_rcp_f32_e32 v5, v0
	v_and_b32_e32 v17, 0xffff0000, v20
	v_and_b32_e32 v21, 0xffff0000, v28
	v_and_b32_e32 v29, 0xffff0000, v32
	v_pk_mul_f32 v[0:1], v[4:5], v[52:53]
	v_lshlrev_b32_e32 v4, 16, v8
	v_and_b32_e32 v5, 0xffff0000, v8
	v_lshlrev_b32_e32 v8, 16, v12
	v_lshlrev_b32_e32 v12, 16, v16
	v_lshlrev_b32_e32 v16, 16, v20
	v_lshlrev_b32_e32 v20, 16, v28
	v_lshlrev_b32_e32 v28, 16, v32
	v_lshlrev_b32_e32 v32, 16, v36
	v_and_b32_e32 v33, 0xffff0000, v36
	v_pk_fma_f32 v[36:37], v[86:87], v[124:125], v[56:57] op_sel_hi:[0,1,1]
	v_pk_fma_f32 v[4:5], v[90:91], v[4:5], v[36:37] op_sel_hi:[0,1,1]
	v_pk_fma_f32 v[4:5], v[92:93], v[8:9], v[4:5] op_sel_hi:[0,1,1]
	v_pk_fma_f32 v[4:5], v[94:95], v[12:13], v[4:5] op_sel_hi:[0,1,1]
	v_pk_fma_f32 v[4:5], v[96:97], v[16:17], v[4:5] op_sel_hi:[0,1,1]
	v_pk_fma_f32 v[4:5], v[98:99], v[20:21], v[4:5] op_sel_hi:[0,1,1]
	v_pk_fma_f32 v[4:5], v[100:101], v[28:29], v[4:5] op_sel_hi:[0,1,1]
	v_pk_fma_f32 v[4:5], v[102:103], v[32:33], v[4:5] op_sel_hi:[0,1,1]
	v_pk_fma_f32 v[4:5], v[104:105], v[24:25], v[4:5] op_sel_hi:[0,1,1]
	v_lshlrev_b32_e32 v128, 16, v60
	v_and_b32_e32 v129, 0xffff0000, v60
	v_pk_fma_f32 v[4:5], v[106:107], v[126:127], v[4:5] op_sel_hi:[0,1,1]
	v_lshlrev_b32_e32 v130, 16, v64
	v_and_b32_e32 v131, 0xffff0000, v64
	v_pk_fma_f32 v[4:5], v[110:111], v[128:129], v[4:5] op_sel_hi:[0,1,1]
	v_pk_fma_f32 v[4:5], v[114:115], v[130:131], v[4:5] op_sel_hi:[0,1,1]
	v_lshlrev_b32_e32 v8, 16, v40
	v_and_b32_e32 v9, 0xffff0000, v40
	v_pk_fma_f32 v[4:5], v[118:119], v[8:9], v[4:5] op_sel_hi:[0,1,1]
	v_lshlrev_b32_e32 v8, 16, v44
	v_and_b32_e32 v9, 0xffff0000, v44
	v_pk_fma_f32 v[4:5], v[120:121], v[8:9], v[4:5] op_sel_hi:[0,1,1]
	v_lshlrev_b32_e32 v8, 16, v48
	v_and_b32_e32 v9, 0xffff0000, v48
	v_lshlrev_b32_e32 v88, 16, v27
	v_pk_fma_f32 v[4:5], v[122:123], v[8:9], v[4:5] op_sel_hi:[0,1,1]
	v_and_b32_e32 v89, 0xffff0000, v27
	v_lshlrev_b32_e32 v8, 16, v3
	v_and_b32_e32 v9, 0xffff0000, v3
	v_lshlrev_b32_e32 v10, 16, v11
	v_and_b32_e32 v11, 0xffff0000, v11
	v_pk_fma_f32 v[24:25], v[86:87], v[88:89], v[8:9] op_sel_hi:[0,1,1]
	v_lshlrev_b32_e32 v12, 16, v15
	v_and_b32_e32 v13, 0xffff0000, v15
	v_pk_fma_f32 v[10:11], v[90:91], v[10:11], v[24:25] op_sel_hi:[0,1,1]
	v_lshlrev_b32_e32 v14, 16, v19
	v_and_b32_e32 v15, 0xffff0000, v19
	v_pk_fma_f32 v[10:11], v[92:93], v[12:13], v[10:11] op_sel_hi:[0,1,1]
	v_lshlrev_b32_e32 v16, 16, v23
	v_and_b32_e32 v17, 0xffff0000, v23
	v_pk_fma_f32 v[10:11], v[94:95], v[14:15], v[10:11] op_sel_hi:[0,1,1]
	v_lshlrev_b32_e32 v18, 16, v31
	v_and_b32_e32 v19, 0xffff0000, v31
	v_pk_fma_f32 v[10:11], v[96:97], v[16:17], v[10:11] op_sel_hi:[0,1,1]
	v_pk_fma_f32 v[4:5], v[84:85], v[4:5], v[56:57] op_sel_hi:[0,1,1] neg_lo:[0,0,1] neg_hi:[0,0,1]
	v_lshlrev_b32_e32 v6, 16, v7
	v_and_b32_e32 v7, 0xffff0000, v7
	v_lshlrev_b32_e32 v20, 16, v35
	v_and_b32_e32 v21, 0xffff0000, v35
	v_pk_fma_f32 v[10:11], v[98:99], v[18:19], v[10:11] op_sel_hi:[0,1,1]
	v_pk_mul_f32 v[4:5], v[80:81], v[4:5]
	v_mul_f32_e32 v2, 0xbfb8aa3b, v6
	v_lshlrev_b32_e32 v22, 16, v39
	v_and_b32_e32 v23, 0xffff0000, v39
	v_pk_fma_f32 v[10:11], v[100:101], v[20:21], v[10:11] op_sel_hi:[0,1,1]
	v_mul_f32_e32 v3, 0xbfb8aa3b, v7
	v_pk_mul_f32 v[0:1], v[0:1], v[4:5]
	v_lshlrev_b32_e32 v4, 16, v55
	v_and_b32_e32 v5, 0xffff0000, v55
	v_exp_f32_e32 v2, v2
	v_pk_fma_f32 v[10:11], v[102:103], v[22:23], v[10:11] op_sel_hi:[0,1,1]
	v_exp_f32_e32 v3, v3
	v_lshlrev_b32_e32 v108, 16, v59
	v_and_b32_e32 v109, 0xffff0000, v59
	v_pk_fma_f32 v[4:5], v[104:105], v[4:5], v[10:11] op_sel_hi:[0,1,1]
	v_lshlrev_b32_e32 v112, 16, v63
	v_and_b32_e32 v113, 0xffff0000, v63
	v_pk_fma_f32 v[4:5], v[106:107], v[108:109], v[4:5] op_sel_hi:[0,1,1]
	v_lshlrev_b32_e32 v116, 16, v67
	v_and_b32_e32 v117, 0xffff0000, v67
	v_pk_fma_f32 v[4:5], v[110:111], v[112:113], v[4:5] op_sel_hi:[0,1,1]
	v_add_f32_e32 v2, 1.0, v2
	v_pk_fma_f32 v[4:5], v[114:115], v[116:117], v[4:5] op_sel_hi:[0,1,1]
	v_lshlrev_b32_e32 v10, 16, v43
	v_and_b32_e32 v11, 0xffff0000, v43
	v_add_f32_e32 v3, 1.0, v3
	v_rcp_f32_e32 v2, v2
	v_pk_fma_f32 v[4:5], v[118:119], v[10:11], v[4:5] op_sel_hi:[0,1,1]
	v_lshlrev_b32_e32 v10, 16, v47
	v_and_b32_e32 v11, 0xffff0000, v47
	v_rcp_f32_e32 v3, v3
	v_pk_fma_f32 v[4:5], v[120:121], v[10:11], v[4:5] op_sel_hi:[0,1,1]
	v_lshlrev_b32_e32 v10, 16, v51
	v_and_b32_e32 v11, 0xffff0000, v51
	v_pk_fma_f32 v[4:5], v[122:123], v[10:11], v[4:5] op_sel_hi:[0,1,1]
	v_pk_fma_f32 v[4:5], v[84:85], v[4:5], v[8:9] op_sel_hi:[0,1,1] neg_lo:[0,0,1] neg_hi:[0,0,1]
	v_pk_mul_f32 v[4:5], v[70:71], v[4:5]
	v_pk_mul_f32 v[2:3], v[2:3], v[6:7]
	v_pk_mul_f32 v[82:83], v[134:135], v[82:83]
	v_pk_mul_f32 v[4:5], v[2:3], v[4:5]
	s_add_i32 s34, s34, s74
	v_cvt_pk_bf16_f32 v0, v0, v1
	v_cvt_pk_bf16_f32 v1, v82, v83
	v_cvt_pk_bf16_f32 v2, v68, v69
	v_cvt_pk_bf16_f32 v3, v4, v5
	v_add_u32_e32 v78, s82, v78
	s_cmpk_gt_i32 s34, 0x1fff
	global_store_dwordx4 v[76:77], v[0:3], off offset:3584 nt
	s_cbranch_scc0 .LBB0_394

; template <int NI> __device__ __forceinline__ void conv_items(bf16_t* PB, const float* cw, const int (&items)[NI], int lane) {
;     u32x4 uw[NI][3], cgw[NI][3], bgw[NI], zcw[NI]; f32x4 w0[NI][3], w1[NI][3]; int t[NI]; bf16_t* zp[NI];
; #pragma unroll
;     for (int q = 0; q < NI; ++q) { const int row = items[q] >> 1, ch = (items[q] & 1) * 512 + lane * 8; t[q] = row & (SEQ - 1);
;         const bf16_t* base = PB + (size_t)row * PBW + ch;
; #pragma unroll
;         for (int dt = 0; dt < 3; ++dt) { const int back = (dt <= t[q]) ? dt : 0;
;             uw[q][dt] = *(const u32x4*)(base - (size_t)back * PBW + C_U); cgw[q][dt] = *(const u32x4*)(base - (size_t)back * PBW + C_CG);
;             w0[q][dt] = *(const f32x4*)(cw + (2 - dt) * 1024 + ch); w1[q][dt] = *(const f32x4*)(cw + (2 - dt) * 1024 + ch + 4); }
;         zp[q] = PB + (size_t)row * PBW + C_ZC + ch;
;         bgw[q] = *(const u32x4*)(base + C_BG); zcw[q] = *(const u32x4*)zp[q]; }
;     u32x4 outw[NI];
; #pragma unroll
;     for (int q = 0; q < NI; ++q) {
;         float y[8];
; #pragma unroll
;         for (int e = 0; e < 8; ++e) y[e] = 0.f;
; #pragma unroll
;         for (int dt = 0; dt < 3; ++dt) { float u[8], c[8]; unpack8(uw[q][dt], u); unpack8(cgw[q][dt], c); const float mk = (dt <= t[q]) ? 1.f : 0.f;
; #pragma unroll
;             for (int e = 0; e < 8; ++e) { const float wv = (e < 4) ? w0[q][dt][e & 3] : w1[q][dt][e & 3]; y[e] += (mk * wv) * (c[e] * u[e]); } }
.LBB0_397:
	s_and_b32 s5, s6, 0x200
	v_add_u32_e32 v0, s5, v163
	s_add_i32 s4, s81, s95
	v_ashrrev_i32_e32 v1, 31, v0
	s_ashr_i32 s4, s4, 1
	v_lshlrev_b64 v[24:25], 1, v[0:1]
	v_lshl_add_u64 v[0:1], v[0:1], 2, s[2:3]
	s_and_b32 s7, s4, 0xfff
	s_mul_hi_i32 s5, s4, 0x9000
	s_mul_i32 s4, s4, 0x9000
	v_add_co_u32_e32 v4, vcc, s52, v0
	s_add_u32 s4, s92, s4
	s_nop 0
	v_addc_co_u32_e32 v5, vcc, 0, v1, vcc
	s_addc_u32 s5, s93, s5
	v_add_co_u32_e32 v10, vcc, s1, v0
	v_lshl_add_u64 v[26:27], s[4:5], 0, v[24:25]
	s_nop 0
	v_addc_co_u32_e32 v11, vcc, 0, v1, vcc
	s_cmp_eq_u32 s7, 0
	v_add_co_u32_e32 v28, vcc, s33, v26
	s_cselect_b64 s[4:5], -1, 0
	s_nop 0
	v_addc_co_u32_e32 v29, vcc, 0, v27, vcc
	v_add_co_u32_e32 v80, vcc, s90, v26
	v_cndmask_b32_e64 v84, 1.0, 0, s[4:5]
	s_and_b64 s[4:5], s[4:5], exec
	v_lshl_add_u64 v[2:3], v[0:1], 0, s[38:39]
	v_lshl_add_u64 v[8:9], v[0:1], 0, s[40:41]
	v_addc_co_u32_e32 v81, vcc, 0, v27, vcc
	s_cselect_b32 s5, 0, -1
	s_cselect_b32 s4, 0, 0xffff7000
	s_cmp_lt_u32 s7, 2
	global_load_dwordx4 v[16:19], v[0:1], off offset:16
	global_load_dwordx4 v[20:23], v[0:1], off
	s_nop 0
	global_load_dwordx4 v[4:7], v[4:5], off
	s_nop 0
	global_load_dwordx4 v[0:3], v[2:3], off offset:16
	s_nop 0
	global_load_dwordx4 v[12:15], v[10:11], off
	s_nop 0
	global_load_dwordx4 v[8:11], v[8:9], off offset:16
	s_waitcnt vmcnt(1)
	v_pk_mul_f32 v[106:107], v[84:85], v[14:15] op_sel_hi:[0,1]
	global_load_dwordx4 v[56:59], v[80:81], off offset:-4096
	global_load_dwordx4 v[60:63], v[28:29], off offset:2048
	global_load_dwordx4 v[68:71], v[80:81], off
	global_load_dwordx4 v[76:79], v[80:81], off offset:2048
	v_lshl_add_u64 v[28:29], v[26:27], 0, s[4:5]
	s_cselect_b64 s[4:5], -1, 0
	v_cndmask_b32_e64 v86, 1.0, 0, s[4:5]
	s_and_b64 s[4:5], s[4:5], exec
	s_cselect_b32 s5, 0, -1
	s_cselect_b32 s4, 0, 0xfffee000
	s_ashr_i32 s7, s76, 1
	v_add_co_u32_e32 v28, vcc, s90, v28
	v_lshl_add_u64 v[26:27], v[26:27], 0, s[4:5]
	s_and_b32 s8, s7, 0xfff
	s_mul_hi_i32 s5, s7, 0x9000
	s_mul_i32 s7, s7, 0x9000
	v_addc_co_u32_e32 v29, vcc, 0, v29, vcc
	s_add_u32 s4, s92, s7
	global_load_dwordx4 v[64:67], v[28:29], off offset:-4096
	global_load_dwordx4 v[72:75], v[28:29], off
	v_add_co_u32_e32 v26, vcc, s90, v26
	s_addc_u32 s5, s93, s5
	s_nop 0
	v_addc_co_u32_e32 v27, vcc, 0, v27, vcc
	v_lshl_add_u64 v[92:93], s[4:5], 0, v[24:25]
	s_cmp_eq_u32 s8, 0
	v_add_co_u32_e32 v24, vcc, s33, v92
	s_cselect_b64 s[4:5], -1, 0
	s_nop 0
	v_addc_co_u32_e32 v25, vcc, 0, v93, vcc
	global_load_dwordx4 v[48:51], v[26:27], off offset:-4096
	global_load_dwordx4 v[52:55], v[26:27], off
	v_add_co_u32_e32 v82, vcc, s90, v92
	v_cndmask_b32_e64 v88, 1.0, 0, s[4:5]
	s_and_b64 s[4:5], s[4:5], exec
	v_addc_co_u32_e32 v83, vcc, 0, v93, vcc
	s_cselect_b32 s5, 0, -1
	s_cselect_b32 s4, 0, 0xffff7000
	global_load_dwordx4 v[36:39], v[82:83], off offset:-4096
	global_load_dwordx4 v[44:47], v[82:83], off
	global_load_dwordx4 v[40:43], v[24:25], off offset:2048
	s_cmp_lt_u32 s8, 2
	v_lshl_add_u64 v[24:25], v[92:93], 0, s[4:5]
	s_cselect_b64 s[4:5], -1, 0
	v_add_co_u32_e32 v28, vcc, s90, v24
	v_cndmask_b32_e64 v90, 1.0, 0, s[4:5]
	s_nop 0
	v_addc_co_u32_e32 v29, vcc, 0, v25, vcc
	s_and_b64 s[4:5], s[4:5], exec
	global_load_dwordx4 v[24:27], v[28:29], off
	s_cselect_b32 s5, 0, -1
	s_cselect_b32 s4, 0, 0xfffee000
	global_load_dwordx4 v[32:35], v[28:29], off offset:-4096
	s_nop 0
	global_load_dwordx4 v[28:31], v[82:83], off offset:2048
	v_lshl_add_u64 v[92:93], v[92:93], 0, s[4:5]
	v_add_co_u32_e32 v96, vcc, s90, v92
	v_pk_mul_f32 v[100:101], v[86:87], v[20:21] op_sel_hi:[0,1]
	s_nop 0
	v_addc_co_u32_e32 v97, vcc, 0, v93, vcc
	global_load_dwordx4 v[92:95], v[96:97], off offset:-4096
	s_nop 0
	global_load_dwordx4 v[96:99], v[96:97], off
	v_pk_mul_f32 v[102:103], v[86:87], v[22:23] op_sel_hi:[0,1]
	v_pk_mul_f32 v[104:105], v[86:87], v[16:17] op_sel_hi:[0,1]
	v_pk_mul_f32 v[86:87], v[86:87], v[18:19] op_sel_hi:[0,1]
	v_pk_mul_f32 v[20:21], v[90:91], v[20:21] op_sel_hi:[0,1]
	v_pk_mul_f32 v[22:23], v[90:91], v[22:23] op_sel_hi:[0,1]
	v_pk_mul_f32 v[16:17], v[90:91], v[16:17] op_sel_hi:[0,1]
	v_pk_mul_f32 v[18:19], v[90:91], v[18:19] op_sel_hi:[0,1]
	v_pk_mul_f32 v[90:91], v[84:85], v[12:13] op_sel_hi:[0,1]
	s_waitcnt vmcnt(16)
	v_pk_mul_f32 v[108:109], v[84:85], v[8:9] op_sel_hi:[0,1]
	v_pk_mul_f32 v[84:85], v[84:85], v[10:11] op_sel_hi:[0,1]
	v_pk_mul_f32 v[12:13], v[88:89], v[12:13] op_sel_hi:[0,1]
	v_pk_mul_f32 v[14:15], v[88:89], v[14:15] op_sel_hi:[0,1]
	v_pk_mul_f32 v[8:9], v[88:89], v[8:9] op_sel_hi:[0,1]
	v_pk_mul_f32 v[10:11], v[88:89], v[10:11] op_sel_hi:[0,1]
	s_add_i32 s75, s75, s82
	s_add_i32 s95, s95, s82
	s_add_i32 s6, s6, s9
	s_waitcnt vmcnt(14)
	v_lshlrev_b32_e32 v114, 16, v60
	s_waitcnt vmcnt(13)
	v_lshlrev_b32_e32 v110, 16, v68
	s_waitcnt vmcnt(12)
	v_lshlrev_b32_e32 v88, 16, v76
	v_and_b32_e32 v89, 0xffff0000, v76
	v_and_b32_e32 v111, 0xffff0000, v68
	v_lshlrev_b32_e32 v112, 16, v56
	v_and_b32_e32 v113, 0xffff0000, v56
	v_lshlrev_b32_e32 v76, 16, v77
	v_and_b32_e32 v77, 0xffff0000, v77
	v_lshlrev_b32_e32 v68, 16, v69
	v_and_b32_e32 v69, 0xffff0000, v69
	v_lshlrev_b32_e32 v56, 16, v57
	v_and_b32_e32 v57, 0xffff0000, v57
	v_lshlrev_b32_e32 v116, 16, v78
	v_and_b32_e32 v117, 0xffff0000, v78
	v_lshlrev_b32_e32 v118, 16, v70
	v_and_b32_e32 v119, 0xffff0000, v70
	v_lshlrev_b32_e32 v120, 16, v58
	v_and_b32_e32 v121, 0xffff0000, v58
	v_lshlrev_b32_e32 v78, 16, v79
	v_and_b32_e32 v79, 0xffff0000, v79
	v_mul_f32_e32 v124, 0xbfb8aa3b, v88
	v_pk_mul_f32 v[110:111], v[112:113], v[110:111]
	v_mul_f32_e32 v112, 0xbfb8aa3b, v89
	v_mul_f32_e32 v113, 0xbfb8aa3b, v76
	v_pk_mul_f32 v[56:57], v[56:57], v[68:69]
	v_mul_f32_e32 v125, 0xbfb8aa3b, v77
	v_mul_f32_e32 v126, 0xbfb8aa3b, v116
	v_pk_mul_f32 v[68:69], v[120:121], v[118:119]
	v_mul_f32_e32 v118, 0xbfb8aa3b, v117
	v_mul_f32_e32 v119, 0xbfb8aa3b, v79
	v_mul_f32_e32 v120, 0xbfb8aa3b, v78
	v_exp_f32_e32 v124, v124
	v_exp_f32_e32 v127, v112
	v_exp_f32_e32 v128, v113
	v_exp_f32_e32 v125, v125
	v_exp_f32_e32 v126, v126
	v_exp_f32_e32 v129, v118
	v_exp_f32_e32 v130, v119
	v_exp_f32_e32 v131, v120
	v_lshlrev_b32_e32 v70, 16, v71
	v_and_b32_e32 v71, 0xffff0000, v71
	v_lshlrev_b32_e32 v58, 16, v59
	v_and_b32_e32 v59, 0xffff0000, v59
	v_pk_mul_f32 v[58:59], v[58:59], v[70:71]
	v_pk_fma_f32 v[70:71], v[4:5], v[110:111], 0 op_sel_hi:[1,1,0]
	s_waitcnt vmcnt(10)
; __device__ __forceinline__ float fsigmoid(float v) { return __builtin_amdgcn_rcpf(1.f + __builtin_amdgcn_exp2f(-v * LOG2E)); }
; __device__ __forceinline__ u32x4 pack8(const float (&f)[8]) { u32x4 w; w.x = cvtpk(f[0], f[1]); w.y = cvtpk(f[2], f[3]); w.z = cvtpk(f[4], f[5]); w.w = cvtpk(f[6], f[7]); return w; }
; template <int NI> __device__ __forceinline__ void conv_items(bf16_t* PB, const float* cw, const int (&items)[NI], int lane) {
;     ...
;     for (int q = 0; q < NI; ++q) {
;         float y[8];
; #pragma unroll
;         for (int e = 0; e < 8; ++e) y[e] = 0.f;
; #pragma unroll
;         for (int dt = 0; dt < 3; ++dt) { float u[8], c[8]; unpack8(uw[q][dt], u); unpack8(cgw[q][dt], c); const float mk = (dt <= t[q]) ? 1.f : 0.f;
; #pragma unroll
;             for (int e = 0; e < 8; ++e) { const float wv = (e < 4) ? w0[q][dt][e & 3] : w1[q][dt][e & 3]; y[e] += (mk * wv) * (c[e] * u[e]); } }
;         float bg[8], zc[8]; unpack8(bgw[q], bg); unpack8(zcw[q], zc);
; #pragma unroll
;         for (int e = 0; e < 8; ++e) y[e] = bg[e] * y[e] * (zc[e] * fsigmoid(zc[e]));
;         outw[q] = pack8(y); }
	v_lshlrev_b32_e32 v110, 16, v72
	v_and_b32_e32 v111, 0xffff0000, v72
	v_lshlrev_b32_e32 v112, 16, v64
	v_and_b32_e32 v113, 0xffff0000, v64
	v_lshlrev_b32_e32 v72, 16, v73
	v_and_b32_e32 v73, 0xffff0000, v73
	v_lshlrev_b32_e32 v64, 16, v65
	v_and_b32_e32 v65, 0xffff0000, v65
	v_lshlrev_b32_e32 v118, 16, v74
	v_and_b32_e32 v119, 0xffff0000, v74
	v_lshlrev_b32_e32 v120, 16, v66
	v_and_b32_e32 v121, 0xffff0000, v66
	v_pk_fma_f32 v[56:57], v[6:7], v[56:57], 0 op_sel_hi:[1,1,0]
	v_pk_fma_f32 v[68:69], v[0:1], v[68:69], 0 op_sel_hi:[1,1,0]
	v_lshlrev_b32_e32 v74, 16, v75
	v_and_b32_e32 v75, 0xffff0000, v75
	v_lshlrev_b32_e32 v66, 16, v67
	v_and_b32_e32 v67, 0xffff0000, v67
	v_pk_mul_f32 v[110:111], v[112:113], v[110:111]
	v_pk_mul_f32 v[64:65], v[64:65], v[72:73]
	v_pk_mul_f32 v[72:73], v[120:121], v[118:119]
	v_pk_fma_f32 v[58:59], v[2:3], v[58:59], 0 op_sel_hi:[1,1,0]
	v_pk_mul_f32 v[66:67], v[66:67], v[74:75]
	v_add_f32_e32 v74, 1.0, v124
	v_pk_fma_f32 v[70:71], v[90:91], v[110:111], v[70:71]
	v_add_f32_e32 v75, 1.0, v127
	v_add_f32_e32 v90, 1.0, v128
	v_pk_fma_f32 v[56:57], v[106:107], v[64:65], v[56:57]
	v_add_f32_e32 v91, 1.0, v125
	v_add_f32_e32 v106, 1.0, v126
	v_pk_fma_f32 v[64:65], v[72:73], v[108:109], v[68:69]
	v_add_f32_e32 v108, 1.0, v129
	v_add_f32_e32 v109, 1.0, v130
	v_add_f32_e32 v110, 1.0, v131
	v_pk_fma_f32 v[58:59], v[66:67], v[84:85], v[58:59]
	v_rcp_f32_e32 v66, v74
	s_waitcnt vmcnt(9)
	v_lshlrev_b32_e32 v72, 16, v48
	v_and_b32_e32 v73, 0xffff0000, v48
	v_rcp_f32_e32 v67, v75
	v_rcp_f32_e32 v48, v90
	v_lshlrev_b32_e32 v74, 16, v49
	v_and_b32_e32 v75, 0xffff0000, v49
	v_rcp_f32_e32 v49, v91
	v_rcp_f32_e32 v84, v106
	v_rcp_f32_e32 v85, v108
	v_rcp_f32_e32 v109, v109
	v_rcp_f32_e32 v108, v110
	s_waitcnt vmcnt(8)
	v_lshlrev_b32_e32 v68, 16, v52
	v_and_b32_e32 v69, 0xffff0000, v52
	v_lshlrev_b32_e32 v52, 16, v53
	v_and_b32_e32 v53, 0xffff0000, v53
	v_lshlrev_b32_e32 v90, 16, v54
	v_and_b32_e32 v91, 0xffff0000, v54
	v_lshlrev_b32_e32 v106, 16, v50
	v_and_b32_e32 v107, 0xffff0000, v50
	v_lshlrev_b32_e32 v54, 16, v55
	v_and_b32_e32 v55, 0xffff0000, v55
	v_lshlrev_b32_e32 v50, 16, v51
	v_and_b32_e32 v51, 0xffff0000, v51
	v_pk_mul_f32 v[68:69], v[72:73], v[68:69]
	v_pk_mul_f32 v[52:53], v[74:75], v[52:53]
	v_pk_mul_f32 v[72:73], v[106:107], v[90:91]
	v_pk_mul_f32 v[50:51], v[50:51], v[54:55]
	v_and_b32_e32 v115, 0xffff0000, v60
	v_lshlrev_b32_e32 v60, 16, v61
	v_and_b32_e32 v61, 0xffff0000, v61
	v_lshlrev_b32_e32 v122, 16, v62
	v_and_b32_e32 v123, 0xffff0000, v62
	v_lshlrev_b32_e32 v62, 16, v63
	v_and_b32_e32 v63, 0xffff0000, v63
	v_pk_fma_f32 v[54:55], v[100:101], v[68:69], v[70:71]
	v_pk_fma_f32 v[52:53], v[102:103], v[52:53], v[56:57]
	v_pk_fma_f32 v[56:57], v[72:73], v[104:105], v[64:65]
	v_pk_fma_f32 v[50:51], v[50:51], v[86:87], v[58:59]
	v_pk_mul_f32 v[54:55], v[54:55], v[114:115]
	v_pk_mul_f32 v[52:53], v[52:53], v[60:61]
	v_pk_mul_f32 v[56:57], v[56:57], v[122:123]
	v_pk_mul_f32 v[50:51], v[50:51], v[62:63]
	s_waitcnt vmcnt(6)
	v_lshlrev_b32_e32 v58, 16, v44
	v_and_b32_e32 v59, 0xffff0000, v44
	v_lshlrev_b32_e32 v60, 16, v36
	v_and_b32_e32 v61, 0xffff0000, v36
	v_lshlrev_b32_e32 v44, 16, v45
	v_and_b32_e32 v45, 0xffff0000, v45
	v_lshlrev_b32_e32 v36, 16, v37
	v_and_b32_e32 v37, 0xffff0000, v37
	v_lshlrev_b32_e32 v64, 16, v46
	v_and_b32_e32 v65, 0xffff0000, v46
	v_lshlrev_b32_e32 v68, 16, v38
	v_and_b32_e32 v69, 0xffff0000, v38
	v_lshlrev_b32_e32 v46, 16, v47
	v_and_b32_e32 v47, 0xffff0000, v47
	v_lshlrev_b32_e32 v38, 16, v39
	v_and_b32_e32 v39, 0xffff0000, v39
	v_pk_mul_f32 v[66:67], v[66:67], v[88:89]
	v_pk_mul_f32 v[48:49], v[48:49], v[76:77]
	v_pk_mul_f32 v[72:73], v[84:85], v[116:117]
	v_pk_mul_f32 v[74:75], v[108:109], v[78:79]
	v_pk_mul_f32 v[36:37], v[36:37], v[44:45]
	v_pk_mul_f32 v[44:45], v[68:69], v[64:65]
	v_pk_mul_f32 v[38:39], v[38:39], v[46:47]
	v_pk_mul_f32 v[46:47], v[54:55], v[66:67]
	v_pk_mul_f32 v[48:49], v[52:53], v[48:49]
	v_pk_mul_f32 v[52:53], v[56:57], v[72:73]
	v_pk_mul_f32 v[50:51], v[50:51], v[74:75]
	v_pk_mul_f32 v[58:59], v[60:61], v[58:59]
	v_pk_fma_f32 v[6:7], v[6:7], v[36:37], 0 op_sel_hi:[1,1,0]
	v_pk_fma_f32 v[36:37], v[0:1], v[44:45], 0 op_sel_hi:[1,1,0]
	v_pk_fma_f32 v[38:39], v[2:3], v[38:39], 0 op_sel_hi:[1,1,0]
	v_cvt_pk_bf16_f32 v0, v46, v47
	v_cvt_pk_bf16_f32 v1, v48, v49
	v_cvt_pk_bf16_f32 v2, v52, v53
	v_cvt_pk_bf16_f32 v3, v50, v51
	s_waitcnt vmcnt(4)
; __device__ __forceinline__ float fsigmoid(float v) { return __builtin_amdgcn_rcpf(1.f + __builtin_amdgcn_exp2f(-v * LOG2E)); }
; __device__ __forceinline__ u32x4 pack8(const float (&f)[8]) { u32x4 w; w.x = cvtpk(f[0], f[1]); w.y = cvtpk(f[2], f[3]); w.z = cvtpk(f[4], f[5]); w.w = cvtpk(f[6], f[7]); return w; }
; template <int NI> __device__ __forceinline__ void conv_items(bf16_t* PB, const float* cw, const int (&items)[NI], int lane) {
;     ...
;     for (int q = 0; q < NI; ++q) {
;         float y[8];
; #pragma unroll
;         for (int e = 0; e < 8; ++e) y[e] = 0.f;
; #pragma unroll
;         for (int dt = 0; dt < 3; ++dt) { float u[8], c[8]; unpack8(uw[q][dt], u); unpack8(cgw[q][dt], c); const float mk = (dt <= t[q]) ? 1.f : 0.f;
; #pragma unroll
;             for (int e = 0; e < 8; ++e) { const float wv = (e < 4) ? w0[q][dt][e & 3] : w1[q][dt][e & 3]; y[e] += (mk * wv) * (c[e] * u[e]); } }
;         float bg[8], zc[8]; unpack8(bgw[q], bg); unpack8(zcw[q], zc);
; #pragma unroll
;         for (int e = 0; e < 8; ++e) y[e] = bg[e] * y[e] * (zc[e] * fsigmoid(zc[e]));
;         outw[q] = pack8(y); }
; #pragma unroll
;     for (int q = 0; q < NI; ++q) *(u32x4*)zp[q] = outw[q];
	v_lshlrev_b32_e32 v44, 16, v24
	v_and_b32_e32 v45, 0xffff0000, v24
	s_waitcnt vmcnt(3)
	v_lshlrev_b32_e32 v46, 16, v32
	v_and_b32_e32 v47, 0xffff0000, v32
	s_waitcnt vmcnt(2)
	v_lshlrev_b32_e32 v48, 16, v28
	v_and_b32_e32 v49, 0xffff0000, v28
	v_lshlrev_b32_e32 v24, 16, v25
	v_and_b32_e32 v25, 0xffff0000, v25
	v_lshlrev_b32_e32 v32, 16, v33
	v_and_b32_e32 v33, 0xffff0000, v33
	v_lshlrev_b32_e32 v28, 16, v29
	v_and_b32_e32 v29, 0xffff0000, v29
	v_lshlrev_b32_e32 v50, 16, v26
	v_and_b32_e32 v51, 0xffff0000, v26
	v_lshlrev_b32_e32 v52, 16, v34
	v_and_b32_e32 v53, 0xffff0000, v34
	v_lshlrev_b32_e32 v54, 16, v30
	v_and_b32_e32 v55, 0xffff0000, v30
	v_lshlrev_b32_e32 v26, 16, v27
	v_and_b32_e32 v27, 0xffff0000, v27
	v_lshlrev_b32_e32 v34, 16, v35
	v_and_b32_e32 v35, 0xffff0000, v35
	v_lshlrev_b32_e32 v30, 16, v31
	v_and_b32_e32 v31, 0xffff0000, v31
	v_pk_fma_f32 v[4:5], v[4:5], v[58:59], 0 op_sel_hi:[1,1,0]
	global_store_dwordx4 v[80:81], v[0:3], off offset:2048 nt
	v_pk_mul_f32 v[26:27], v[34:35], v[26:27]
	v_mul_f32_e32 v34, 0xbfb8aa3b, v30
	v_pk_mul_f32 v[0:1], v[46:47], v[44:45]
	v_mul_f32_e32 v44, 0xbfb8aa3b, v48
	v_mul_f32_e32 v45, 0xbfb8aa3b, v49
	v_pk_mul_f32 v[2:3], v[32:33], v[24:25]
	v_mul_f32_e32 v32, 0xbfb8aa3b, v28
	v_mul_f32_e32 v33, 0xbfb8aa3b, v29
	v_pk_mul_f32 v[24:25], v[52:53], v[50:51]
	v_mul_f32_e32 v46, 0xbfb8aa3b, v54
	v_mul_f32_e32 v47, 0xbfb8aa3b, v55
	v_mul_f32_e32 v35, 0xbfb8aa3b, v31
	v_pk_fma_f32 v[0:1], v[12:13], v[0:1], v[4:5]
	v_exp_f32_e32 v44, v44
	v_exp_f32_e32 v45, v45
	v_pk_fma_f32 v[2:3], v[14:15], v[2:3], v[6:7]
	v_exp_f32_e32 v50, v32
	v_exp_f32_e32 v51, v33
	v_pk_fma_f32 v[4:5], v[8:9], v[24:25], v[36:37]
	v_exp_f32_e32 v36, v46
	v_exp_f32_e32 v37, v47
	v_pk_fma_f32 v[6:7], v[10:11], v[26:27], v[38:39]
	v_exp_f32_e32 v38, v34
	v_exp_f32_e32 v39, v35
	s_waitcnt vmcnt(1)
	v_lshlrev_b32_e32 v8, 16, v96
	v_and_b32_e32 v9, 0xffff0000, v96
	v_lshlrev_b32_e32 v10, 16, v92
	v_and_b32_e32 v11, 0xffff0000, v92
	v_lshlrev_b32_e32 v12, 16, v97
	v_and_b32_e32 v13, 0xffff0000, v97
	v_lshlrev_b32_e32 v14, 16, v93
	v_and_b32_e32 v15, 0xffff0000, v93
	v_lshlrev_b32_e32 v24, 16, v98
	v_and_b32_e32 v25, 0xffff0000, v98
	v_lshlrev_b32_e32 v26, 16, v94
	v_and_b32_e32 v27, 0xffff0000, v94
	v_lshlrev_b32_e32 v32, 16, v95
	v_and_b32_e32 v33, 0xffff0000, v95
	v_lshlrev_b32_e32 v34, 16, v99
	v_and_b32_e32 v35, 0xffff0000, v99
	v_pk_mul_f32 v[8:9], v[10:11], v[8:9]
	v_pk_mul_f32 v[10:11], v[14:15], v[12:13]
	v_pk_mul_f32 v[12:13], v[26:27], v[24:25]
	v_pk_mul_f32 v[14:15], v[32:33], v[34:35]
	v_pk_fma_f32 v[0:1], v[20:21], v[8:9], v[0:1]
	v_pk_fma_f32 v[2:3], v[22:23], v[10:11], v[2:3]
	v_pk_fma_f32 v[4:5], v[16:17], v[12:13], v[4:5]
	v_pk_fma_f32 v[6:7], v[18:19], v[14:15], v[6:7]
	v_add_f32_e32 v8, 1.0, v44
	v_add_f32_e32 v9, 1.0, v45
	v_add_f32_e32 v10, 1.0, v50
	v_add_f32_e32 v11, 1.0, v51
	v_add_f32_e32 v12, 1.0, v36
	v_add_f32_e32 v13, 1.0, v37
	v_add_f32_e32 v14, 1.0, v38
	v_add_f32_e32 v15, 1.0, v39
	v_rcp_f32_e32 v8, v8
	v_rcp_f32_e32 v9, v9
	v_rcp_f32_e32 v10, v10
	v_rcp_f32_e32 v11, v11
	v_rcp_f32_e32 v12, v12
	v_rcp_f32_e32 v13, v13
	v_rcp_f32_e32 v14, v14
	v_rcp_f32_e32 v15, v15
	v_lshlrev_b32_e32 v62, 16, v40
	v_and_b32_e32 v63, 0xffff0000, v40
	v_lshlrev_b32_e32 v40, 16, v41
	v_and_b32_e32 v41, 0xffff0000, v41
	v_lshlrev_b32_e32 v70, 16, v42
	v_and_b32_e32 v71, 0xffff0000, v42
	v_lshlrev_b32_e32 v42, 16, v43
	v_and_b32_e32 v43, 0xffff0000, v43
	v_pk_mul_f32 v[0:1], v[0:1], v[62:63]
	v_pk_mul_f32 v[2:3], v[2:3], v[40:41]
	v_pk_mul_f32 v[4:5], v[4:5], v[70:71]
	v_pk_mul_f32 v[6:7], v[6:7], v[42:43]
	v_pk_mul_f32 v[8:9], v[8:9], v[48:49]
	v_pk_mul_f32 v[10:11], v[10:11], v[28:29]
	v_pk_mul_f32 v[12:13], v[12:13], v[54:55]
	v_pk_mul_f32 v[14:15], v[14:15], v[30:31]
	s_add_i32 s76, s75, s74
	s_add_i32 s4, s88, s95
	v_pk_mul_f32 v[0:1], v[0:1], v[8:9]
	v_pk_mul_f32 v[2:3], v[2:3], v[10:11]
	v_pk_mul_f32 v[4:5], v[4:5], v[12:13]
	v_pk_mul_f32 v[6:7], v[6:7], v[14:15]
	s_cmpk_gt_i32 s4, 0x7fff
	v_cvt_pk_bf16_f32 v0, v0, v1
	v_cvt_pk_bf16_f32 v1, v2, v3
	v_cvt_pk_bf16_f32 v2, v4, v5
	v_cvt_pk_bf16_f32 v3, v6, v7
	global_store_dwordx4 v[82:83], v[0:3], off offset:2048 nt
	s_cbranch_scc0 .LBB0_397
	s_add_i32 s75, s81, s95

; template <int NI> __device__ __forceinline__ void conv_items(bf16_t* PB, const float* cw, const int (&items)[NI], int lane) {
;     u32x4 uw[NI][3], cgw[NI][3], bgw[NI], zcw[NI]; f32x4 w0[NI][3], w1[NI][3]; int t[NI]; bf16_t* zp[NI];
; #pragma unroll
;     for (int q = 0; q < NI; ++q) { const int row = items[q] >> 1, ch = (items[q] & 1) * 512 + lane * 8; t[q] = row & (SEQ - 1);
;         const bf16_t* base = PB + (size_t)row * PBW + ch;
; #pragma unroll
;         for (int dt = 0; dt < 3; ++dt) { const int back = (dt <= t[q]) ? dt : 0;
;             uw[q][dt] = *(const u32x4*)(base - (size_t)back * PBW + C_U); cgw[q][dt] = *(const u32x4*)(base - (size_t)back * PBW + C_CG);
;             w0[q][dt] = *(const f32x4*)(cw + (2 - dt) * 1024 + ch); w1[q][dt] = *(const f32x4*)(cw + (2 - dt) * 1024 + ch + 4); }
;         zp[q] = PB + (size_t)row * PBW + C_ZC + ch;
;         bgw[q] = *(const u32x4*)(base + C_BG); zcw[q] = *(const u32x4*)zp[q]; }
;     u32x4 outw[NI];
; #pragma unroll
;     for (int q = 0; q < NI; ++q) {
;         float y[8];
; #pragma unroll
;         for (int e = 0; e < 8; ++e) y[e] = 0.f;
; #pragma unroll
;         for (int dt = 0; dt < 3; ++dt) { float u[8], c[8]; unpack8(uw[q][dt], u); unpack8(cgw[q][dt], c); const float mk = (dt <= t[q]) ? 1.f : 0.f;
; #pragma unroll
;             for (int e = 0; e < 8; ++e) { const float wv = (e < 4) ? w0[q][dt][e & 3] : w1[q][dt][e & 3]; y[e] += (mk * wv) * (c[e] * u[e]); } }
.LBB0_401:
	s_and_b32 s5, s6, 0x200
	v_add_u32_e32 v0, s5, v163
	v_ashrrev_i32_e32 v1, 31, v0
	s_ashr_i32 s4, s75, 1
	v_lshl_add_u64 v[2:3], v[0:1], 2, s[2:3]
	s_and_b32 s7, s4, 0xfff
	s_mul_hi_i32 s5, s4, 0x9000
	s_mul_i32 s4, s4, 0x9000
	v_add_co_u32_e32 v4, vcc, s52, v2
	s_add_u32 s4, s92, s4
	s_nop 0
	v_addc_co_u32_e32 v5, vcc, 0, v3, vcc
	s_addc_u32 s5, s93, s5
	v_add_co_u32_e32 v10, vcc, s1, v2
	v_lshl_add_u64 v[50:51], v[0:1], 1, s[4:5]
	s_cmp_eq_u32 s7, 0
	v_addc_co_u32_e32 v11, vcc, 0, v3, vcc
	v_add_co_u32_e32 v12, vcc, s33, v50
	s_cselect_b64 s[4:5], -1, 0
	v_cndmask_b32_e64 v52, 1.0, 0, s[4:5]
	v_addc_co_u32_e32 v13, vcc, 0, v51, vcc
	s_and_b64 s[4:5], s[4:5], exec
	v_lshl_add_u64 v[0:1], v[2:3], 0, s[38:39]
	v_lshl_add_u64 v[8:9], v[2:3], 0, s[40:41]
	v_add_co_u32_e32 v48, vcc, s90, v50
	s_cselect_b32 s5, 0, -1
	s_cselect_b32 s4, 0, 0xffff7000
	s_cmp_lt_u32 s7, 2
	global_load_dwordx4 v[28:31], v[2:3], off offset:16
	global_load_dwordx4 v[36:39], v[2:3], off
	s_nop 0
	global_load_dwordx4 v[4:7], v[4:5], off
	s_nop 0
	global_load_dwordx4 v[0:3], v[0:1], off offset:16
	s_nop 0
	global_load_dwordx4 v[40:43], v[10:11], off
	global_load_dwordx4 v[32:35], v[8:9], off offset:16
	v_addc_co_u32_e32 v49, vcc, 0, v51, vcc
	v_lshl_add_u64 v[8:9], v[50:51], 0, s[4:5]
	s_cselect_b64 s[4:5], -1, 0
	global_load_dwordx4 v[44:47], v[12:13], off offset:2048
	global_load_dwordx4 v[24:27], v[48:49], off
	global_load_dwordx4 v[20:23], v[48:49], off offset:-4096
	global_load_dwordx4 v[16:19], v[48:49], off offset:2048
	v_cndmask_b32_e64 v54, 1.0, 0, s[4:5]
	s_and_b64 s[4:5], s[4:5], exec
	v_add_co_u32_e32 v8, vcc, s90, v8
	s_cselect_b32 s5, 0, -1
	s_cselect_b32 s4, 0, 0xfffee000
	v_addc_co_u32_e32 v9, vcc, 0, v9, vcc
	v_lshl_add_u64 v[50:51], v[50:51], 0, s[4:5]
	global_load_dwordx4 v[12:15], v[8:9], off
	s_nop 0
	global_load_dwordx4 v[8:11], v[8:9], off offset:-4096
	v_add_co_u32_e32 v50, vcc, s90, v50
	s_add_i32 s75, s75, s74
	s_nop 0
	v_addc_co_u32_e32 v51, vcc, 0, v51, vcc
	global_load_dwordx4 v[56:59], v[50:51], off offset:-4096
	global_load_dwordx4 v[60:63], v[50:51], off
	s_add_i32 s6, s6, s8
	s_cmp_lt_i32 s75, 0x8000
	s_waitcnt vmcnt(13)
	v_pk_mul_f32 v[28:29], v[54:55], v[28:29] op_sel_hi:[0,1]
	s_waitcnt vmcnt(12)
	v_pk_mul_f32 v[36:37], v[54:55], v[36:37] op_sel_hi:[0,1]
	v_pk_mul_f32 v[38:39], v[54:55], v[38:39] op_sel_hi:[0,1]
	v_pk_mul_f32 v[30:31], v[54:55], v[30:31] op_sel_hi:[0,1]
	s_waitcnt vmcnt(9)
	v_pk_mul_f32 v[40:41], v[52:53], v[40:41] op_sel_hi:[0,1]
	v_pk_mul_f32 v[42:43], v[52:53], v[42:43] op_sel_hi:[0,1]
	s_waitcnt vmcnt(6)
	v_lshlrev_b32_e32 v54, 16, v24
	v_and_b32_e32 v55, 0xffff0000, v24
	s_waitcnt vmcnt(5)
	v_lshlrev_b32_e32 v64, 16, v20
	v_and_b32_e32 v65, 0xffff0000, v20
	s_waitcnt vmcnt(4)
	v_lshlrev_b32_e32 v66, 16, v16
	v_and_b32_e32 v67, 0xffff0000, v16
	v_lshlrev_b32_e32 v24, 16, v25
	v_and_b32_e32 v25, 0xffff0000, v25
	v_lshlrev_b32_e32 v20, 16, v21
	v_and_b32_e32 v21, 0xffff0000, v21
	v_lshlrev_b32_e32 v16, 16, v17
	v_and_b32_e32 v17, 0xffff0000, v17
	v_lshlrev_b32_e32 v68, 16, v26
	v_and_b32_e32 v69, 0xffff0000, v26
	v_lshlrev_b32_e32 v70, 16, v22
	v_and_b32_e32 v71, 0xffff0000, v22
	v_lshlrev_b32_e32 v72, 16, v18
	v_and_b32_e32 v73, 0xffff0000, v18
	v_lshlrev_b32_e32 v18, 16, v19
	v_and_b32_e32 v19, 0xffff0000, v19
	v_pk_mul_f32 v[54:55], v[64:65], v[54:55]
	v_mul_f32_e32 v64, 0xbfb8aa3b, v66
	v_mul_f32_e32 v65, 0xbfb8aa3b, v67
	v_pk_mul_f32 v[20:21], v[20:21], v[24:25]
	v_mul_f32_e32 v74, 0xbfb8aa3b, v16
	v_mul_f32_e32 v75, 0xbfb8aa3b, v17
	v_pk_mul_f32 v[24:25], v[70:71], v[68:69]
	v_mul_f32_e32 v68, 0xbfb8aa3b, v72
	v_mul_f32_e32 v69, 0xbfb8aa3b, v73
	v_mul_f32_e32 v70, 0xbfb8aa3b, v18
	v_mul_f32_e32 v71, 0xbfb8aa3b, v19
	v_lshlrev_b32_e32 v26, 16, v27
	v_and_b32_e32 v27, 0xffff0000, v27
	v_lshlrev_b32_e32 v22, 16, v23
	v_and_b32_e32 v23, 0xffff0000, v23
	v_exp_f32_e32 v64, v64
	v_exp_f32_e32 v65, v65
	v_exp_f32_e32 v74, v74
	v_exp_f32_e32 v75, v75
	v_exp_f32_e32 v68, v68
	v_exp_f32_e32 v69, v69
	v_exp_f32_e32 v70, v70
	v_exp_f32_e32 v71, v71
	v_pk_mul_f32 v[22:23], v[22:23], v[26:27]
	v_pk_fma_f32 v[4:5], v[4:5], v[54:55], 0 op_sel_hi:[1,1,0]
	s_waitcnt vmcnt(3)
; __device__ __forceinline__ float fsigmoid(float v) { return __builtin_amdgcn_rcpf(1.f + __builtin_amdgcn_exp2f(-v * LOG2E)); }
; __device__ __forceinline__ u32x4 pack8(const float (&f)[8]) { u32x4 w; w.x = cvtpk(f[0], f[1]); w.y = cvtpk(f[2], f[3]); w.z = cvtpk(f[4], f[5]); w.w = cvtpk(f[6], f[7]); return w; }
; template <int NI> __device__ __forceinline__ void conv_items(bf16_t* PB, const float* cw, const int (&items)[NI], int lane) {
;     ...
;     for (int q = 0; q < NI; ++q) {
;         float y[8];
; #pragma unroll
;         for (int e = 0; e < 8; ++e) y[e] = 0.f;
; #pragma unroll
;         for (int dt = 0; dt < 3; ++dt) { float u[8], c[8]; unpack8(uw[q][dt], u); unpack8(cgw[q][dt], c); const float mk = (dt <= t[q]) ? 1.f : 0.f;
; #pragma unroll
;             for (int e = 0; e < 8; ++e) { const float wv = (e < 4) ? w0[q][dt][e & 3] : w1[q][dt][e & 3]; y[e] += (mk * wv) * (c[e] * u[e]); } }
;         float bg[8], zc[8]; unpack8(bgw[q], bg); unpack8(zcw[q], zc);
; #pragma unroll
;         for (int e = 0; e < 8; ++e) y[e] = bg[e] * y[e] * (zc[e] * fsigmoid(zc[e]));
;         outw[q] = pack8(y); }
; #pragma unroll
;     for (int q = 0; q < NI; ++q) *(u32x4*)zp[q] = outw[q];
	v_lshlrev_b32_e32 v26, 16, v12
	v_and_b32_e32 v27, 0xffff0000, v12
	s_waitcnt vmcnt(2)
	v_lshlrev_b32_e32 v54, 16, v8
	v_and_b32_e32 v55, 0xffff0000, v8
	v_pk_fma_f32 v[6:7], v[6:7], v[20:21], 0 op_sel_hi:[1,1,0]
	v_lshlrev_b32_e32 v12, 16, v13
	v_and_b32_e32 v13, 0xffff0000, v13
	v_lshlrev_b32_e32 v8, 16, v9
	v_and_b32_e32 v9, 0xffff0000, v9
	v_pk_fma_f32 v[0:1], v[0:1], v[24:25], 0 op_sel_hi:[1,1,0]
	v_lshlrev_b32_e32 v20, 16, v14
	v_and_b32_e32 v21, 0xffff0000, v14
	v_lshlrev_b32_e32 v24, 16, v10
	v_and_b32_e32 v25, 0xffff0000, v10
	v_lshlrev_b32_e32 v14, 16, v15
	v_and_b32_e32 v15, 0xffff0000, v15
	v_lshlrev_b32_e32 v10, 16, v11
	v_and_b32_e32 v11, 0xffff0000, v11
	v_pk_mul_f32 v[32:33], v[52:53], v[32:33] op_sel_hi:[0,1]
	v_pk_mul_f32 v[34:35], v[52:53], v[34:35] op_sel_hi:[0,1]
	v_pk_fma_f32 v[2:3], v[2:3], v[22:23], 0 op_sel_hi:[1,1,0]
	v_pk_mul_f32 v[22:23], v[54:55], v[26:27]
	v_pk_mul_f32 v[8:9], v[8:9], v[12:13]
	v_pk_mul_f32 v[12:13], v[24:25], v[20:21]
	v_pk_mul_f32 v[10:11], v[10:11], v[14:15]
	v_pk_fma_f32 v[4:5], v[40:41], v[22:23], v[4:5]
	v_pk_fma_f32 v[6:7], v[42:43], v[8:9], v[6:7]
	v_pk_fma_f32 v[0:1], v[12:13], v[32:33], v[0:1]
	v_pk_fma_f32 v[2:3], v[10:11], v[34:35], v[2:3]
	s_waitcnt vmcnt(0)
	v_lshlrev_b32_e32 v8, 16, v60
	v_and_b32_e32 v9, 0xffff0000, v60
	v_lshlrev_b32_e32 v10, 16, v56
	v_and_b32_e32 v11, 0xffff0000, v56
	v_lshlrev_b32_e32 v12, 16, v61
	v_and_b32_e32 v13, 0xffff0000, v61
	v_lshlrev_b32_e32 v14, 16, v57
	v_and_b32_e32 v15, 0xffff0000, v57
	v_lshlrev_b32_e32 v20, 16, v62
	v_and_b32_e32 v21, 0xffff0000, v62
	v_lshlrev_b32_e32 v22, 16, v58
	v_and_b32_e32 v23, 0xffff0000, v58
	v_lshlrev_b32_e32 v24, 16, v59
	v_and_b32_e32 v25, 0xffff0000, v59
	v_lshlrev_b32_e32 v26, 16, v63
	v_and_b32_e32 v27, 0xffff0000, v63
	v_pk_mul_f32 v[8:9], v[10:11], v[8:9]
	v_add_f32_e32 v32, 1.0, v64
	v_add_f32_e32 v33, 1.0, v65
	v_pk_mul_f32 v[10:11], v[14:15], v[12:13]
	v_add_f32_e32 v34, 1.0, v74
	v_add_f32_e32 v35, 1.0, v75
	v_pk_mul_f32 v[12:13], v[22:23], v[20:21]
	v_add_f32_e32 v20, 1.0, v68
	v_add_f32_e32 v21, 1.0, v69
	v_pk_mul_f32 v[14:15], v[24:25], v[26:27]
	v_add_f32_e32 v22, 1.0, v70
	v_add_f32_e32 v23, 1.0, v71
	v_pk_fma_f32 v[4:5], v[36:37], v[8:9], v[4:5]
	v_rcp_f32_e32 v8, v32
	v_rcp_f32_e32 v9, v33
	v_pk_fma_f32 v[6:7], v[38:39], v[10:11], v[6:7]
	v_rcp_f32_e32 v10, v34
	v_rcp_f32_e32 v11, v35
	v_pk_fma_f32 v[0:1], v[12:13], v[28:29], v[0:1]
	v_rcp_f32_e32 v12, v20
	v_rcp_f32_e32 v13, v21
	v_pk_fma_f32 v[2:3], v[14:15], v[30:31], v[2:3]
	v_rcp_f32_e32 v14, v22
	v_rcp_f32_e32 v15, v23
	v_lshlrev_b32_e32 v50, 16, v44
	v_and_b32_e32 v51, 0xffff0000, v44
	v_lshlrev_b32_e32 v44, 16, v45
	v_and_b32_e32 v45, 0xffff0000, v45
	v_lshlrev_b32_e32 v52, 16, v46
	v_and_b32_e32 v53, 0xffff0000, v46
	v_lshlrev_b32_e32 v46, 16, v47
	v_and_b32_e32 v47, 0xffff0000, v47
	v_pk_mul_f32 v[4:5], v[4:5], v[50:51]
	v_pk_mul_f32 v[6:7], v[6:7], v[44:45]
	v_pk_mul_f32 v[0:1], v[0:1], v[52:53]
	v_pk_mul_f32 v[2:3], v[2:3], v[46:47]
	v_pk_mul_f32 v[8:9], v[8:9], v[66:67]
	v_pk_mul_f32 v[10:11], v[10:11], v[16:17]
	v_pk_mul_f32 v[12:13], v[12:13], v[72:73]
	v_pk_mul_f32 v[14:15], v[14:15], v[18:19]
	v_pk_mul_f32 v[4:5], v[8:9], v[4:5]
	v_pk_mul_f32 v[6:7], v[10:11], v[6:7]
	v_pk_mul_f32 v[8:9], v[12:13], v[0:1]
	v_pk_mul_f32 v[10:11], v[14:15], v[2:3]
	v_cvt_pk_bf16_f32 v0, v4, v5
	v_cvt_pk_bf16_f32 v1, v6, v7
	v_cvt_pk_bf16_f32 v2, v8, v9
	v_cvt_pk_bf16_f32 v3, v10, v11
	global_store_dwordx4 v[48:49], v[0:3], off offset:2048 nt
	s_cbranch_scc1 .LBB0_401
